# hybrid prep fold item: uniform operands via LDS, w_out loads 48 in flight (same fma order)
# speedup vs baseline: 1.0369x; 1.0100x over previous
; __device__ __forceinline__ void prep_hybrid(const float* w_in, const float* w_out, const float* pool_w, const float* pool_scale, bf16_t* WIN, bf16_t* WOUT, int gw, int NGW, LAS float* scr, int lane) {
;     ...
;         const int g = it >> 8, c8 = (it >> 4) & 15, n = (it & 15) * 64 + lane;
;         float a[8];
; #pragma unroll
;         for (int i = 0; i < 8; ++i) a[i] = 0.f;
;         const float* pw = pool_w + ((size_t)g * 128 + c8 * 8) * 128;
; #pragma unroll 4
;         for (int d = 0; d < 128; ++d) {
;             const float wv = w_out[(size_t)(512 + g * 128 + d) * D + n] * pool_scale[g * 128 + d];
; #pragma unroll
;             for (int i = 0; i < 8; ++i) a[i] += pw[i * 128 + d] * wv;
.LBB0_45:
	s_mov_b32 s2, s31
	s_mov_b32 s3, s34
	s_mov_b32 s38, s8
	s_mov_b32 s39, s30
	v_mbcnt_hi_u32_b32 v190, -1, v254
	v_and_b32_e32 v191, 31, v190
	v_lshlrev_b32_e32 v190, 4, v190
	v_lshlrev_b32_e32 v191, 4, v191
	global_load_dwordx4 v[116:119], v190, s[2:3]
	global_load_dwordx4 v[120:123], v190, s[2:3] offset:1024
	global_load_dwordx4 v[124:127], v190, s[2:3] offset:2048
	global_load_dwordx4 v[128:131], v190, s[2:3] offset:3072
	global_load_dwordx4 v[132:135], v191, s[38:39]
	v_add_co_u32_e32 v2, vcc, 0xffffd000, v2
	s_nop 1
	v_addc_co_u32_e32 v3, vcc, -1, v3, vcc
	s_mov_b32 s14, 0x1000
	s_mov_b32 s15, 0
	global_load_dword v56, v[2:3], off
	v_lshl_add_u64 v[2:3], v[2:3], 0, s[14:15]
	global_load_dword v57, v[2:3], off
	v_lshl_add_u64 v[2:3], v[2:3], 0, s[14:15]
	global_load_dword v58, v[2:3], off
	v_lshl_add_u64 v[2:3], v[2:3], 0, s[14:15]
	global_load_dword v59, v[2:3], off
	v_lshl_add_u64 v[2:3], v[2:3], 0, s[14:15]
	global_load_dword v68, v[2:3], off
	v_lshl_add_u64 v[2:3], v[2:3], 0, s[14:15]
	global_load_dword v69, v[2:3], off
	v_lshl_add_u64 v[2:3], v[2:3], 0, s[14:15]
	global_load_dword v70, v[2:3], off
	v_lshl_add_u64 v[2:3], v[2:3], 0, s[14:15]
	global_load_dword v71, v[2:3], off
	v_lshl_add_u64 v[2:3], v[2:3], 0, s[14:15]
	global_load_dword v72, v[2:3], off
	v_lshl_add_u64 v[2:3], v[2:3], 0, s[14:15]
	global_load_dword v73, v[2:3], off
	v_lshl_add_u64 v[2:3], v[2:3], 0, s[14:15]
	global_load_dword v74, v[2:3], off
	v_lshl_add_u64 v[2:3], v[2:3], 0, s[14:15]
	global_load_dword v75, v[2:3], off
	v_lshl_add_u64 v[2:3], v[2:3], 0, s[14:15]
	global_load_dword v76, v[2:3], off
	v_lshl_add_u64 v[2:3], v[2:3], 0, s[14:15]
	global_load_dword v77, v[2:3], off
	v_lshl_add_u64 v[2:3], v[2:3], 0, s[14:15]
	global_load_dword v78, v[2:3], off
	v_lshl_add_u64 v[2:3], v[2:3], 0, s[14:15]
	global_load_dword v79, v[2:3], off
	v_lshl_add_u64 v[2:3], v[2:3], 0, s[14:15]
	global_load_dword v80, v[2:3], off
	v_lshl_add_u64 v[2:3], v[2:3], 0, s[14:15]
	global_load_dword v81, v[2:3], off
	v_lshl_add_u64 v[2:3], v[2:3], 0, s[14:15]
	global_load_dword v82, v[2:3], off
	v_lshl_add_u64 v[2:3], v[2:3], 0, s[14:15]
	global_load_dword v83, v[2:3], off
	v_lshl_add_u64 v[2:3], v[2:3], 0, s[14:15]
	global_load_dword v84, v[2:3], off
	v_lshl_add_u64 v[2:3], v[2:3], 0, s[14:15]
	global_load_dword v85, v[2:3], off
	v_lshl_add_u64 v[2:3], v[2:3], 0, s[14:15]
	global_load_dword v86, v[2:3], off
	v_lshl_add_u64 v[2:3], v[2:3], 0, s[14:15]
	global_load_dword v87, v[2:3], off
	v_lshl_add_u64 v[2:3], v[2:3], 0, s[14:15]
	global_load_dword v92, v[2:3], off
	v_lshl_add_u64 v[2:3], v[2:3], 0, s[14:15]
	global_load_dword v93, v[2:3], off
	v_lshl_add_u64 v[2:3], v[2:3], 0, s[14:15]
	global_load_dword v94, v[2:3], off
	v_lshl_add_u64 v[2:3], v[2:3], 0, s[14:15]
	global_load_dword v95, v[2:3], off
	v_lshl_add_u64 v[2:3], v[2:3], 0, s[14:15]
	global_load_dword v96, v[2:3], off
	v_lshl_add_u64 v[2:3], v[2:3], 0, s[14:15]
	global_load_dword v97, v[2:3], off
	v_lshl_add_u64 v[2:3], v[2:3], 0, s[14:15]
	global_load_dword v98, v[2:3], off
	v_lshl_add_u64 v[2:3], v[2:3], 0, s[14:15]
	global_load_dword v99, v[2:3], off
	v_lshl_add_u64 v[2:3], v[2:3], 0, s[14:15]
	global_load_dword v100, v[2:3], off
	v_lshl_add_u64 v[2:3], v[2:3], 0, s[14:15]
	global_load_dword v101, v[2:3], off
	v_lshl_add_u64 v[2:3], v[2:3], 0, s[14:15]
	global_load_dword v102, v[2:3], off
	v_lshl_add_u64 v[2:3], v[2:3], 0, s[14:15]
	global_load_dword v103, v[2:3], off
	v_lshl_add_u64 v[2:3], v[2:3], 0, s[14:15]
	global_load_dword v104, v[2:3], off
	v_lshl_add_u64 v[2:3], v[2:3], 0, s[14:15]
	global_load_dword v105, v[2:3], off
	v_lshl_add_u64 v[2:3], v[2:3], 0, s[14:15]
	global_load_dword v106, v[2:3], off
	v_lshl_add_u64 v[2:3], v[2:3], 0, s[14:15]
	global_load_dword v107, v[2:3], off
	v_lshl_add_u64 v[2:3], v[2:3], 0, s[14:15]
	global_load_dword v108, v[2:3], off
	v_lshl_add_u64 v[2:3], v[2:3], 0, s[14:15]
	global_load_dword v109, v[2:3], off
	v_lshl_add_u64 v[2:3], v[2:3], 0, s[14:15]
	global_load_dword v110, v[2:3], off
	v_lshl_add_u64 v[2:3], v[2:3], 0, s[14:15]
	global_load_dword v111, v[2:3], off
	v_lshl_add_u64 v[2:3], v[2:3], 0, s[14:15]
	global_load_dword v112, v[2:3], off
	v_lshl_add_u64 v[2:3], v[2:3], 0, s[14:15]
	global_load_dword v113, v[2:3], off
	v_lshl_add_u64 v[2:3], v[2:3], 0, s[14:15]
	global_load_dword v114, v[2:3], off
	v_lshl_add_u64 v[2:3], v[2:3], 0, s[14:15]
	global_load_dword v115, v[2:3], off
	v_lshl_add_u64 v[2:3], v[2:3], 0, s[14:15]
	s_mul_i32 s2, s33, 0x2100
	v_add_u32_e32 v192, s2, v190
	v_add_u32_e32 v193, s2, v191
	v_mov_b32_e32 v189, s2
	s_waitcnt vmcnt(48)
	ds_write_b128 v192, v[116:119]
	ds_write_b128 v192, v[120:123] offset:1024
	ds_write_b128 v192, v[124:127] offset:2048
	ds_write_b128 v192, v[128:131] offset:3072
	ds_write_b128 v193, v[132:135] offset:4096
	s_waitcnt lgkmcnt(0)
	ds_read_b128 v[116:119], v189 offset:4096
	ds_read_b128 v[120:123], v189 offset:0
	ds_read_b128 v[124:127], v189 offset:512
	ds_read_b128 v[128:131], v189 offset:1024
	ds_read_b128 v[132:135], v189 offset:1536
	ds_read_b128 v[136:139], v189 offset:2048
	ds_read_b128 v[140:143], v189 offset:2560
	ds_read_b128 v[144:147], v189 offset:3072
	ds_read_b128 v[148:151], v189 offset:3584
	s_waitcnt vmcnt(32)
	ds_read_b128 v[152:155], v189 offset:4112
	ds_read_b128 v[156:159], v189 offset:16
	ds_read_b128 v[160:163], v189 offset:528
	ds_read_b128 v[164:167], v189 offset:1040
	ds_read_b128 v[168:171], v189 offset:1552
	ds_read_b128 v[172:175], v189 offset:2064
	ds_read_b128 v[176:179], v189 offset:2576
	ds_read_b128 v[180:183], v189 offset:3088
	ds_read_b128 v[184:187], v189 offset:3600
	s_waitcnt lgkmcnt(9)
; __device__ __forceinline__ void prep_hybrid(const float* w_in, const float* w_out, const float* pool_w, const float* pool_scale, bf16_t* WIN, bf16_t* WOUT, int gw, int NGW, LAS float* scr, int lane) {
;     ...
;         for (int d = 0; d < 128; ++d) {
;             const float wv = w_out[(size_t)(512 + g * 128 + d) * D + n] * pool_scale[g * 128 + d];
; #pragma unroll
;             for (int i = 0; i < 8; ++i) a[i] += pw[i * 128 + d] * wv;
;         }
	v_mul_f32_e32 v188, v56, v116
	v_fmac_f32_e32 v6, v188, v120
	v_fmac_f32_e32 v7, v188, v124
	v_fmac_f32_e32 v8, v188, v128
	v_fmac_f32_e32 v9, v188, v132
	v_fmac_f32_e32 v10, v188, v136
	v_fmac_f32_e32 v11, v188, v140
	v_fmac_f32_e32 v4, v188, v144
	v_fmac_f32_e32 v5, v188, v148
	v_mul_f32_e32 v188, v57, v117
	v_fmac_f32_e32 v6, v188, v121
	v_fmac_f32_e32 v7, v188, v125
	v_fmac_f32_e32 v8, v188, v129
	v_fmac_f32_e32 v9, v188, v133
	v_fmac_f32_e32 v10, v188, v137
	v_fmac_f32_e32 v11, v188, v141
	v_fmac_f32_e32 v4, v188, v145
	v_fmac_f32_e32 v5, v188, v149
	v_mul_f32_e32 v188, v58, v118
	v_fmac_f32_e32 v6, v188, v122
	v_fmac_f32_e32 v7, v188, v126
	v_fmac_f32_e32 v8, v188, v130
	v_fmac_f32_e32 v9, v188, v134
	v_fmac_f32_e32 v10, v188, v138
	v_fmac_f32_e32 v11, v188, v142
	v_fmac_f32_e32 v4, v188, v146
	v_fmac_f32_e32 v5, v188, v150
	v_mul_f32_e32 v188, v59, v119
	v_fmac_f32_e32 v6, v188, v123
	v_fmac_f32_e32 v7, v188, v127
	v_fmac_f32_e32 v8, v188, v131
	v_fmac_f32_e32 v9, v188, v135
	v_fmac_f32_e32 v10, v188, v139
	v_fmac_f32_e32 v11, v188, v143
	v_fmac_f32_e32 v4, v188, v147
	v_fmac_f32_e32 v5, v188, v151
	ds_read_b128 v[116:119], v189 offset:4128
	ds_read_b128 v[120:123], v189 offset:32
	ds_read_b128 v[124:127], v189 offset:544
	ds_read_b128 v[128:131], v189 offset:1056
	ds_read_b128 v[132:135], v189 offset:1568
	ds_read_b128 v[136:139], v189 offset:2080
	ds_read_b128 v[140:143], v189 offset:2592
	ds_read_b128 v[144:147], v189 offset:3104
	ds_read_b128 v[148:151], v189 offset:3616
	s_waitcnt lgkmcnt(9)
	v_mul_f32_e32 v188, v68, v152
	v_fmac_f32_e32 v6, v188, v156
	v_fmac_f32_e32 v7, v188, v160
	v_fmac_f32_e32 v8, v188, v164
	v_fmac_f32_e32 v9, v188, v168
	v_fmac_f32_e32 v10, v188, v172
	v_fmac_f32_e32 v11, v188, v176
	v_fmac_f32_e32 v4, v188, v180
	v_fmac_f32_e32 v5, v188, v184
	v_mul_f32_e32 v188, v69, v153
	v_fmac_f32_e32 v6, v188, v157
	v_fmac_f32_e32 v7, v188, v161
	v_fmac_f32_e32 v8, v188, v165
	v_fmac_f32_e32 v9, v188, v169
	v_fmac_f32_e32 v10, v188, v173
	v_fmac_f32_e32 v11, v188, v177
	v_fmac_f32_e32 v4, v188, v181
	v_fmac_f32_e32 v5, v188, v185
	v_mul_f32_e32 v188, v70, v154
	v_fmac_f32_e32 v6, v188, v158
	v_fmac_f32_e32 v7, v188, v162
	v_fmac_f32_e32 v8, v188, v166
	v_fmac_f32_e32 v9, v188, v170
	v_fmac_f32_e32 v10, v188, v174
	v_fmac_f32_e32 v11, v188, v178
	v_fmac_f32_e32 v4, v188, v182
	v_fmac_f32_e32 v5, v188, v186
	v_mul_f32_e32 v188, v71, v155
	v_fmac_f32_e32 v6, v188, v159
	v_fmac_f32_e32 v7, v188, v163
	v_fmac_f32_e32 v8, v188, v167
	v_fmac_f32_e32 v9, v188, v171
	v_fmac_f32_e32 v10, v188, v175
	v_fmac_f32_e32 v11, v188, v179
	v_fmac_f32_e32 v4, v188, v183
	v_fmac_f32_e32 v5, v188, v187
	ds_read_b128 v[152:155], v189 offset:4144
	ds_read_b128 v[156:159], v189 offset:48
	ds_read_b128 v[160:163], v189 offset:560
	ds_read_b128 v[164:167], v189 offset:1072
	ds_read_b128 v[168:171], v189 offset:1584
	ds_read_b128 v[172:175], v189 offset:2096
	ds_read_b128 v[176:179], v189 offset:2608
	ds_read_b128 v[180:183], v189 offset:3120
	ds_read_b128 v[184:187], v189 offset:3632
	s_waitcnt lgkmcnt(9)
	v_mul_f32_e32 v188, v72, v116
	v_fmac_f32_e32 v6, v188, v120
	v_fmac_f32_e32 v7, v188, v124
	v_fmac_f32_e32 v8, v188, v128
	v_fmac_f32_e32 v9, v188, v132
	v_fmac_f32_e32 v10, v188, v136
	v_fmac_f32_e32 v11, v188, v140
	v_fmac_f32_e32 v4, v188, v144
	v_fmac_f32_e32 v5, v188, v148
	v_mul_f32_e32 v188, v73, v117
	v_fmac_f32_e32 v6, v188, v121
	v_fmac_f32_e32 v7, v188, v125
	v_fmac_f32_e32 v8, v188, v129
	v_fmac_f32_e32 v9, v188, v133
	v_fmac_f32_e32 v10, v188, v137
	v_fmac_f32_e32 v11, v188, v141
	v_fmac_f32_e32 v4, v188, v145
	v_fmac_f32_e32 v5, v188, v149
	v_mul_f32_e32 v188, v74, v118
	v_fmac_f32_e32 v6, v188, v122
	v_fmac_f32_e32 v7, v188, v126
	v_fmac_f32_e32 v8, v188, v130
	v_fmac_f32_e32 v9, v188, v134
	v_fmac_f32_e32 v10, v188, v138
	v_fmac_f32_e32 v11, v188, v142
	v_fmac_f32_e32 v4, v188, v146
	v_fmac_f32_e32 v5, v188, v150
	v_mul_f32_e32 v188, v75, v119
	v_fmac_f32_e32 v6, v188, v123
	v_fmac_f32_e32 v7, v188, v127
	v_fmac_f32_e32 v8, v188, v131
	v_fmac_f32_e32 v9, v188, v135
	v_fmac_f32_e32 v10, v188, v139
	v_fmac_f32_e32 v11, v188, v143
	v_fmac_f32_e32 v4, v188, v147
	v_fmac_f32_e32 v5, v188, v151
	ds_read_b128 v[116:119], v189 offset:4160
	ds_read_b128 v[120:123], v189 offset:64
	ds_read_b128 v[124:127], v189 offset:576
	ds_read_b128 v[128:131], v189 offset:1088
	ds_read_b128 v[132:135], v189 offset:1600
	ds_read_b128 v[136:139], v189 offset:2112
	ds_read_b128 v[140:143], v189 offset:2624
	ds_read_b128 v[144:147], v189 offset:3136
	ds_read_b128 v[148:151], v189 offset:3648
	s_waitcnt lgkmcnt(9)
; __device__ __forceinline__ void prep_hybrid(const float* w_in, const float* w_out, const float* pool_w, const float* pool_scale, bf16_t* WIN, bf16_t* WOUT, int gw, int NGW, LAS float* scr, int lane) {
;     ...
;         for (int d = 0; d < 128; ++d) {
;             const float wv = w_out[(size_t)(512 + g * 128 + d) * D + n] * pool_scale[g * 128 + d];
; #pragma unroll
;             for (int i = 0; i < 8; ++i) a[i] += pw[i * 128 + d] * wv;
;         }
	v_mul_f32_e32 v188, v76, v152
	v_fmac_f32_e32 v6, v188, v156
	v_fmac_f32_e32 v7, v188, v160
	v_fmac_f32_e32 v8, v188, v164
	v_fmac_f32_e32 v9, v188, v168
	v_fmac_f32_e32 v10, v188, v172
	v_fmac_f32_e32 v11, v188, v176
	v_fmac_f32_e32 v4, v188, v180
	v_fmac_f32_e32 v5, v188, v184
	v_mul_f32_e32 v188, v77, v153
	v_fmac_f32_e32 v6, v188, v157
	v_fmac_f32_e32 v7, v188, v161
	v_fmac_f32_e32 v8, v188, v165
	v_fmac_f32_e32 v9, v188, v169
	v_fmac_f32_e32 v10, v188, v173
	v_fmac_f32_e32 v11, v188, v177
	v_fmac_f32_e32 v4, v188, v181
	v_fmac_f32_e32 v5, v188, v185
	v_mul_f32_e32 v188, v78, v154
	v_fmac_f32_e32 v6, v188, v158
	v_fmac_f32_e32 v7, v188, v162
	v_fmac_f32_e32 v8, v188, v166
	v_fmac_f32_e32 v9, v188, v170
	v_fmac_f32_e32 v10, v188, v174
	v_fmac_f32_e32 v11, v188, v178
	v_fmac_f32_e32 v4, v188, v182
	v_fmac_f32_e32 v5, v188, v186
	v_mul_f32_e32 v188, v79, v155
	v_fmac_f32_e32 v6, v188, v159
	v_fmac_f32_e32 v7, v188, v163
	v_fmac_f32_e32 v8, v188, v167
	v_fmac_f32_e32 v9, v188, v171
	v_fmac_f32_e32 v10, v188, v175
	v_fmac_f32_e32 v11, v188, v179
	v_fmac_f32_e32 v4, v188, v183
	v_fmac_f32_e32 v5, v188, v187
	global_load_dword v56, v[2:3], off
	v_lshl_add_u64 v[2:3], v[2:3], 0, s[14:15]
	global_load_dword v57, v[2:3], off
	v_lshl_add_u64 v[2:3], v[2:3], 0, s[14:15]
	global_load_dword v58, v[2:3], off
	v_lshl_add_u64 v[2:3], v[2:3], 0, s[14:15]
	global_load_dword v59, v[2:3], off
	v_lshl_add_u64 v[2:3], v[2:3], 0, s[14:15]
	global_load_dword v68, v[2:3], off
	v_lshl_add_u64 v[2:3], v[2:3], 0, s[14:15]
	global_load_dword v69, v[2:3], off
	v_lshl_add_u64 v[2:3], v[2:3], 0, s[14:15]
	global_load_dword v70, v[2:3], off
	v_lshl_add_u64 v[2:3], v[2:3], 0, s[14:15]
	global_load_dword v71, v[2:3], off
	v_lshl_add_u64 v[2:3], v[2:3], 0, s[14:15]
	global_load_dword v72, v[2:3], off
	v_lshl_add_u64 v[2:3], v[2:3], 0, s[14:15]
	global_load_dword v73, v[2:3], off
	v_lshl_add_u64 v[2:3], v[2:3], 0, s[14:15]
	global_load_dword v74, v[2:3], off
	v_lshl_add_u64 v[2:3], v[2:3], 0, s[14:15]
	global_load_dword v75, v[2:3], off
	v_lshl_add_u64 v[2:3], v[2:3], 0, s[14:15]
	global_load_dword v76, v[2:3], off
	v_lshl_add_u64 v[2:3], v[2:3], 0, s[14:15]
	global_load_dword v77, v[2:3], off
	v_lshl_add_u64 v[2:3], v[2:3], 0, s[14:15]
	global_load_dword v78, v[2:3], off
	v_lshl_add_u64 v[2:3], v[2:3], 0, s[14:15]
	global_load_dword v79, v[2:3], off
	v_lshl_add_u64 v[2:3], v[2:3], 0, s[14:15]
	s_waitcnt vmcnt(32)
	ds_read_b128 v[152:155], v189 offset:4176
	ds_read_b128 v[156:159], v189 offset:80
	ds_read_b128 v[160:163], v189 offset:592
	ds_read_b128 v[164:167], v189 offset:1104
	ds_read_b128 v[168:171], v189 offset:1616
	ds_read_b128 v[172:175], v189 offset:2128
	ds_read_b128 v[176:179], v189 offset:2640
	ds_read_b128 v[180:183], v189 offset:3152
	ds_read_b128 v[184:187], v189 offset:3664
	s_waitcnt lgkmcnt(9)
	v_mul_f32_e32 v188, v80, v116
	v_fmac_f32_e32 v6, v188, v120
	v_fmac_f32_e32 v7, v188, v124
	v_fmac_f32_e32 v8, v188, v128
	v_fmac_f32_e32 v9, v188, v132
	v_fmac_f32_e32 v10, v188, v136
	v_fmac_f32_e32 v11, v188, v140
	v_fmac_f32_e32 v4, v188, v144
	v_fmac_f32_e32 v5, v188, v148
	v_mul_f32_e32 v188, v81, v117
	v_fmac_f32_e32 v6, v188, v121
	v_fmac_f32_e32 v7, v188, v125
	v_fmac_f32_e32 v8, v188, v129
	v_fmac_f32_e32 v9, v188, v133
	v_fmac_f32_e32 v10, v188, v137
	v_fmac_f32_e32 v11, v188, v141
	v_fmac_f32_e32 v4, v188, v145
	v_fmac_f32_e32 v5, v188, v149
	v_mul_f32_e32 v188, v82, v118
	v_fmac_f32_e32 v6, v188, v122
	v_fmac_f32_e32 v7, v188, v126
	v_fmac_f32_e32 v8, v188, v130
	v_fmac_f32_e32 v9, v188, v134
	v_fmac_f32_e32 v10, v188, v138
	v_fmac_f32_e32 v11, v188, v142
	v_fmac_f32_e32 v4, v188, v146
	v_fmac_f32_e32 v5, v188, v150
	v_mul_f32_e32 v188, v83, v119
	v_fmac_f32_e32 v6, v188, v123
	v_fmac_f32_e32 v7, v188, v127
	v_fmac_f32_e32 v8, v188, v131
	v_fmac_f32_e32 v9, v188, v135
	v_fmac_f32_e32 v10, v188, v139
	v_fmac_f32_e32 v11, v188, v143
	v_fmac_f32_e32 v4, v188, v147
	v_fmac_f32_e32 v5, v188, v151
	ds_read_b128 v[116:119], v189 offset:4192
	ds_read_b128 v[120:123], v189 offset:96
	ds_read_b128 v[124:127], v189 offset:608
	ds_read_b128 v[128:131], v189 offset:1120
	ds_read_b128 v[132:135], v189 offset:1632
	ds_read_b128 v[136:139], v189 offset:2144
	ds_read_b128 v[140:143], v189 offset:2656
	ds_read_b128 v[144:147], v189 offset:3168
	ds_read_b128 v[148:151], v189 offset:3680
	s_waitcnt lgkmcnt(9)
	v_mul_f32_e32 v188, v84, v152
	v_fmac_f32_e32 v6, v188, v156
	v_fmac_f32_e32 v7, v188, v160
	v_fmac_f32_e32 v8, v188, v164
	v_fmac_f32_e32 v9, v188, v168
	v_fmac_f32_e32 v10, v188, v172
	v_fmac_f32_e32 v11, v188, v176
	v_fmac_f32_e32 v4, v188, v180
	v_fmac_f32_e32 v5, v188, v184
	v_mul_f32_e32 v188, v85, v153
	v_fmac_f32_e32 v6, v188, v157
	v_fmac_f32_e32 v7, v188, v161
	v_fmac_f32_e32 v8, v188, v165
	v_fmac_f32_e32 v9, v188, v169
	v_fmac_f32_e32 v10, v188, v173
	v_fmac_f32_e32 v11, v188, v177
	v_fmac_f32_e32 v4, v188, v181
	v_fmac_f32_e32 v5, v188, v185
	v_mul_f32_e32 v188, v86, v154
	v_fmac_f32_e32 v6, v188, v158
	v_fmac_f32_e32 v7, v188, v162
	v_fmac_f32_e32 v8, v188, v166
	v_fmac_f32_e32 v9, v188, v170
	v_fmac_f32_e32 v10, v188, v174
	v_fmac_f32_e32 v11, v188, v178
	v_fmac_f32_e32 v4, v188, v182
	v_fmac_f32_e32 v5, v188, v186
	v_mul_f32_e32 v188, v87, v155
	v_fmac_f32_e32 v6, v188, v159
	v_fmac_f32_e32 v7, v188, v163
	v_fmac_f32_e32 v8, v188, v167
	v_fmac_f32_e32 v9, v188, v171
	v_fmac_f32_e32 v10, v188, v175
	v_fmac_f32_e32 v11, v188, v179
	v_fmac_f32_e32 v4, v188, v183
	v_fmac_f32_e32 v5, v188, v187
	ds_read_b128 v[152:155], v189 offset:4208
	ds_read_b128 v[156:159], v189 offset:112
	ds_read_b128 v[160:163], v189 offset:624
	ds_read_b128 v[164:167], v189 offset:1136
	ds_read_b128 v[168:171], v189 offset:1648
	ds_read_b128 v[172:175], v189 offset:2160
	ds_read_b128 v[176:179], v189 offset:2672
	ds_read_b128 v[180:183], v189 offset:3184
	ds_read_b128 v[184:187], v189 offset:3696
	s_waitcnt lgkmcnt(9)
; __device__ __forceinline__ void prep_hybrid(const float* w_in, const float* w_out, const float* pool_w, const float* pool_scale, bf16_t* WIN, bf16_t* WOUT, int gw, int NGW, LAS float* scr, int lane) {
;     ...
;         for (int d = 0; d < 128; ++d) {
;             const float wv = w_out[(size_t)(512 + g * 128 + d) * D + n] * pool_scale[g * 128 + d];
; #pragma unroll
;             for (int i = 0; i < 8; ++i) a[i] += pw[i * 128 + d] * wv;
;         }
	v_mul_f32_e32 v188, v92, v116
	v_fmac_f32_e32 v6, v188, v120
	v_fmac_f32_e32 v7, v188, v124
	v_fmac_f32_e32 v8, v188, v128
	v_fmac_f32_e32 v9, v188, v132
	v_fmac_f32_e32 v10, v188, v136
	v_fmac_f32_e32 v11, v188, v140
	v_fmac_f32_e32 v4, v188, v144
	v_fmac_f32_e32 v5, v188, v148
	v_mul_f32_e32 v188, v93, v117
	v_fmac_f32_e32 v6, v188, v121
	v_fmac_f32_e32 v7, v188, v125
	v_fmac_f32_e32 v8, v188, v129
	v_fmac_f32_e32 v9, v188, v133
	v_fmac_f32_e32 v10, v188, v137
	v_fmac_f32_e32 v11, v188, v141
	v_fmac_f32_e32 v4, v188, v145
	v_fmac_f32_e32 v5, v188, v149
	v_mul_f32_e32 v188, v94, v118
	v_fmac_f32_e32 v6, v188, v122
	v_fmac_f32_e32 v7, v188, v126
	v_fmac_f32_e32 v8, v188, v130
	v_fmac_f32_e32 v9, v188, v134
	v_fmac_f32_e32 v10, v188, v138
	v_fmac_f32_e32 v11, v188, v142
	v_fmac_f32_e32 v4, v188, v146
	v_fmac_f32_e32 v5, v188, v150
	v_mul_f32_e32 v188, v95, v119
	v_fmac_f32_e32 v6, v188, v123
	v_fmac_f32_e32 v7, v188, v127
	v_fmac_f32_e32 v8, v188, v131
	v_fmac_f32_e32 v9, v188, v135
	v_fmac_f32_e32 v10, v188, v139
	v_fmac_f32_e32 v11, v188, v143
	v_fmac_f32_e32 v4, v188, v147
	v_fmac_f32_e32 v5, v188, v151
	ds_read_b128 v[116:119], v189 offset:4224
	ds_read_b128 v[120:123], v189 offset:128
	ds_read_b128 v[124:127], v189 offset:640
	ds_read_b128 v[128:131], v189 offset:1152
	ds_read_b128 v[132:135], v189 offset:1664
	ds_read_b128 v[136:139], v189 offset:2176
	ds_read_b128 v[140:143], v189 offset:2688
	ds_read_b128 v[144:147], v189 offset:3200
	ds_read_b128 v[148:151], v189 offset:3712
	s_waitcnt lgkmcnt(9)
	v_mul_f32_e32 v188, v96, v152
	v_fmac_f32_e32 v6, v188, v156
	v_fmac_f32_e32 v7, v188, v160
	v_fmac_f32_e32 v8, v188, v164
	v_fmac_f32_e32 v9, v188, v168
	v_fmac_f32_e32 v10, v188, v172
	v_fmac_f32_e32 v11, v188, v176
	v_fmac_f32_e32 v4, v188, v180
	v_fmac_f32_e32 v5, v188, v184
	v_mul_f32_e32 v188, v97, v153
	v_fmac_f32_e32 v6, v188, v157
	v_fmac_f32_e32 v7, v188, v161
	v_fmac_f32_e32 v8, v188, v165
	v_fmac_f32_e32 v9, v188, v169
	v_fmac_f32_e32 v10, v188, v173
	v_fmac_f32_e32 v11, v188, v177
	v_fmac_f32_e32 v4, v188, v181
	v_fmac_f32_e32 v5, v188, v185
	v_mul_f32_e32 v188, v98, v154
	v_fmac_f32_e32 v6, v188, v158
	v_fmac_f32_e32 v7, v188, v162
	v_fmac_f32_e32 v8, v188, v166
	v_fmac_f32_e32 v9, v188, v170
	v_fmac_f32_e32 v10, v188, v174
	v_fmac_f32_e32 v11, v188, v178
	v_fmac_f32_e32 v4, v188, v182
	v_fmac_f32_e32 v5, v188, v186
	v_mul_f32_e32 v188, v99, v155
	v_fmac_f32_e32 v6, v188, v159
	v_fmac_f32_e32 v7, v188, v163
	v_fmac_f32_e32 v8, v188, v167
	v_fmac_f32_e32 v9, v188, v171
	v_fmac_f32_e32 v10, v188, v175
	v_fmac_f32_e32 v11, v188, v179
	v_fmac_f32_e32 v4, v188, v183
	v_fmac_f32_e32 v5, v188, v187
	global_load_dword v80, v[2:3], off
	v_lshl_add_u64 v[2:3], v[2:3], 0, s[14:15]
	global_load_dword v81, v[2:3], off
	v_lshl_add_u64 v[2:3], v[2:3], 0, s[14:15]
	global_load_dword v82, v[2:3], off
	v_lshl_add_u64 v[2:3], v[2:3], 0, s[14:15]
	global_load_dword v83, v[2:3], off
	v_lshl_add_u64 v[2:3], v[2:3], 0, s[14:15]
	global_load_dword v84, v[2:3], off
	v_lshl_add_u64 v[2:3], v[2:3], 0, s[14:15]
	global_load_dword v85, v[2:3], off
	v_lshl_add_u64 v[2:3], v[2:3], 0, s[14:15]
	global_load_dword v86, v[2:3], off
	v_lshl_add_u64 v[2:3], v[2:3], 0, s[14:15]
	global_load_dword v87, v[2:3], off
	v_lshl_add_u64 v[2:3], v[2:3], 0, s[14:15]
	global_load_dword v92, v[2:3], off
	v_lshl_add_u64 v[2:3], v[2:3], 0, s[14:15]
	global_load_dword v93, v[2:3], off
	v_lshl_add_u64 v[2:3], v[2:3], 0, s[14:15]
	global_load_dword v94, v[2:3], off
	v_lshl_add_u64 v[2:3], v[2:3], 0, s[14:15]
	global_load_dword v95, v[2:3], off
	v_lshl_add_u64 v[2:3], v[2:3], 0, s[14:15]
	global_load_dword v96, v[2:3], off
	v_lshl_add_u64 v[2:3], v[2:3], 0, s[14:15]
	global_load_dword v97, v[2:3], off
	v_lshl_add_u64 v[2:3], v[2:3], 0, s[14:15]
	global_load_dword v98, v[2:3], off
	v_lshl_add_u64 v[2:3], v[2:3], 0, s[14:15]
	global_load_dword v99, v[2:3], off
	v_lshl_add_u64 v[2:3], v[2:3], 0, s[14:15]
	s_waitcnt vmcnt(32)
	ds_read_b128 v[152:155], v189 offset:4240
	ds_read_b128 v[156:159], v189 offset:144
	ds_read_b128 v[160:163], v189 offset:656
	ds_read_b128 v[164:167], v189 offset:1168
	ds_read_b128 v[168:171], v189 offset:1680
	ds_read_b128 v[172:175], v189 offset:2192
	ds_read_b128 v[176:179], v189 offset:2704
	ds_read_b128 v[180:183], v189 offset:3216
	ds_read_b128 v[184:187], v189 offset:3728
	s_waitcnt lgkmcnt(9)
	v_mul_f32_e32 v188, v100, v116
	v_fmac_f32_e32 v6, v188, v120
	v_fmac_f32_e32 v7, v188, v124
	v_fmac_f32_e32 v8, v188, v128
	v_fmac_f32_e32 v9, v188, v132
	v_fmac_f32_e32 v10, v188, v136
	v_fmac_f32_e32 v11, v188, v140
	v_fmac_f32_e32 v4, v188, v144
	v_fmac_f32_e32 v5, v188, v148
	v_mul_f32_e32 v188, v101, v117
	v_fmac_f32_e32 v6, v188, v121
	v_fmac_f32_e32 v7, v188, v125
	v_fmac_f32_e32 v8, v188, v129
	v_fmac_f32_e32 v9, v188, v133
	v_fmac_f32_e32 v10, v188, v137
	v_fmac_f32_e32 v11, v188, v141
	v_fmac_f32_e32 v4, v188, v145
	v_fmac_f32_e32 v5, v188, v149
	v_mul_f32_e32 v188, v102, v118
	v_fmac_f32_e32 v6, v188, v122
	v_fmac_f32_e32 v7, v188, v126
	v_fmac_f32_e32 v8, v188, v130
	v_fmac_f32_e32 v9, v188, v134
	v_fmac_f32_e32 v10, v188, v138
	v_fmac_f32_e32 v11, v188, v142
	v_fmac_f32_e32 v4, v188, v146
	v_fmac_f32_e32 v5, v188, v150
	v_mul_f32_e32 v188, v103, v119
	v_fmac_f32_e32 v6, v188, v123
	v_fmac_f32_e32 v7, v188, v127
	v_fmac_f32_e32 v8, v188, v131
	v_fmac_f32_e32 v9, v188, v135
	v_fmac_f32_e32 v10, v188, v139
	v_fmac_f32_e32 v11, v188, v143
	v_fmac_f32_e32 v4, v188, v147
	v_fmac_f32_e32 v5, v188, v151
	ds_read_b128 v[116:119], v189 offset:4256
	ds_read_b128 v[120:123], v189 offset:160
	ds_read_b128 v[124:127], v189 offset:672
	ds_read_b128 v[128:131], v189 offset:1184
	ds_read_b128 v[132:135], v189 offset:1696
	ds_read_b128 v[136:139], v189 offset:2208
	ds_read_b128 v[140:143], v189 offset:2720
	ds_read_b128 v[144:147], v189 offset:3232
	ds_read_b128 v[148:151], v189 offset:3744
	s_waitcnt lgkmcnt(9)
; __device__ __forceinline__ void prep_hybrid(const float* w_in, const float* w_out, const float* pool_w, const float* pool_scale, bf16_t* WIN, bf16_t* WOUT, int gw, int NGW, LAS float* scr, int lane) {
;     ...
;         for (int d = 0; d < 128; ++d) {
;             const float wv = w_out[(size_t)(512 + g * 128 + d) * D + n] * pool_scale[g * 128 + d];
; #pragma unroll
;             for (int i = 0; i < 8; ++i) a[i] += pw[i * 128 + d] * wv;
;         }
	v_mul_f32_e32 v188, v104, v152
	v_fmac_f32_e32 v6, v188, v156
	v_fmac_f32_e32 v7, v188, v160
	v_fmac_f32_e32 v8, v188, v164
	v_fmac_f32_e32 v9, v188, v168
	v_fmac_f32_e32 v10, v188, v172
	v_fmac_f32_e32 v11, v188, v176
	v_fmac_f32_e32 v4, v188, v180
	v_fmac_f32_e32 v5, v188, v184
	v_mul_f32_e32 v188, v105, v153
	v_fmac_f32_e32 v6, v188, v157
	v_fmac_f32_e32 v7, v188, v161
	v_fmac_f32_e32 v8, v188, v165
	v_fmac_f32_e32 v9, v188, v169
	v_fmac_f32_e32 v10, v188, v173
	v_fmac_f32_e32 v11, v188, v177
	v_fmac_f32_e32 v4, v188, v181
	v_fmac_f32_e32 v5, v188, v185
	v_mul_f32_e32 v188, v106, v154
	v_fmac_f32_e32 v6, v188, v158
	v_fmac_f32_e32 v7, v188, v162
	v_fmac_f32_e32 v8, v188, v166
	v_fmac_f32_e32 v9, v188, v170
	v_fmac_f32_e32 v10, v188, v174
	v_fmac_f32_e32 v11, v188, v178
	v_fmac_f32_e32 v4, v188, v182
	v_fmac_f32_e32 v5, v188, v186
	v_mul_f32_e32 v188, v107, v155
	v_fmac_f32_e32 v6, v188, v159
	v_fmac_f32_e32 v7, v188, v163
	v_fmac_f32_e32 v8, v188, v167
	v_fmac_f32_e32 v9, v188, v171
	v_fmac_f32_e32 v10, v188, v175
	v_fmac_f32_e32 v11, v188, v179
	v_fmac_f32_e32 v4, v188, v183
	v_fmac_f32_e32 v5, v188, v187
	ds_read_b128 v[152:155], v189 offset:4272
	ds_read_b128 v[156:159], v189 offset:176
	ds_read_b128 v[160:163], v189 offset:688
	ds_read_b128 v[164:167], v189 offset:1200
	ds_read_b128 v[168:171], v189 offset:1712
	ds_read_b128 v[172:175], v189 offset:2224
	ds_read_b128 v[176:179], v189 offset:2736
	ds_read_b128 v[180:183], v189 offset:3248
	ds_read_b128 v[184:187], v189 offset:3760
	s_waitcnt lgkmcnt(9)
	v_mul_f32_e32 v188, v108, v116
	v_fmac_f32_e32 v6, v188, v120
	v_fmac_f32_e32 v7, v188, v124
	v_fmac_f32_e32 v8, v188, v128
	v_fmac_f32_e32 v9, v188, v132
	v_fmac_f32_e32 v10, v188, v136
	v_fmac_f32_e32 v11, v188, v140
	v_fmac_f32_e32 v4, v188, v144
	v_fmac_f32_e32 v5, v188, v148
	v_mul_f32_e32 v188, v109, v117
	v_fmac_f32_e32 v6, v188, v121
	v_fmac_f32_e32 v7, v188, v125
	v_fmac_f32_e32 v8, v188, v129
	v_fmac_f32_e32 v9, v188, v133
	v_fmac_f32_e32 v10, v188, v137
	v_fmac_f32_e32 v11, v188, v141
	v_fmac_f32_e32 v4, v188, v145
	v_fmac_f32_e32 v5, v188, v149
	v_mul_f32_e32 v188, v110, v118
	v_fmac_f32_e32 v6, v188, v122
	v_fmac_f32_e32 v7, v188, v126
	v_fmac_f32_e32 v8, v188, v130
	v_fmac_f32_e32 v9, v188, v134
	v_fmac_f32_e32 v10, v188, v138
	v_fmac_f32_e32 v11, v188, v142
	v_fmac_f32_e32 v4, v188, v146
	v_fmac_f32_e32 v5, v188, v150
	v_mul_f32_e32 v188, v111, v119
	v_fmac_f32_e32 v6, v188, v123
	v_fmac_f32_e32 v7, v188, v127
	v_fmac_f32_e32 v8, v188, v131
	v_fmac_f32_e32 v9, v188, v135
	v_fmac_f32_e32 v10, v188, v139
	v_fmac_f32_e32 v11, v188, v143
	v_fmac_f32_e32 v4, v188, v147
	v_fmac_f32_e32 v5, v188, v151
	ds_read_b128 v[116:119], v189 offset:4288
	ds_read_b128 v[120:123], v189 offset:192
	ds_read_b128 v[124:127], v189 offset:704
	ds_read_b128 v[128:131], v189 offset:1216
	ds_read_b128 v[132:135], v189 offset:1728
	ds_read_b128 v[136:139], v189 offset:2240
	ds_read_b128 v[140:143], v189 offset:2752
	ds_read_b128 v[144:147], v189 offset:3264
	ds_read_b128 v[148:151], v189 offset:3776
	s_waitcnt lgkmcnt(9)
	v_mul_f32_e32 v188, v112, v152
	v_fmac_f32_e32 v6, v188, v156
	v_fmac_f32_e32 v7, v188, v160
	v_fmac_f32_e32 v8, v188, v164
	v_fmac_f32_e32 v9, v188, v168
	v_fmac_f32_e32 v10, v188, v172
	v_fmac_f32_e32 v11, v188, v176
	v_fmac_f32_e32 v4, v188, v180
	v_fmac_f32_e32 v5, v188, v184
	v_mul_f32_e32 v188, v113, v153
	v_fmac_f32_e32 v6, v188, v157
	v_fmac_f32_e32 v7, v188, v161
	v_fmac_f32_e32 v8, v188, v165
	v_fmac_f32_e32 v9, v188, v169
	v_fmac_f32_e32 v10, v188, v173
	v_fmac_f32_e32 v11, v188, v177
	v_fmac_f32_e32 v4, v188, v181
	v_fmac_f32_e32 v5, v188, v185
	v_mul_f32_e32 v188, v114, v154
	v_fmac_f32_e32 v6, v188, v158
	v_fmac_f32_e32 v7, v188, v162
	v_fmac_f32_e32 v8, v188, v166
	v_fmac_f32_e32 v9, v188, v170
	v_fmac_f32_e32 v10, v188, v174
	v_fmac_f32_e32 v11, v188, v178
	v_fmac_f32_e32 v4, v188, v182
	v_fmac_f32_e32 v5, v188, v186
	v_mul_f32_e32 v188, v115, v155
	v_fmac_f32_e32 v6, v188, v159
	v_fmac_f32_e32 v7, v188, v163
	v_fmac_f32_e32 v8, v188, v167
	v_fmac_f32_e32 v9, v188, v171
	v_fmac_f32_e32 v10, v188, v175
	v_fmac_f32_e32 v11, v188, v179
	v_fmac_f32_e32 v4, v188, v183
	v_fmac_f32_e32 v5, v188, v187
	global_load_dword v100, v[2:3], off
	v_lshl_add_u64 v[2:3], v[2:3], 0, s[14:15]
	global_load_dword v101, v[2:3], off
	v_lshl_add_u64 v[2:3], v[2:3], 0, s[14:15]
	global_load_dword v102, v[2:3], off
	v_lshl_add_u64 v[2:3], v[2:3], 0, s[14:15]
	global_load_dword v103, v[2:3], off
	v_lshl_add_u64 v[2:3], v[2:3], 0, s[14:15]
	global_load_dword v104, v[2:3], off
	v_lshl_add_u64 v[2:3], v[2:3], 0, s[14:15]
	global_load_dword v105, v[2:3], off
	v_lshl_add_u64 v[2:3], v[2:3], 0, s[14:15]
	global_load_dword v106, v[2:3], off
	v_lshl_add_u64 v[2:3], v[2:3], 0, s[14:15]
	global_load_dword v107, v[2:3], off
	v_lshl_add_u64 v[2:3], v[2:3], 0, s[14:15]
	global_load_dword v108, v[2:3], off
	v_lshl_add_u64 v[2:3], v[2:3], 0, s[14:15]
	global_load_dword v109, v[2:3], off
	v_lshl_add_u64 v[2:3], v[2:3], 0, s[14:15]
	global_load_dword v110, v[2:3], off
	v_lshl_add_u64 v[2:3], v[2:3], 0, s[14:15]
	global_load_dword v111, v[2:3], off
	v_lshl_add_u64 v[2:3], v[2:3], 0, s[14:15]
	global_load_dword v112, v[2:3], off
	v_lshl_add_u64 v[2:3], v[2:3], 0, s[14:15]
	global_load_dword v113, v[2:3], off
	v_lshl_add_u64 v[2:3], v[2:3], 0, s[14:15]
	global_load_dword v114, v[2:3], off
	v_lshl_add_u64 v[2:3], v[2:3], 0, s[14:15]
	global_load_dword v115, v[2:3], off
	v_lshl_add_u64 v[2:3], v[2:3], 0, s[14:15]
	s_waitcnt vmcnt(32)
; __device__ __forceinline__ void prep_hybrid(const float* w_in, const float* w_out, const float* pool_w, const float* pool_scale, bf16_t* WIN, bf16_t* WOUT, int gw, int NGW, LAS float* scr, int lane) {
;     ...
;         for (int d = 0; d < 128; ++d) {
;             const float wv = w_out[(size_t)(512 + g * 128 + d) * D + n] * pool_scale[g * 128 + d];
; #pragma unroll
;             for (int i = 0; i < 8; ++i) a[i] += pw[i * 128 + d] * wv;
;         }
	ds_read_b128 v[152:155], v189 offset:4304
	ds_read_b128 v[156:159], v189 offset:208
	ds_read_b128 v[160:163], v189 offset:720
	ds_read_b128 v[164:167], v189 offset:1232
	ds_read_b128 v[168:171], v189 offset:1744
	ds_read_b128 v[172:175], v189 offset:2256
	ds_read_b128 v[176:179], v189 offset:2768
	ds_read_b128 v[180:183], v189 offset:3280
	ds_read_b128 v[184:187], v189 offset:3792
	s_waitcnt lgkmcnt(9)
	v_mul_f32_e32 v188, v56, v116
	v_fmac_f32_e32 v6, v188, v120
	v_fmac_f32_e32 v7, v188, v124
	v_fmac_f32_e32 v8, v188, v128
	v_fmac_f32_e32 v9, v188, v132
	v_fmac_f32_e32 v10, v188, v136
	v_fmac_f32_e32 v11, v188, v140
	v_fmac_f32_e32 v4, v188, v144
	v_fmac_f32_e32 v5, v188, v148
	v_mul_f32_e32 v188, v57, v117
	v_fmac_f32_e32 v6, v188, v121
	v_fmac_f32_e32 v7, v188, v125
	v_fmac_f32_e32 v8, v188, v129
	v_fmac_f32_e32 v9, v188, v133
	v_fmac_f32_e32 v10, v188, v137
	v_fmac_f32_e32 v11, v188, v141
	v_fmac_f32_e32 v4, v188, v145
	v_fmac_f32_e32 v5, v188, v149
	v_mul_f32_e32 v188, v58, v118
	v_fmac_f32_e32 v6, v188, v122
	v_fmac_f32_e32 v7, v188, v126
	v_fmac_f32_e32 v8, v188, v130
	v_fmac_f32_e32 v9, v188, v134
	v_fmac_f32_e32 v10, v188, v138
	v_fmac_f32_e32 v11, v188, v142
	v_fmac_f32_e32 v4, v188, v146
	v_fmac_f32_e32 v5, v188, v150
	v_mul_f32_e32 v188, v59, v119
	v_fmac_f32_e32 v6, v188, v123
	v_fmac_f32_e32 v7, v188, v127
	v_fmac_f32_e32 v8, v188, v131
	v_fmac_f32_e32 v9, v188, v135
	v_fmac_f32_e32 v10, v188, v139
	v_fmac_f32_e32 v11, v188, v143
	v_fmac_f32_e32 v4, v188, v147
	v_fmac_f32_e32 v5, v188, v151
	ds_read_b128 v[116:119], v189 offset:4320
	ds_read_b128 v[120:123], v189 offset:224
	ds_read_b128 v[124:127], v189 offset:736
	ds_read_b128 v[128:131], v189 offset:1248
	ds_read_b128 v[132:135], v189 offset:1760
	ds_read_b128 v[136:139], v189 offset:2272
	ds_read_b128 v[140:143], v189 offset:2784
	ds_read_b128 v[144:147], v189 offset:3296
	ds_read_b128 v[148:151], v189 offset:3808
	s_waitcnt lgkmcnt(9)
	v_mul_f32_e32 v188, v68, v152
	v_fmac_f32_e32 v6, v188, v156
	v_fmac_f32_e32 v7, v188, v160
	v_fmac_f32_e32 v8, v188, v164
	v_fmac_f32_e32 v9, v188, v168
	v_fmac_f32_e32 v10, v188, v172
	v_fmac_f32_e32 v11, v188, v176
	v_fmac_f32_e32 v4, v188, v180
	v_fmac_f32_e32 v5, v188, v184
	v_mul_f32_e32 v188, v69, v153
	v_fmac_f32_e32 v6, v188, v157
	v_fmac_f32_e32 v7, v188, v161
	v_fmac_f32_e32 v8, v188, v165
	v_fmac_f32_e32 v9, v188, v169
	v_fmac_f32_e32 v10, v188, v173
	v_fmac_f32_e32 v11, v188, v177
	v_fmac_f32_e32 v4, v188, v181
	v_fmac_f32_e32 v5, v188, v185
	v_mul_f32_e32 v188, v70, v154
	v_fmac_f32_e32 v6, v188, v158
	v_fmac_f32_e32 v7, v188, v162
	v_fmac_f32_e32 v8, v188, v166
	v_fmac_f32_e32 v9, v188, v170
	v_fmac_f32_e32 v10, v188, v174
	v_fmac_f32_e32 v11, v188, v178
	v_fmac_f32_e32 v4, v188, v182
	v_fmac_f32_e32 v5, v188, v186
	v_mul_f32_e32 v188, v71, v155
	v_fmac_f32_e32 v6, v188, v159
	v_fmac_f32_e32 v7, v188, v163
	v_fmac_f32_e32 v8, v188, v167
	v_fmac_f32_e32 v9, v188, v171
	v_fmac_f32_e32 v10, v188, v175
	v_fmac_f32_e32 v11, v188, v179
	v_fmac_f32_e32 v4, v188, v183
	v_fmac_f32_e32 v5, v188, v187
	ds_read_b128 v[152:155], v189 offset:4336
	ds_read_b128 v[156:159], v189 offset:240
	ds_read_b128 v[160:163], v189 offset:752
	ds_read_b128 v[164:167], v189 offset:1264
	ds_read_b128 v[168:171], v189 offset:1776
	ds_read_b128 v[172:175], v189 offset:2288
	ds_read_b128 v[176:179], v189 offset:2800
	ds_read_b128 v[180:183], v189 offset:3312
	ds_read_b128 v[184:187], v189 offset:3824
	s_waitcnt lgkmcnt(9)
	v_mul_f32_e32 v188, v72, v116
	v_fmac_f32_e32 v6, v188, v120
	v_fmac_f32_e32 v7, v188, v124
	v_fmac_f32_e32 v8, v188, v128
	v_fmac_f32_e32 v9, v188, v132
	v_fmac_f32_e32 v10, v188, v136
	v_fmac_f32_e32 v11, v188, v140
	v_fmac_f32_e32 v4, v188, v144
	v_fmac_f32_e32 v5, v188, v148
	v_mul_f32_e32 v188, v73, v117
	v_fmac_f32_e32 v6, v188, v121
	v_fmac_f32_e32 v7, v188, v125
	v_fmac_f32_e32 v8, v188, v129
	v_fmac_f32_e32 v9, v188, v133
	v_fmac_f32_e32 v10, v188, v137
	v_fmac_f32_e32 v11, v188, v141
	v_fmac_f32_e32 v4, v188, v145
	v_fmac_f32_e32 v5, v188, v149
	v_mul_f32_e32 v188, v74, v118
	v_fmac_f32_e32 v6, v188, v122
	v_fmac_f32_e32 v7, v188, v126
	v_fmac_f32_e32 v8, v188, v130
	v_fmac_f32_e32 v9, v188, v134
	v_fmac_f32_e32 v10, v188, v138
	v_fmac_f32_e32 v11, v188, v142
	v_fmac_f32_e32 v4, v188, v146
	v_fmac_f32_e32 v5, v188, v150
	v_mul_f32_e32 v188, v75, v119
	v_fmac_f32_e32 v6, v188, v123
	v_fmac_f32_e32 v7, v188, v127
	v_fmac_f32_e32 v8, v188, v131
	v_fmac_f32_e32 v9, v188, v135
	v_fmac_f32_e32 v10, v188, v139
	v_fmac_f32_e32 v11, v188, v143
	v_fmac_f32_e32 v4, v188, v147
	v_fmac_f32_e32 v5, v188, v151
	ds_read_b128 v[116:119], v189 offset:4352
	ds_read_b128 v[120:123], v189 offset:256
	ds_read_b128 v[124:127], v189 offset:768
	ds_read_b128 v[128:131], v189 offset:1280
	ds_read_b128 v[132:135], v189 offset:1792
	ds_read_b128 v[136:139], v189 offset:2304
	ds_read_b128 v[140:143], v189 offset:2816
	ds_read_b128 v[144:147], v189 offset:3328
	ds_read_b128 v[148:151], v189 offset:3840
	s_waitcnt lgkmcnt(9)
; __device__ __forceinline__ void prep_hybrid(const float* w_in, const float* w_out, const float* pool_w, const float* pool_scale, bf16_t* WIN, bf16_t* WOUT, int gw, int NGW, LAS float* scr, int lane) {
;     ...
;         for (int d = 0; d < 128; ++d) {
;             const float wv = w_out[(size_t)(512 + g * 128 + d) * D + n] * pool_scale[g * 128 + d];
; #pragma unroll
;             for (int i = 0; i < 8; ++i) a[i] += pw[i * 128 + d] * wv;
;         }
	v_mul_f32_e32 v188, v76, v152
	v_fmac_f32_e32 v6, v188, v156
	v_fmac_f32_e32 v7, v188, v160
	v_fmac_f32_e32 v8, v188, v164
	v_fmac_f32_e32 v9, v188, v168
	v_fmac_f32_e32 v10, v188, v172
	v_fmac_f32_e32 v11, v188, v176
	v_fmac_f32_e32 v4, v188, v180
	v_fmac_f32_e32 v5, v188, v184
	v_mul_f32_e32 v188, v77, v153
	v_fmac_f32_e32 v6, v188, v157
	v_fmac_f32_e32 v7, v188, v161
	v_fmac_f32_e32 v8, v188, v165
	v_fmac_f32_e32 v9, v188, v169
	v_fmac_f32_e32 v10, v188, v173
	v_fmac_f32_e32 v11, v188, v177
	v_fmac_f32_e32 v4, v188, v181
	v_fmac_f32_e32 v5, v188, v185
	v_mul_f32_e32 v188, v78, v154
	v_fmac_f32_e32 v6, v188, v158
	v_fmac_f32_e32 v7, v188, v162
	v_fmac_f32_e32 v8, v188, v166
	v_fmac_f32_e32 v9, v188, v170
	v_fmac_f32_e32 v10, v188, v174
	v_fmac_f32_e32 v11, v188, v178
	v_fmac_f32_e32 v4, v188, v182
	v_fmac_f32_e32 v5, v188, v186
	v_mul_f32_e32 v188, v79, v155
	v_fmac_f32_e32 v6, v188, v159
	v_fmac_f32_e32 v7, v188, v163
	v_fmac_f32_e32 v8, v188, v167
	v_fmac_f32_e32 v9, v188, v171
	v_fmac_f32_e32 v10, v188, v175
	v_fmac_f32_e32 v11, v188, v179
	v_fmac_f32_e32 v4, v188, v183
	v_fmac_f32_e32 v5, v188, v187
	global_load_dword v56, v[2:3], off
	v_lshl_add_u64 v[2:3], v[2:3], 0, s[14:15]
	global_load_dword v57, v[2:3], off
	v_lshl_add_u64 v[2:3], v[2:3], 0, s[14:15]
	global_load_dword v58, v[2:3], off
	v_lshl_add_u64 v[2:3], v[2:3], 0, s[14:15]
	global_load_dword v59, v[2:3], off
	v_lshl_add_u64 v[2:3], v[2:3], 0, s[14:15]
	global_load_dword v68, v[2:3], off
	v_lshl_add_u64 v[2:3], v[2:3], 0, s[14:15]
	global_load_dword v69, v[2:3], off
	v_lshl_add_u64 v[2:3], v[2:3], 0, s[14:15]
	global_load_dword v70, v[2:3], off
	v_lshl_add_u64 v[2:3], v[2:3], 0, s[14:15]
	global_load_dword v71, v[2:3], off
	v_lshl_add_u64 v[2:3], v[2:3], 0, s[14:15]
	global_load_dword v72, v[2:3], off
	v_lshl_add_u64 v[2:3], v[2:3], 0, s[14:15]
	global_load_dword v73, v[2:3], off
	v_lshl_add_u64 v[2:3], v[2:3], 0, s[14:15]
	global_load_dword v74, v[2:3], off
	v_lshl_add_u64 v[2:3], v[2:3], 0, s[14:15]
	global_load_dword v75, v[2:3], off
	v_lshl_add_u64 v[2:3], v[2:3], 0, s[14:15]
	global_load_dword v76, v[2:3], off
	v_lshl_add_u64 v[2:3], v[2:3], 0, s[14:15]
	global_load_dword v77, v[2:3], off
	v_lshl_add_u64 v[2:3], v[2:3], 0, s[14:15]
	global_load_dword v78, v[2:3], off
	v_lshl_add_u64 v[2:3], v[2:3], 0, s[14:15]
	global_load_dword v79, v[2:3], off
	v_lshl_add_u64 v[2:3], v[2:3], 0, s[14:15]
	s_waitcnt vmcnt(32)
	ds_read_b128 v[152:155], v189 offset:4368
	ds_read_b128 v[156:159], v189 offset:272
	ds_read_b128 v[160:163], v189 offset:784
	ds_read_b128 v[164:167], v189 offset:1296
	ds_read_b128 v[168:171], v189 offset:1808
	ds_read_b128 v[172:175], v189 offset:2320
	ds_read_b128 v[176:179], v189 offset:2832
	ds_read_b128 v[180:183], v189 offset:3344
	ds_read_b128 v[184:187], v189 offset:3856
	s_waitcnt lgkmcnt(9)
	v_mul_f32_e32 v188, v80, v116
	v_fmac_f32_e32 v6, v188, v120
	v_fmac_f32_e32 v7, v188, v124
	v_fmac_f32_e32 v8, v188, v128
	v_fmac_f32_e32 v9, v188, v132
	v_fmac_f32_e32 v10, v188, v136
	v_fmac_f32_e32 v11, v188, v140
	v_fmac_f32_e32 v4, v188, v144
	v_fmac_f32_e32 v5, v188, v148
	v_mul_f32_e32 v188, v81, v117
	v_fmac_f32_e32 v6, v188, v121
	v_fmac_f32_e32 v7, v188, v125
	v_fmac_f32_e32 v8, v188, v129
	v_fmac_f32_e32 v9, v188, v133
	v_fmac_f32_e32 v10, v188, v137
	v_fmac_f32_e32 v11, v188, v141
	v_fmac_f32_e32 v4, v188, v145
	v_fmac_f32_e32 v5, v188, v149
	v_mul_f32_e32 v188, v82, v118
	v_fmac_f32_e32 v6, v188, v122
	v_fmac_f32_e32 v7, v188, v126
	v_fmac_f32_e32 v8, v188, v130
	v_fmac_f32_e32 v9, v188, v134
	v_fmac_f32_e32 v10, v188, v138
	v_fmac_f32_e32 v11, v188, v142
	v_fmac_f32_e32 v4, v188, v146
	v_fmac_f32_e32 v5, v188, v150
	v_mul_f32_e32 v188, v83, v119
	v_fmac_f32_e32 v6, v188, v123
	v_fmac_f32_e32 v7, v188, v127
	v_fmac_f32_e32 v8, v188, v131
	v_fmac_f32_e32 v9, v188, v135
	v_fmac_f32_e32 v10, v188, v139
	v_fmac_f32_e32 v11, v188, v143
	v_fmac_f32_e32 v4, v188, v147
	v_fmac_f32_e32 v5, v188, v151
	ds_read_b128 v[116:119], v189 offset:4384
	ds_read_b128 v[120:123], v189 offset:288
	ds_read_b128 v[124:127], v189 offset:800
	ds_read_b128 v[128:131], v189 offset:1312
	ds_read_b128 v[132:135], v189 offset:1824
	ds_read_b128 v[136:139], v189 offset:2336
	ds_read_b128 v[140:143], v189 offset:2848
	ds_read_b128 v[144:147], v189 offset:3360
	ds_read_b128 v[148:151], v189 offset:3872
	s_waitcnt lgkmcnt(9)
	v_mul_f32_e32 v188, v84, v152
	v_fmac_f32_e32 v6, v188, v156
	v_fmac_f32_e32 v7, v188, v160
	v_fmac_f32_e32 v8, v188, v164
	v_fmac_f32_e32 v9, v188, v168
	v_fmac_f32_e32 v10, v188, v172
	v_fmac_f32_e32 v11, v188, v176
	v_fmac_f32_e32 v4, v188, v180
	v_fmac_f32_e32 v5, v188, v184
	v_mul_f32_e32 v188, v85, v153
	v_fmac_f32_e32 v6, v188, v157
	v_fmac_f32_e32 v7, v188, v161
	v_fmac_f32_e32 v8, v188, v165
	v_fmac_f32_e32 v9, v188, v169
	v_fmac_f32_e32 v10, v188, v173
	v_fmac_f32_e32 v11, v188, v177
	v_fmac_f32_e32 v4, v188, v181
	v_fmac_f32_e32 v5, v188, v185
	v_mul_f32_e32 v188, v86, v154
	v_fmac_f32_e32 v6, v188, v158
	v_fmac_f32_e32 v7, v188, v162
	v_fmac_f32_e32 v8, v188, v166
	v_fmac_f32_e32 v9, v188, v170
	v_fmac_f32_e32 v10, v188, v174
	v_fmac_f32_e32 v11, v188, v178
	v_fmac_f32_e32 v4, v188, v182
	v_fmac_f32_e32 v5, v188, v186
	v_mul_f32_e32 v188, v87, v155
	v_fmac_f32_e32 v6, v188, v159
	v_fmac_f32_e32 v7, v188, v163
	v_fmac_f32_e32 v8, v188, v167
	v_fmac_f32_e32 v9, v188, v171
	v_fmac_f32_e32 v10, v188, v175
	v_fmac_f32_e32 v11, v188, v179
	v_fmac_f32_e32 v4, v188, v183
	v_fmac_f32_e32 v5, v188, v187
	ds_read_b128 v[152:155], v189 offset:4400
	ds_read_b128 v[156:159], v189 offset:304
	ds_read_b128 v[160:163], v189 offset:816
	ds_read_b128 v[164:167], v189 offset:1328
	ds_read_b128 v[168:171], v189 offset:1840
	ds_read_b128 v[172:175], v189 offset:2352
	ds_read_b128 v[176:179], v189 offset:2864
	ds_read_b128 v[180:183], v189 offset:3376
	ds_read_b128 v[184:187], v189 offset:3888
	s_waitcnt lgkmcnt(9)
; __device__ __forceinline__ void prep_hybrid(const float* w_in, const float* w_out, const float* pool_w, const float* pool_scale, bf16_t* WIN, bf16_t* WOUT, int gw, int NGW, LAS float* scr, int lane) {
;     ...
;         for (int d = 0; d < 128; ++d) {
;             const float wv = w_out[(size_t)(512 + g * 128 + d) * D + n] * pool_scale[g * 128 + d];
; #pragma unroll
;             for (int i = 0; i < 8; ++i) a[i] += pw[i * 128 + d] * wv;
;         }
	v_mul_f32_e32 v188, v92, v116
	v_fmac_f32_e32 v6, v188, v120
	v_fmac_f32_e32 v7, v188, v124
	v_fmac_f32_e32 v8, v188, v128
	v_fmac_f32_e32 v9, v188, v132
	v_fmac_f32_e32 v10, v188, v136
	v_fmac_f32_e32 v11, v188, v140
	v_fmac_f32_e32 v4, v188, v144
	v_fmac_f32_e32 v5, v188, v148
	v_mul_f32_e32 v188, v93, v117
	v_fmac_f32_e32 v6, v188, v121
	v_fmac_f32_e32 v7, v188, v125
	v_fmac_f32_e32 v8, v188, v129
	v_fmac_f32_e32 v9, v188, v133
	v_fmac_f32_e32 v10, v188, v137
	v_fmac_f32_e32 v11, v188, v141
	v_fmac_f32_e32 v4, v188, v145
	v_fmac_f32_e32 v5, v188, v149
	v_mul_f32_e32 v188, v94, v118
	v_fmac_f32_e32 v6, v188, v122
	v_fmac_f32_e32 v7, v188, v126
	v_fmac_f32_e32 v8, v188, v130
	v_fmac_f32_e32 v9, v188, v134
	v_fmac_f32_e32 v10, v188, v138
	v_fmac_f32_e32 v11, v188, v142
	v_fmac_f32_e32 v4, v188, v146
	v_fmac_f32_e32 v5, v188, v150
	v_mul_f32_e32 v188, v95, v119
	v_fmac_f32_e32 v6, v188, v123
	v_fmac_f32_e32 v7, v188, v127
	v_fmac_f32_e32 v8, v188, v131
	v_fmac_f32_e32 v9, v188, v135
	v_fmac_f32_e32 v10, v188, v139
	v_fmac_f32_e32 v11, v188, v143
	v_fmac_f32_e32 v4, v188, v147
	v_fmac_f32_e32 v5, v188, v151
	ds_read_b128 v[116:119], v189 offset:4416
	ds_read_b128 v[120:123], v189 offset:320
	ds_read_b128 v[124:127], v189 offset:832
	ds_read_b128 v[128:131], v189 offset:1344
	ds_read_b128 v[132:135], v189 offset:1856
	ds_read_b128 v[136:139], v189 offset:2368
	ds_read_b128 v[140:143], v189 offset:2880
	ds_read_b128 v[144:147], v189 offset:3392
	ds_read_b128 v[148:151], v189 offset:3904
	s_waitcnt lgkmcnt(9)
	v_mul_f32_e32 v188, v96, v152
	v_fmac_f32_e32 v6, v188, v156
	v_fmac_f32_e32 v7, v188, v160
	v_fmac_f32_e32 v8, v188, v164
	v_fmac_f32_e32 v9, v188, v168
	v_fmac_f32_e32 v10, v188, v172
	v_fmac_f32_e32 v11, v188, v176
	v_fmac_f32_e32 v4, v188, v180
	v_fmac_f32_e32 v5, v188, v184
	v_mul_f32_e32 v188, v97, v153
	v_fmac_f32_e32 v6, v188, v157
	v_fmac_f32_e32 v7, v188, v161
	v_fmac_f32_e32 v8, v188, v165
	v_fmac_f32_e32 v9, v188, v169
	v_fmac_f32_e32 v10, v188, v173
	v_fmac_f32_e32 v11, v188, v177
	v_fmac_f32_e32 v4, v188, v181
	v_fmac_f32_e32 v5, v188, v185
	v_mul_f32_e32 v188, v98, v154
	v_fmac_f32_e32 v6, v188, v158
	v_fmac_f32_e32 v7, v188, v162
	v_fmac_f32_e32 v8, v188, v166
	v_fmac_f32_e32 v9, v188, v170
	v_fmac_f32_e32 v10, v188, v174
	v_fmac_f32_e32 v11, v188, v178
	v_fmac_f32_e32 v4, v188, v182
	v_fmac_f32_e32 v5, v188, v186
	v_mul_f32_e32 v188, v99, v155
	v_fmac_f32_e32 v6, v188, v159
	v_fmac_f32_e32 v7, v188, v163
	v_fmac_f32_e32 v8, v188, v167
	v_fmac_f32_e32 v9, v188, v171
	v_fmac_f32_e32 v10, v188, v175
	v_fmac_f32_e32 v11, v188, v179
	v_fmac_f32_e32 v4, v188, v183
	v_fmac_f32_e32 v5, v188, v187
	global_load_dword v80, v[2:3], off
	v_lshl_add_u64 v[2:3], v[2:3], 0, s[14:15]
	global_load_dword v81, v[2:3], off
	v_lshl_add_u64 v[2:3], v[2:3], 0, s[14:15]
	global_load_dword v82, v[2:3], off
	v_lshl_add_u64 v[2:3], v[2:3], 0, s[14:15]
	global_load_dword v83, v[2:3], off
	v_lshl_add_u64 v[2:3], v[2:3], 0, s[14:15]
	global_load_dword v84, v[2:3], off
	v_lshl_add_u64 v[2:3], v[2:3], 0, s[14:15]
	global_load_dword v85, v[2:3], off
	v_lshl_add_u64 v[2:3], v[2:3], 0, s[14:15]
	global_load_dword v86, v[2:3], off
	v_lshl_add_u64 v[2:3], v[2:3], 0, s[14:15]
	global_load_dword v87, v[2:3], off
	v_lshl_add_u64 v[2:3], v[2:3], 0, s[14:15]
	global_load_dword v92, v[2:3], off
	v_lshl_add_u64 v[2:3], v[2:3], 0, s[14:15]
	global_load_dword v93, v[2:3], off
	v_lshl_add_u64 v[2:3], v[2:3], 0, s[14:15]
	global_load_dword v94, v[2:3], off
	v_lshl_add_u64 v[2:3], v[2:3], 0, s[14:15]
	global_load_dword v95, v[2:3], off
	v_lshl_add_u64 v[2:3], v[2:3], 0, s[14:15]
	global_load_dword v96, v[2:3], off
	v_lshl_add_u64 v[2:3], v[2:3], 0, s[14:15]
	global_load_dword v97, v[2:3], off
	v_lshl_add_u64 v[2:3], v[2:3], 0, s[14:15]
	global_load_dword v98, v[2:3], off
	v_lshl_add_u64 v[2:3], v[2:3], 0, s[14:15]
	global_load_dword v99, v[2:3], off
	v_lshl_add_u64 v[2:3], v[2:3], 0, s[14:15]
	s_waitcnt vmcnt(32)
	ds_read_b128 v[152:155], v189 offset:4432
	ds_read_b128 v[156:159], v189 offset:336
	ds_read_b128 v[160:163], v189 offset:848
	ds_read_b128 v[164:167], v189 offset:1360
	ds_read_b128 v[168:171], v189 offset:1872
	ds_read_b128 v[172:175], v189 offset:2384
	ds_read_b128 v[176:179], v189 offset:2896
	ds_read_b128 v[180:183], v189 offset:3408
	ds_read_b128 v[184:187], v189 offset:3920
	s_waitcnt lgkmcnt(9)
	v_mul_f32_e32 v188, v100, v116
	v_fmac_f32_e32 v6, v188, v120
	v_fmac_f32_e32 v7, v188, v124
	v_fmac_f32_e32 v8, v188, v128
	v_fmac_f32_e32 v9, v188, v132
	v_fmac_f32_e32 v10, v188, v136
	v_fmac_f32_e32 v11, v188, v140
	v_fmac_f32_e32 v4, v188, v144
	v_fmac_f32_e32 v5, v188, v148
	v_mul_f32_e32 v188, v101, v117
	v_fmac_f32_e32 v6, v188, v121
	v_fmac_f32_e32 v7, v188, v125
	v_fmac_f32_e32 v8, v188, v129
	v_fmac_f32_e32 v9, v188, v133
	v_fmac_f32_e32 v10, v188, v137
	v_fmac_f32_e32 v11, v188, v141
	v_fmac_f32_e32 v4, v188, v145
	v_fmac_f32_e32 v5, v188, v149
	v_mul_f32_e32 v188, v102, v118
	v_fmac_f32_e32 v6, v188, v122
	v_fmac_f32_e32 v7, v188, v126
	v_fmac_f32_e32 v8, v188, v130
	v_fmac_f32_e32 v9, v188, v134
	v_fmac_f32_e32 v10, v188, v138
	v_fmac_f32_e32 v11, v188, v142
	v_fmac_f32_e32 v4, v188, v146
	v_fmac_f32_e32 v5, v188, v150
	v_mul_f32_e32 v188, v103, v119
	v_fmac_f32_e32 v6, v188, v123
	v_fmac_f32_e32 v7, v188, v127
	v_fmac_f32_e32 v8, v188, v131
	v_fmac_f32_e32 v9, v188, v135
	v_fmac_f32_e32 v10, v188, v139
	v_fmac_f32_e32 v11, v188, v143
	v_fmac_f32_e32 v4, v188, v147
	v_fmac_f32_e32 v5, v188, v151
	ds_read_b128 v[116:119], v189 offset:4448
	ds_read_b128 v[120:123], v189 offset:352
	ds_read_b128 v[124:127], v189 offset:864
	ds_read_b128 v[128:131], v189 offset:1376
	ds_read_b128 v[132:135], v189 offset:1888
	ds_read_b128 v[136:139], v189 offset:2400
	ds_read_b128 v[140:143], v189 offset:2912
	ds_read_b128 v[144:147], v189 offset:3424
	ds_read_b128 v[148:151], v189 offset:3936
	s_waitcnt lgkmcnt(9)
; __device__ __forceinline__ void prep_hybrid(const float* w_in, const float* w_out, const float* pool_w, const float* pool_scale, bf16_t* WIN, bf16_t* WOUT, int gw, int NGW, LAS float* scr, int lane) {
;     ...
;         for (int d = 0; d < 128; ++d) {
;             const float wv = w_out[(size_t)(512 + g * 128 + d) * D + n] * pool_scale[g * 128 + d];
; #pragma unroll
;             for (int i = 0; i < 8; ++i) a[i] += pw[i * 128 + d] * wv;
;         }
	v_mul_f32_e32 v188, v104, v152
	v_fmac_f32_e32 v6, v188, v156
	v_fmac_f32_e32 v7, v188, v160
	v_fmac_f32_e32 v8, v188, v164
	v_fmac_f32_e32 v9, v188, v168
	v_fmac_f32_e32 v10, v188, v172
	v_fmac_f32_e32 v11, v188, v176
	v_fmac_f32_e32 v4, v188, v180
	v_fmac_f32_e32 v5, v188, v184
	v_mul_f32_e32 v188, v105, v153
	v_fmac_f32_e32 v6, v188, v157
	v_fmac_f32_e32 v7, v188, v161
	v_fmac_f32_e32 v8, v188, v165
	v_fmac_f32_e32 v9, v188, v169
	v_fmac_f32_e32 v10, v188, v173
	v_fmac_f32_e32 v11, v188, v177
	v_fmac_f32_e32 v4, v188, v181
	v_fmac_f32_e32 v5, v188, v185
	v_mul_f32_e32 v188, v106, v154
	v_fmac_f32_e32 v6, v188, v158
	v_fmac_f32_e32 v7, v188, v162
	v_fmac_f32_e32 v8, v188, v166
	v_fmac_f32_e32 v9, v188, v170
	v_fmac_f32_e32 v10, v188, v174
	v_fmac_f32_e32 v11, v188, v178
	v_fmac_f32_e32 v4, v188, v182
	v_fmac_f32_e32 v5, v188, v186
	v_mul_f32_e32 v188, v107, v155
	v_fmac_f32_e32 v6, v188, v159
	v_fmac_f32_e32 v7, v188, v163
	v_fmac_f32_e32 v8, v188, v167
	v_fmac_f32_e32 v9, v188, v171
	v_fmac_f32_e32 v10, v188, v175
	v_fmac_f32_e32 v11, v188, v179
	v_fmac_f32_e32 v4, v188, v183
	v_fmac_f32_e32 v5, v188, v187
	ds_read_b128 v[152:155], v189 offset:4464
	ds_read_b128 v[156:159], v189 offset:368
	ds_read_b128 v[160:163], v189 offset:880
	ds_read_b128 v[164:167], v189 offset:1392
	ds_read_b128 v[168:171], v189 offset:1904
	ds_read_b128 v[172:175], v189 offset:2416
	ds_read_b128 v[176:179], v189 offset:2928
	ds_read_b128 v[180:183], v189 offset:3440
	ds_read_b128 v[184:187], v189 offset:3952
	s_waitcnt lgkmcnt(9)
	v_mul_f32_e32 v188, v108, v116
	v_fmac_f32_e32 v6, v188, v120
	v_fmac_f32_e32 v7, v188, v124
	v_fmac_f32_e32 v8, v188, v128
	v_fmac_f32_e32 v9, v188, v132
	v_fmac_f32_e32 v10, v188, v136
	v_fmac_f32_e32 v11, v188, v140
	v_fmac_f32_e32 v4, v188, v144
	v_fmac_f32_e32 v5, v188, v148
	v_mul_f32_e32 v188, v109, v117
	v_fmac_f32_e32 v6, v188, v121
	v_fmac_f32_e32 v7, v188, v125
	v_fmac_f32_e32 v8, v188, v129
	v_fmac_f32_e32 v9, v188, v133
	v_fmac_f32_e32 v10, v188, v137
	v_fmac_f32_e32 v11, v188, v141
	v_fmac_f32_e32 v4, v188, v145
	v_fmac_f32_e32 v5, v188, v149
	v_mul_f32_e32 v188, v110, v118
	v_fmac_f32_e32 v6, v188, v122
	v_fmac_f32_e32 v7, v188, v126
	v_fmac_f32_e32 v8, v188, v130
	v_fmac_f32_e32 v9, v188, v134
	v_fmac_f32_e32 v10, v188, v138
	v_fmac_f32_e32 v11, v188, v142
	v_fmac_f32_e32 v4, v188, v146
	v_fmac_f32_e32 v5, v188, v150
	v_mul_f32_e32 v188, v111, v119
	v_fmac_f32_e32 v6, v188, v123
	v_fmac_f32_e32 v7, v188, v127
	v_fmac_f32_e32 v8, v188, v131
	v_fmac_f32_e32 v9, v188, v135
	v_fmac_f32_e32 v10, v188, v139
	v_fmac_f32_e32 v11, v188, v143
	v_fmac_f32_e32 v4, v188, v147
	v_fmac_f32_e32 v5, v188, v151
	ds_read_b128 v[116:119], v189 offset:4480
	ds_read_b128 v[120:123], v189 offset:384
	ds_read_b128 v[124:127], v189 offset:896
	ds_read_b128 v[128:131], v189 offset:1408
	ds_read_b128 v[132:135], v189 offset:1920
	ds_read_b128 v[136:139], v189 offset:2432
	ds_read_b128 v[140:143], v189 offset:2944
	ds_read_b128 v[144:147], v189 offset:3456
	ds_read_b128 v[148:151], v189 offset:3968
	s_waitcnt lgkmcnt(9)
	v_mul_f32_e32 v188, v112, v152
	v_fmac_f32_e32 v6, v188, v156
	v_fmac_f32_e32 v7, v188, v160
	v_fmac_f32_e32 v8, v188, v164
	v_fmac_f32_e32 v9, v188, v168
	v_fmac_f32_e32 v10, v188, v172
	v_fmac_f32_e32 v11, v188, v176
	v_fmac_f32_e32 v4, v188, v180
	v_fmac_f32_e32 v5, v188, v184
	v_mul_f32_e32 v188, v113, v153
	v_fmac_f32_e32 v6, v188, v157
	v_fmac_f32_e32 v7, v188, v161
	v_fmac_f32_e32 v8, v188, v165
	v_fmac_f32_e32 v9, v188, v169
	v_fmac_f32_e32 v10, v188, v173
	v_fmac_f32_e32 v11, v188, v177
	v_fmac_f32_e32 v4, v188, v181
	v_fmac_f32_e32 v5, v188, v185
	v_mul_f32_e32 v188, v114, v154
	v_fmac_f32_e32 v6, v188, v158
	v_fmac_f32_e32 v7, v188, v162
	v_fmac_f32_e32 v8, v188, v166
	v_fmac_f32_e32 v9, v188, v170
	v_fmac_f32_e32 v10, v188, v174
	v_fmac_f32_e32 v11, v188, v178
	v_fmac_f32_e32 v4, v188, v182
	v_fmac_f32_e32 v5, v188, v186
	v_mul_f32_e32 v188, v115, v155
	v_fmac_f32_e32 v6, v188, v159
	v_fmac_f32_e32 v7, v188, v163
	v_fmac_f32_e32 v8, v188, v167
	v_fmac_f32_e32 v9, v188, v171
	v_fmac_f32_e32 v10, v188, v175
	v_fmac_f32_e32 v11, v188, v179
	v_fmac_f32_e32 v4, v188, v183
	v_fmac_f32_e32 v5, v188, v187
	s_waitcnt vmcnt(16)
	ds_read_b128 v[152:155], v189 offset:4496
	ds_read_b128 v[156:159], v189 offset:400
	ds_read_b128 v[160:163], v189 offset:912
	ds_read_b128 v[164:167], v189 offset:1424
	ds_read_b128 v[168:171], v189 offset:1936
	ds_read_b128 v[172:175], v189 offset:2448
	ds_read_b128 v[176:179], v189 offset:2960
	ds_read_b128 v[180:183], v189 offset:3472
	ds_read_b128 v[184:187], v189 offset:3984
	s_waitcnt lgkmcnt(9)
	v_mul_f32_e32 v188, v56, v116
	v_fmac_f32_e32 v6, v188, v120
	v_fmac_f32_e32 v7, v188, v124
	v_fmac_f32_e32 v8, v188, v128
	v_fmac_f32_e32 v9, v188, v132
	v_fmac_f32_e32 v10, v188, v136
	v_fmac_f32_e32 v11, v188, v140
	v_fmac_f32_e32 v4, v188, v144
	v_fmac_f32_e32 v5, v188, v148
	v_mul_f32_e32 v188, v57, v117
	v_fmac_f32_e32 v6, v188, v121
	v_fmac_f32_e32 v7, v188, v125
	v_fmac_f32_e32 v8, v188, v129
	v_fmac_f32_e32 v9, v188, v133
	v_fmac_f32_e32 v10, v188, v137
	v_fmac_f32_e32 v11, v188, v141
	v_fmac_f32_e32 v4, v188, v145
	v_fmac_f32_e32 v5, v188, v149
	v_mul_f32_e32 v188, v58, v118
	v_fmac_f32_e32 v6, v188, v122
	v_fmac_f32_e32 v7, v188, v126
	v_fmac_f32_e32 v8, v188, v130
	v_fmac_f32_e32 v9, v188, v134
	v_fmac_f32_e32 v10, v188, v138
	v_fmac_f32_e32 v11, v188, v142
	v_fmac_f32_e32 v4, v188, v146
	v_fmac_f32_e32 v5, v188, v150
	v_mul_f32_e32 v188, v59, v119
	v_fmac_f32_e32 v6, v188, v123
	v_fmac_f32_e32 v7, v188, v127
	v_fmac_f32_e32 v8, v188, v131
	v_fmac_f32_e32 v9, v188, v135
	v_fmac_f32_e32 v10, v188, v139
	v_fmac_f32_e32 v11, v188, v143
	v_fmac_f32_e32 v4, v188, v147
	v_fmac_f32_e32 v5, v188, v151
	ds_read_b128 v[116:119], v189 offset:4512
	ds_read_b128 v[120:123], v189 offset:416
	ds_read_b128 v[124:127], v189 offset:928
	ds_read_b128 v[128:131], v189 offset:1440
	ds_read_b128 v[132:135], v189 offset:1952
	ds_read_b128 v[136:139], v189 offset:2464
	ds_read_b128 v[140:143], v189 offset:2976
	ds_read_b128 v[144:147], v189 offset:3488
	ds_read_b128 v[148:151], v189 offset:4000
	s_waitcnt lgkmcnt(9)
; __device__ __forceinline__ void prep_hybrid(const float* w_in, const float* w_out, const float* pool_w, const float* pool_scale, bf16_t* WIN, bf16_t* WOUT, int gw, int NGW, LAS float* scr, int lane) {
;     ...
;         for (int d = 0; d < 128; ++d) {
;             const float wv = w_out[(size_t)(512 + g * 128 + d) * D + n] * pool_scale[g * 128 + d];
; #pragma unroll
;             for (int i = 0; i < 8; ++i) a[i] += pw[i * 128 + d] * wv;
;         }
	v_mul_f32_e32 v188, v68, v152
	v_fmac_f32_e32 v6, v188, v156
	v_fmac_f32_e32 v7, v188, v160
	v_fmac_f32_e32 v8, v188, v164
	v_fmac_f32_e32 v9, v188, v168
	v_fmac_f32_e32 v10, v188, v172
	v_fmac_f32_e32 v11, v188, v176
	v_fmac_f32_e32 v4, v188, v180
	v_fmac_f32_e32 v5, v188, v184
	v_mul_f32_e32 v188, v69, v153
	v_fmac_f32_e32 v6, v188, v157
	v_fmac_f32_e32 v7, v188, v161
	v_fmac_f32_e32 v8, v188, v165
	v_fmac_f32_e32 v9, v188, v169
	v_fmac_f32_e32 v10, v188, v173
	v_fmac_f32_e32 v11, v188, v177
	v_fmac_f32_e32 v4, v188, v181
	v_fmac_f32_e32 v5, v188, v185
	v_mul_f32_e32 v188, v70, v154
	v_fmac_f32_e32 v6, v188, v158
	v_fmac_f32_e32 v7, v188, v162
	v_fmac_f32_e32 v8, v188, v166
	v_fmac_f32_e32 v9, v188, v170
	v_fmac_f32_e32 v10, v188, v174
	v_fmac_f32_e32 v11, v188, v178
	v_fmac_f32_e32 v4, v188, v182
	v_fmac_f32_e32 v5, v188, v186
	v_mul_f32_e32 v188, v71, v155
	v_fmac_f32_e32 v6, v188, v159
	v_fmac_f32_e32 v7, v188, v163
	v_fmac_f32_e32 v8, v188, v167
	v_fmac_f32_e32 v9, v188, v171
	v_fmac_f32_e32 v10, v188, v175
	v_fmac_f32_e32 v11, v188, v179
	v_fmac_f32_e32 v4, v188, v183
	v_fmac_f32_e32 v5, v188, v187
	ds_read_b128 v[152:155], v189 offset:4528
	ds_read_b128 v[156:159], v189 offset:432
	ds_read_b128 v[160:163], v189 offset:944
	ds_read_b128 v[164:167], v189 offset:1456
	ds_read_b128 v[168:171], v189 offset:1968
	ds_read_b128 v[172:175], v189 offset:2480
	ds_read_b128 v[176:179], v189 offset:2992
	ds_read_b128 v[180:183], v189 offset:3504
	ds_read_b128 v[184:187], v189 offset:4016
	s_waitcnt lgkmcnt(9)
	v_mul_f32_e32 v188, v72, v116
	v_fmac_f32_e32 v6, v188, v120
	v_fmac_f32_e32 v7, v188, v124
	v_fmac_f32_e32 v8, v188, v128
	v_fmac_f32_e32 v9, v188, v132
	v_fmac_f32_e32 v10, v188, v136
	v_fmac_f32_e32 v11, v188, v140
	v_fmac_f32_e32 v4, v188, v144
	v_fmac_f32_e32 v5, v188, v148
	v_mul_f32_e32 v188, v73, v117
	v_fmac_f32_e32 v6, v188, v121
	v_fmac_f32_e32 v7, v188, v125
	v_fmac_f32_e32 v8, v188, v129
	v_fmac_f32_e32 v9, v188, v133
	v_fmac_f32_e32 v10, v188, v137
	v_fmac_f32_e32 v11, v188, v141
	v_fmac_f32_e32 v4, v188, v145
	v_fmac_f32_e32 v5, v188, v149
	v_mul_f32_e32 v188, v74, v118
	v_fmac_f32_e32 v6, v188, v122
	v_fmac_f32_e32 v7, v188, v126
	v_fmac_f32_e32 v8, v188, v130
	v_fmac_f32_e32 v9, v188, v134
	v_fmac_f32_e32 v10, v188, v138
	v_fmac_f32_e32 v11, v188, v142
	v_fmac_f32_e32 v4, v188, v146
	v_fmac_f32_e32 v5, v188, v150
	v_mul_f32_e32 v188, v75, v119
	v_fmac_f32_e32 v6, v188, v123
	v_fmac_f32_e32 v7, v188, v127
	v_fmac_f32_e32 v8, v188, v131
	v_fmac_f32_e32 v9, v188, v135
	v_fmac_f32_e32 v10, v188, v139
	v_fmac_f32_e32 v11, v188, v143
	v_fmac_f32_e32 v4, v188, v147
	v_fmac_f32_e32 v5, v188, v151
	ds_read_b128 v[116:119], v189 offset:4544
	ds_read_b128 v[120:123], v189 offset:448
	ds_read_b128 v[124:127], v189 offset:960
	ds_read_b128 v[128:131], v189 offset:1472
	ds_read_b128 v[132:135], v189 offset:1984
	ds_read_b128 v[136:139], v189 offset:2496
	ds_read_b128 v[140:143], v189 offset:3008
	ds_read_b128 v[144:147], v189 offset:3520
	ds_read_b128 v[148:151], v189 offset:4032
	s_waitcnt lgkmcnt(9)
	v_mul_f32_e32 v188, v76, v152
	v_fmac_f32_e32 v6, v188, v156
	v_fmac_f32_e32 v7, v188, v160
	v_fmac_f32_e32 v8, v188, v164
	v_fmac_f32_e32 v9, v188, v168
	v_fmac_f32_e32 v10, v188, v172
	v_fmac_f32_e32 v11, v188, v176
	v_fmac_f32_e32 v4, v188, v180
	v_fmac_f32_e32 v5, v188, v184
	v_mul_f32_e32 v188, v77, v153
	v_fmac_f32_e32 v6, v188, v157
	v_fmac_f32_e32 v7, v188, v161
	v_fmac_f32_e32 v8, v188, v165
	v_fmac_f32_e32 v9, v188, v169
	v_fmac_f32_e32 v10, v188, v173
	v_fmac_f32_e32 v11, v188, v177
	v_fmac_f32_e32 v4, v188, v181
	v_fmac_f32_e32 v5, v188, v185
	v_mul_f32_e32 v188, v78, v154
	v_fmac_f32_e32 v6, v188, v158
	v_fmac_f32_e32 v7, v188, v162
	v_fmac_f32_e32 v8, v188, v166
	v_fmac_f32_e32 v9, v188, v170
	v_fmac_f32_e32 v10, v188, v174
	v_fmac_f32_e32 v11, v188, v178
	v_fmac_f32_e32 v4, v188, v182
	v_fmac_f32_e32 v5, v188, v186
	v_mul_f32_e32 v188, v79, v155
	v_fmac_f32_e32 v6, v188, v159
	v_fmac_f32_e32 v7, v188, v163
	v_fmac_f32_e32 v8, v188, v167
	v_fmac_f32_e32 v9, v188, v171
	v_fmac_f32_e32 v10, v188, v175
	v_fmac_f32_e32 v11, v188, v179
	v_fmac_f32_e32 v4, v188, v183
	v_fmac_f32_e32 v5, v188, v187
	s_waitcnt vmcnt(0)
	ds_read_b128 v[152:155], v189 offset:4560
	ds_read_b128 v[156:159], v189 offset:464
	ds_read_b128 v[160:163], v189 offset:976
	ds_read_b128 v[164:167], v189 offset:1488
	ds_read_b128 v[168:171], v189 offset:2000
	ds_read_b128 v[172:175], v189 offset:2512
	ds_read_b128 v[176:179], v189 offset:3024
	ds_read_b128 v[180:183], v189 offset:3536
	ds_read_b128 v[184:187], v189 offset:4048
	s_waitcnt lgkmcnt(9)
; #define GAS __attribute__((address_space(1)))
; __device__ __forceinline__ unsigned cvt_pk_bf16(float lo, float hi) { const f32x2 v = {lo, hi}; return __builtin_bit_cast(unsigned, __builtin_convertvector(v, b16x2_t)); }
; __device__ __forceinline__ void prep_hybrid(const float* w_in, const float* w_out, const float* pool_w, const float* pool_scale, bf16_t* WIN, bf16_t* WOUT, int gw, int NGW, LAS float* scr, int lane) {
;     ...
;         for (int d = 0; d < 128; ++d) {
;             const float wv = w_out[(size_t)(512 + g * 128 + d) * D + n] * pool_scale[g * 128 + d];
; #pragma unroll
;             for (int i = 0; i < 8; ++i) a[i] += pw[i * 128 + d] * wv;
;         }
;         u32x4 o; o.x = cvt_pk_bf16(a[0], a[1]); o.y = cvt_pk_bf16(a[2], a[3]); o.z = cvt_pk_bf16(a[4], a[5]); o.w = cvt_pk_bf16(a[6], a[7]);
;         *(GAS u32x4*)(WOUT + (size_t)n * D + 512 + g * 128 + c8 * 8) = o;
	v_mul_f32_e32 v188, v80, v116
	v_fmac_f32_e32 v6, v188, v120
	v_fmac_f32_e32 v7, v188, v124
	v_fmac_f32_e32 v8, v188, v128
	v_fmac_f32_e32 v9, v188, v132
	v_fmac_f32_e32 v10, v188, v136
	v_fmac_f32_e32 v11, v188, v140
	v_fmac_f32_e32 v4, v188, v144
	v_fmac_f32_e32 v5, v188, v148
	v_mul_f32_e32 v188, v81, v117
	v_fmac_f32_e32 v6, v188, v121
	v_fmac_f32_e32 v7, v188, v125
	v_fmac_f32_e32 v8, v188, v129
	v_fmac_f32_e32 v9, v188, v133
	v_fmac_f32_e32 v10, v188, v137
	v_fmac_f32_e32 v11, v188, v141
	v_fmac_f32_e32 v4, v188, v145
	v_fmac_f32_e32 v5, v188, v149
	v_mul_f32_e32 v188, v82, v118
	v_fmac_f32_e32 v6, v188, v122
	v_fmac_f32_e32 v7, v188, v126
	v_fmac_f32_e32 v8, v188, v130
	v_fmac_f32_e32 v9, v188, v134
	v_fmac_f32_e32 v10, v188, v138
	v_fmac_f32_e32 v11, v188, v142
	v_fmac_f32_e32 v4, v188, v146
	v_fmac_f32_e32 v5, v188, v150
	v_mul_f32_e32 v188, v83, v119
	v_fmac_f32_e32 v6, v188, v123
	v_fmac_f32_e32 v7, v188, v127
	v_fmac_f32_e32 v8, v188, v131
	v_fmac_f32_e32 v9, v188, v135
	v_fmac_f32_e32 v10, v188, v139
	v_fmac_f32_e32 v11, v188, v143
	v_fmac_f32_e32 v4, v188, v147
	v_fmac_f32_e32 v5, v188, v151
	ds_read_b128 v[116:119], v189 offset:4576
	ds_read_b128 v[120:123], v189 offset:480
	ds_read_b128 v[124:127], v189 offset:992
	ds_read_b128 v[128:131], v189 offset:1504
	ds_read_b128 v[132:135], v189 offset:2016
	ds_read_b128 v[136:139], v189 offset:2528
	ds_read_b128 v[140:143], v189 offset:3040
	ds_read_b128 v[144:147], v189 offset:3552
	ds_read_b128 v[148:151], v189 offset:4064
	s_waitcnt lgkmcnt(9)
	v_mul_f32_e32 v188, v84, v152
	v_fmac_f32_e32 v6, v188, v156
	v_fmac_f32_e32 v7, v188, v160
	v_fmac_f32_e32 v8, v188, v164
	v_fmac_f32_e32 v9, v188, v168
	v_fmac_f32_e32 v10, v188, v172
	v_fmac_f32_e32 v11, v188, v176
	v_fmac_f32_e32 v4, v188, v180
	v_fmac_f32_e32 v5, v188, v184
	v_mul_f32_e32 v188, v85, v153
	v_fmac_f32_e32 v6, v188, v157
	v_fmac_f32_e32 v7, v188, v161
	v_fmac_f32_e32 v8, v188, v165
	v_fmac_f32_e32 v9, v188, v169
	v_fmac_f32_e32 v10, v188, v173
	v_fmac_f32_e32 v11, v188, v177
	v_fmac_f32_e32 v4, v188, v181
	v_fmac_f32_e32 v5, v188, v185
	v_mul_f32_e32 v188, v86, v154
	v_fmac_f32_e32 v6, v188, v158
	v_fmac_f32_e32 v7, v188, v162
	v_fmac_f32_e32 v8, v188, v166
	v_fmac_f32_e32 v9, v188, v170
	v_fmac_f32_e32 v10, v188, v174
	v_fmac_f32_e32 v11, v188, v178
	v_fmac_f32_e32 v4, v188, v182
	v_fmac_f32_e32 v5, v188, v186
	v_mul_f32_e32 v188, v87, v155
	v_fmac_f32_e32 v6, v188, v159
	v_fmac_f32_e32 v7, v188, v163
	v_fmac_f32_e32 v8, v188, v167
	v_fmac_f32_e32 v9, v188, v171
	v_fmac_f32_e32 v10, v188, v175
	v_fmac_f32_e32 v11, v188, v179
	v_fmac_f32_e32 v4, v188, v183
	v_fmac_f32_e32 v5, v188, v187
	ds_read_b128 v[152:155], v189 offset:4592
	ds_read_b128 v[156:159], v189 offset:496
	ds_read_b128 v[160:163], v189 offset:1008
	ds_read_b128 v[164:167], v189 offset:1520
	ds_read_b128 v[168:171], v189 offset:2032
	ds_read_b128 v[172:175], v189 offset:2544
	ds_read_b128 v[176:179], v189 offset:3056
	ds_read_b128 v[180:183], v189 offset:3568
	ds_read_b128 v[184:187], v189 offset:4080
	s_waitcnt lgkmcnt(9)
	v_mul_f32_e32 v188, v92, v116
	v_fmac_f32_e32 v6, v188, v120
	v_fmac_f32_e32 v7, v188, v124
	v_fmac_f32_e32 v8, v188, v128
	v_fmac_f32_e32 v9, v188, v132
	v_fmac_f32_e32 v10, v188, v136
	v_fmac_f32_e32 v11, v188, v140
	v_fmac_f32_e32 v4, v188, v144
	v_fmac_f32_e32 v5, v188, v148
	v_mul_f32_e32 v188, v93, v117
	v_fmac_f32_e32 v6, v188, v121
	v_fmac_f32_e32 v7, v188, v125
	v_fmac_f32_e32 v8, v188, v129
	v_fmac_f32_e32 v9, v188, v133
	v_fmac_f32_e32 v10, v188, v137
	v_fmac_f32_e32 v11, v188, v141
	v_fmac_f32_e32 v4, v188, v145
	v_fmac_f32_e32 v5, v188, v149
	v_mul_f32_e32 v188, v94, v118
	v_fmac_f32_e32 v6, v188, v122
	v_fmac_f32_e32 v7, v188, v126
	v_fmac_f32_e32 v8, v188, v130
	v_fmac_f32_e32 v9, v188, v134
	v_fmac_f32_e32 v10, v188, v138
	v_fmac_f32_e32 v11, v188, v142
	v_fmac_f32_e32 v4, v188, v146
	v_fmac_f32_e32 v5, v188, v150
	v_mul_f32_e32 v188, v95, v119
	v_fmac_f32_e32 v6, v188, v123
	v_fmac_f32_e32 v7, v188, v127
	v_fmac_f32_e32 v8, v188, v131
	v_fmac_f32_e32 v9, v188, v135
	v_fmac_f32_e32 v10, v188, v139
	v_fmac_f32_e32 v11, v188, v143
	v_fmac_f32_e32 v4, v188, v147
	v_fmac_f32_e32 v5, v188, v151
	s_waitcnt lgkmcnt(0)
	v_mul_f32_e32 v188, v96, v152
	v_fmac_f32_e32 v6, v188, v156
	v_fmac_f32_e32 v7, v188, v160
	v_fmac_f32_e32 v8, v188, v164
	v_fmac_f32_e32 v9, v188, v168
	v_fmac_f32_e32 v10, v188, v172
	v_fmac_f32_e32 v11, v188, v176
	v_fmac_f32_e32 v4, v188, v180
	v_fmac_f32_e32 v5, v188, v184
	v_mul_f32_e32 v188, v97, v153
	v_fmac_f32_e32 v6, v188, v157
	v_fmac_f32_e32 v7, v188, v161
	v_fmac_f32_e32 v8, v188, v165
	v_fmac_f32_e32 v9, v188, v169
	v_fmac_f32_e32 v10, v188, v173
	v_fmac_f32_e32 v11, v188, v177
	v_fmac_f32_e32 v4, v188, v181
	v_fmac_f32_e32 v5, v188, v185
	v_mul_f32_e32 v188, v98, v154
	v_fmac_f32_e32 v6, v188, v158
	v_fmac_f32_e32 v7, v188, v162
	v_fmac_f32_e32 v8, v188, v166
	v_fmac_f32_e32 v9, v188, v170
	v_fmac_f32_e32 v10, v188, v174
	v_fmac_f32_e32 v11, v188, v178
	v_fmac_f32_e32 v4, v188, v182
	v_fmac_f32_e32 v5, v188, v186
	v_mul_f32_e32 v188, v99, v155
	v_fmac_f32_e32 v6, v188, v159
	v_fmac_f32_e32 v7, v188, v163
	v_fmac_f32_e32 v8, v188, v167
	v_fmac_f32_e32 v9, v188, v171
	v_fmac_f32_e32 v10, v188, v175
	v_fmac_f32_e32 v11, v188, v179
	v_fmac_f32_e32 v4, v188, v183
	v_fmac_f32_e32 v5, v188, v187
	s_lshl_b32 s2, s25, 6
	s_and_b32 s2, s2, 0x3c0
	v_add_u32_e32 v2, s2, v16
	v_ashrrev_i32_e32 v3, 31, v2
	v_lshlrev_b64 v[2:3], 11, v[2:3]
	v_lshl_add_u64 v[2:3], s[4:5], 0, v[2:3]
	v_lshl_add_u64 v[2:3], s[10:11], 1, v[2:3]
	s_and_b32 s8, s25, 0xf0
	s_add_i32 s25, s25, s18
	s_add_i32 s26, s26, s27
	v_cvt_pk_bf16_f32 v6, v6, v7
	v_cvt_pk_bf16_f32 v7, v8, v9
	v_cvt_pk_bf16_f32 v8, v10, v11
	v_cvt_pk_bf16_f32 v9, v4, v5
	v_lshl_add_u64 v[2:3], v[2:3], 0, s[8:9]
	s_cmpk_gt_i32 s25, 0x3ff
	global_store_dwordx4 v[2:3], v[6:9], off offset:1024
	s_cbranch_scc0 .LBB0_44

; __device__ __forceinline__ void prep_hybrid(const float* w_in, const float* w_out, const float* pool_w, const float* pool_scale, bf16_t* WIN, bf16_t* WOUT, int gw, int NGW, LAS float* scr, int lane) {
;     ...
;     for (int it = gw; it < 1024; it += NGW) {
;         const int g = it >> 8, c8 = (it >> 4) & 15, n = (it & 15) * 64 + lane;
;         float a[8];
; #pragma unroll
;         for (int i = 0; i < 8; ++i) a[i] = 0.f;
;         const float* pw = pool_w + ((size_t)g * 128 + c8 * 8) * 128;
; #pragma unroll 4
;         for (int d = 0; d < 128; ++d) {
;             const float wv = w_out[(size_t)(512 + g * 128 + d) * D + n] * pool_scale[g * 128 + d];
; #pragma unroll
;             for (int i = 0; i < 8; ++i) a[i] += pw[i * 128 + d] * wv;
.LBB0_1677:
	s_mov_b32 s2, s31
	s_mov_b32 s3, s34
	s_add_u32 s2, s2, s27
	s_addc_u32 s3, s3, 0
	s_mov_b32 s38, s6
	s_mov_b32 s39, s30
	s_add_u32 s38, s38, 2048
	s_addc_u32 s39, s39, 0
	v_mbcnt_hi_u32_b32 v186, -1, v254
	v_and_b32_e32 v187, 31, v186
	v_lshlrev_b32_e32 v186, 4, v186
	v_lshlrev_b32_e32 v187, 4, v187
	global_load_dwordx4 v[112:115], v186, s[2:3]
	global_load_dwordx4 v[116:119], v186, s[2:3] offset:1024
	global_load_dwordx4 v[120:123], v186, s[2:3] offset:2048
	global_load_dwordx4 v[124:127], v186, s[2:3] offset:3072
	global_load_dwordx4 v[128:131], v187, s[38:39]
	v_add_co_u32_e32 v2, vcc, 0xffffd000, v2
	s_nop 1
	v_addc_co_u32_e32 v3, vcc, -1, v3, vcc
	s_mov_b32 s14, 0x1000
	s_mov_b32 s15, 0
	global_load_dword v56, v[2:3], off
	v_lshl_add_u64 v[2:3], v[2:3], 0, s[14:15]
	global_load_dword v57, v[2:3], off
	v_lshl_add_u64 v[2:3], v[2:3], 0, s[14:15]
	global_load_dword v58, v[2:3], off
	v_lshl_add_u64 v[2:3], v[2:3], 0, s[14:15]
	global_load_dword v59, v[2:3], off
	v_lshl_add_u64 v[2:3], v[2:3], 0, s[14:15]
	global_load_dword v60, v[2:3], off
	v_lshl_add_u64 v[2:3], v[2:3], 0, s[14:15]
	global_load_dword v61, v[2:3], off
	v_lshl_add_u64 v[2:3], v[2:3], 0, s[14:15]
	global_load_dword v62, v[2:3], off
	v_lshl_add_u64 v[2:3], v[2:3], 0, s[14:15]
	global_load_dword v63, v[2:3], off
	v_lshl_add_u64 v[2:3], v[2:3], 0, s[14:15]
	global_load_dword v64, v[2:3], off
	v_lshl_add_u64 v[2:3], v[2:3], 0, s[14:15]
	global_load_dword v65, v[2:3], off
	v_lshl_add_u64 v[2:3], v[2:3], 0, s[14:15]
	global_load_dword v66, v[2:3], off
	v_lshl_add_u64 v[2:3], v[2:3], 0, s[14:15]
	global_load_dword v67, v[2:3], off
	v_lshl_add_u64 v[2:3], v[2:3], 0, s[14:15]
	global_load_dword v68, v[2:3], off
	v_lshl_add_u64 v[2:3], v[2:3], 0, s[14:15]
	global_load_dword v69, v[2:3], off
	v_lshl_add_u64 v[2:3], v[2:3], 0, s[14:15]
	global_load_dword v70, v[2:3], off
	v_lshl_add_u64 v[2:3], v[2:3], 0, s[14:15]
	global_load_dword v71, v[2:3], off
	v_lshl_add_u64 v[2:3], v[2:3], 0, s[14:15]
	global_load_dword v72, v[2:3], off
	v_lshl_add_u64 v[2:3], v[2:3], 0, s[14:15]
	global_load_dword v73, v[2:3], off
	v_lshl_add_u64 v[2:3], v[2:3], 0, s[14:15]
	global_load_dword v74, v[2:3], off
	v_lshl_add_u64 v[2:3], v[2:3], 0, s[14:15]
	global_load_dword v75, v[2:3], off
	v_lshl_add_u64 v[2:3], v[2:3], 0, s[14:15]
	global_load_dword v76, v[2:3], off
	v_lshl_add_u64 v[2:3], v[2:3], 0, s[14:15]
	global_load_dword v77, v[2:3], off
	v_lshl_add_u64 v[2:3], v[2:3], 0, s[14:15]
	global_load_dword v78, v[2:3], off
	v_lshl_add_u64 v[2:3], v[2:3], 0, s[14:15]
	global_load_dword v79, v[2:3], off
	v_lshl_add_u64 v[2:3], v[2:3], 0, s[14:15]
	global_load_dword v80, v[2:3], off
	v_lshl_add_u64 v[2:3], v[2:3], 0, s[14:15]
	global_load_dword v81, v[2:3], off
	v_lshl_add_u64 v[2:3], v[2:3], 0, s[14:15]
	global_load_dword v82, v[2:3], off
	v_lshl_add_u64 v[2:3], v[2:3], 0, s[14:15]
	global_load_dword v83, v[2:3], off
	v_lshl_add_u64 v[2:3], v[2:3], 0, s[14:15]
	global_load_dword v84, v[2:3], off
	v_lshl_add_u64 v[2:3], v[2:3], 0, s[14:15]
	global_load_dword v85, v[2:3], off
	v_lshl_add_u64 v[2:3], v[2:3], 0, s[14:15]
	global_load_dword v86, v[2:3], off
	v_lshl_add_u64 v[2:3], v[2:3], 0, s[14:15]
	global_load_dword v87, v[2:3], off
	v_lshl_add_u64 v[2:3], v[2:3], 0, s[14:15]
	global_load_dword v88, v[2:3], off
	v_lshl_add_u64 v[2:3], v[2:3], 0, s[14:15]
	global_load_dword v89, v[2:3], off
	v_lshl_add_u64 v[2:3], v[2:3], 0, s[14:15]
	global_load_dword v90, v[2:3], off
	v_lshl_add_u64 v[2:3], v[2:3], 0, s[14:15]
	global_load_dword v91, v[2:3], off
	v_lshl_add_u64 v[2:3], v[2:3], 0, s[14:15]
	global_load_dword v100, v[2:3], off
	v_lshl_add_u64 v[2:3], v[2:3], 0, s[14:15]
	global_load_dword v101, v[2:3], off
	v_lshl_add_u64 v[2:3], v[2:3], 0, s[14:15]
	global_load_dword v102, v[2:3], off
	v_lshl_add_u64 v[2:3], v[2:3], 0, s[14:15]
	global_load_dword v103, v[2:3], off
	v_lshl_add_u64 v[2:3], v[2:3], 0, s[14:15]
	global_load_dword v104, v[2:3], off
	v_lshl_add_u64 v[2:3], v[2:3], 0, s[14:15]
	global_load_dword v105, v[2:3], off
	v_lshl_add_u64 v[2:3], v[2:3], 0, s[14:15]
	global_load_dword v106, v[2:3], off
	v_lshl_add_u64 v[2:3], v[2:3], 0, s[14:15]
	global_load_dword v107, v[2:3], off
	v_lshl_add_u64 v[2:3], v[2:3], 0, s[14:15]
	global_load_dword v108, v[2:3], off
	v_lshl_add_u64 v[2:3], v[2:3], 0, s[14:15]
	global_load_dword v109, v[2:3], off
	v_lshl_add_u64 v[2:3], v[2:3], 0, s[14:15]
	global_load_dword v110, v[2:3], off
	v_lshl_add_u64 v[2:3], v[2:3], 0, s[14:15]
	global_load_dword v111, v[2:3], off
	v_lshl_add_u64 v[2:3], v[2:3], 0, s[14:15]
	s_mul_i32 s2, s33, 0x2100
	v_add_u32_e32 v188, s2, v186
	v_add_u32_e32 v189, s2, v187
	v_mov_b32_e32 v185, s2
	s_waitcnt vmcnt(48)
	ds_write_b128 v188, v[112:115]
	ds_write_b128 v188, v[116:119] offset:1024
	ds_write_b128 v188, v[120:123] offset:2048
	ds_write_b128 v188, v[124:127] offset:3072
	ds_write_b128 v189, v[128:131] offset:4096
	s_waitcnt lgkmcnt(0)
	ds_read_b128 v[112:115], v185 offset:4096
	ds_read_b128 v[116:119], v185 offset:0
	ds_read_b128 v[120:123], v185 offset:512
	ds_read_b128 v[124:127], v185 offset:1024
	ds_read_b128 v[128:131], v185 offset:1536
	ds_read_b128 v[132:135], v185 offset:2048
	ds_read_b128 v[136:139], v185 offset:2560
	ds_read_b128 v[140:143], v185 offset:3072
	ds_read_b128 v[144:147], v185 offset:3584
	s_waitcnt vmcnt(32)
	ds_read_b128 v[148:151], v185 offset:4112
	ds_read_b128 v[152:155], v185 offset:16
	ds_read_b128 v[156:159], v185 offset:528
	ds_read_b128 v[160:163], v185 offset:1040
	ds_read_b128 v[164:167], v185 offset:1552
	ds_read_b128 v[168:171], v185 offset:2064
	ds_read_b128 v[172:175], v185 offset:2576
	ds_read_b128 v[176:179], v185 offset:3088
	ds_read_b128 v[180:183], v185 offset:3600
	s_waitcnt lgkmcnt(9)
; __device__ __forceinline__ void prep_hybrid(const float* w_in, const float* w_out, const float* pool_w, const float* pool_scale, bf16_t* WIN, bf16_t* WOUT, int gw, int NGW, LAS float* scr, int lane) {
;     ...
;         for (int d = 0; d < 128; ++d) {
;             const float wv = w_out[(size_t)(512 + g * 128 + d) * D + n] * pool_scale[g * 128 + d];
; #pragma unroll
;             for (int i = 0; i < 8; ++i) a[i] += pw[i * 128 + d] * wv;
;         }
	v_mul_f32_e32 v184, v56, v112
	v_fmac_f32_e32 v6, v184, v116
	v_fmac_f32_e32 v7, v184, v120
	v_fmac_f32_e32 v8, v184, v124
	v_fmac_f32_e32 v9, v184, v128
	v_fmac_f32_e32 v10, v184, v132
	v_fmac_f32_e32 v11, v184, v136
	v_fmac_f32_e32 v4, v184, v140
	v_fmac_f32_e32 v5, v184, v144
	v_mul_f32_e32 v184, v57, v113
	v_fmac_f32_e32 v6, v184, v117
	v_fmac_f32_e32 v7, v184, v121
	v_fmac_f32_e32 v8, v184, v125
	v_fmac_f32_e32 v9, v184, v129
	v_fmac_f32_e32 v10, v184, v133
	v_fmac_f32_e32 v11, v184, v137
	v_fmac_f32_e32 v4, v184, v141
	v_fmac_f32_e32 v5, v184, v145
	v_mul_f32_e32 v184, v58, v114
	v_fmac_f32_e32 v6, v184, v118
	v_fmac_f32_e32 v7, v184, v122
	v_fmac_f32_e32 v8, v184, v126
	v_fmac_f32_e32 v9, v184, v130
	v_fmac_f32_e32 v10, v184, v134
	v_fmac_f32_e32 v11, v184, v138
	v_fmac_f32_e32 v4, v184, v142
	v_fmac_f32_e32 v5, v184, v146
	v_mul_f32_e32 v184, v59, v115
	v_fmac_f32_e32 v6, v184, v119
	v_fmac_f32_e32 v7, v184, v123
	v_fmac_f32_e32 v8, v184, v127
	v_fmac_f32_e32 v9, v184, v131
	v_fmac_f32_e32 v10, v184, v135
	v_fmac_f32_e32 v11, v184, v139
	v_fmac_f32_e32 v4, v184, v143
	v_fmac_f32_e32 v5, v184, v147
	ds_read_b128 v[112:115], v185 offset:4128
	ds_read_b128 v[116:119], v185 offset:32
	ds_read_b128 v[120:123], v185 offset:544
	ds_read_b128 v[124:127], v185 offset:1056
	ds_read_b128 v[128:131], v185 offset:1568
	ds_read_b128 v[132:135], v185 offset:2080
	ds_read_b128 v[136:139], v185 offset:2592
	ds_read_b128 v[140:143], v185 offset:3104
	ds_read_b128 v[144:147], v185 offset:3616
	s_waitcnt lgkmcnt(9)
	v_mul_f32_e32 v184, v60, v148
	v_fmac_f32_e32 v6, v184, v152
	v_fmac_f32_e32 v7, v184, v156
	v_fmac_f32_e32 v8, v184, v160
	v_fmac_f32_e32 v9, v184, v164
	v_fmac_f32_e32 v10, v184, v168
	v_fmac_f32_e32 v11, v184, v172
	v_fmac_f32_e32 v4, v184, v176
	v_fmac_f32_e32 v5, v184, v180
	v_mul_f32_e32 v184, v61, v149
	v_fmac_f32_e32 v6, v184, v153
	v_fmac_f32_e32 v7, v184, v157
	v_fmac_f32_e32 v8, v184, v161
	v_fmac_f32_e32 v9, v184, v165
	v_fmac_f32_e32 v10, v184, v169
	v_fmac_f32_e32 v11, v184, v173
	v_fmac_f32_e32 v4, v184, v177
	v_fmac_f32_e32 v5, v184, v181
	v_mul_f32_e32 v184, v62, v150
	v_fmac_f32_e32 v6, v184, v154
	v_fmac_f32_e32 v7, v184, v158
	v_fmac_f32_e32 v8, v184, v162
	v_fmac_f32_e32 v9, v184, v166
	v_fmac_f32_e32 v10, v184, v170
	v_fmac_f32_e32 v11, v184, v174
	v_fmac_f32_e32 v4, v184, v178
	v_fmac_f32_e32 v5, v184, v182
	v_mul_f32_e32 v184, v63, v151
	v_fmac_f32_e32 v6, v184, v155
	v_fmac_f32_e32 v7, v184, v159
	v_fmac_f32_e32 v8, v184, v163
	v_fmac_f32_e32 v9, v184, v167
	v_fmac_f32_e32 v10, v184, v171
	v_fmac_f32_e32 v11, v184, v175
	v_fmac_f32_e32 v4, v184, v179
	v_fmac_f32_e32 v5, v184, v183
	ds_read_b128 v[148:151], v185 offset:4144
	ds_read_b128 v[152:155], v185 offset:48
	ds_read_b128 v[156:159], v185 offset:560
	ds_read_b128 v[160:163], v185 offset:1072
	ds_read_b128 v[164:167], v185 offset:1584
	ds_read_b128 v[168:171], v185 offset:2096
	ds_read_b128 v[172:175], v185 offset:2608
	ds_read_b128 v[176:179], v185 offset:3120
	ds_read_b128 v[180:183], v185 offset:3632
	s_waitcnt lgkmcnt(9)
	v_mul_f32_e32 v184, v64, v112
	v_fmac_f32_e32 v6, v184, v116
	v_fmac_f32_e32 v7, v184, v120
	v_fmac_f32_e32 v8, v184, v124
	v_fmac_f32_e32 v9, v184, v128
	v_fmac_f32_e32 v10, v184, v132
	v_fmac_f32_e32 v11, v184, v136
	v_fmac_f32_e32 v4, v184, v140
	v_fmac_f32_e32 v5, v184, v144
	v_mul_f32_e32 v184, v65, v113
	v_fmac_f32_e32 v6, v184, v117
	v_fmac_f32_e32 v7, v184, v121
	v_fmac_f32_e32 v8, v184, v125
	v_fmac_f32_e32 v9, v184, v129
	v_fmac_f32_e32 v10, v184, v133
	v_fmac_f32_e32 v11, v184, v137
	v_fmac_f32_e32 v4, v184, v141
	v_fmac_f32_e32 v5, v184, v145
	v_mul_f32_e32 v184, v66, v114
	v_fmac_f32_e32 v6, v184, v118
	v_fmac_f32_e32 v7, v184, v122
	v_fmac_f32_e32 v8, v184, v126
	v_fmac_f32_e32 v9, v184, v130
	v_fmac_f32_e32 v10, v184, v134
	v_fmac_f32_e32 v11, v184, v138
	v_fmac_f32_e32 v4, v184, v142
	v_fmac_f32_e32 v5, v184, v146
	v_mul_f32_e32 v184, v67, v115
	v_fmac_f32_e32 v6, v184, v119
	v_fmac_f32_e32 v7, v184, v123
	v_fmac_f32_e32 v8, v184, v127
	v_fmac_f32_e32 v9, v184, v131
	v_fmac_f32_e32 v10, v184, v135
	v_fmac_f32_e32 v11, v184, v139
	v_fmac_f32_e32 v4, v184, v143
	v_fmac_f32_e32 v5, v184, v147
	ds_read_b128 v[112:115], v185 offset:4160
	ds_read_b128 v[116:119], v185 offset:64
	ds_read_b128 v[120:123], v185 offset:576
	ds_read_b128 v[124:127], v185 offset:1088
	ds_read_b128 v[128:131], v185 offset:1600
	ds_read_b128 v[132:135], v185 offset:2112
	ds_read_b128 v[136:139], v185 offset:2624
	ds_read_b128 v[140:143], v185 offset:3136
	ds_read_b128 v[144:147], v185 offset:3648
	s_waitcnt lgkmcnt(9)
; __device__ __forceinline__ void prep_hybrid(const float* w_in, const float* w_out, const float* pool_w, const float* pool_scale, bf16_t* WIN, bf16_t* WOUT, int gw, int NGW, LAS float* scr, int lane) {
;     ...
;         for (int d = 0; d < 128; ++d) {
;             const float wv = w_out[(size_t)(512 + g * 128 + d) * D + n] * pool_scale[g * 128 + d];
; #pragma unroll
;             for (int i = 0; i < 8; ++i) a[i] += pw[i * 128 + d] * wv;
;         }
	v_mul_f32_e32 v184, v68, v148
	v_fmac_f32_e32 v6, v184, v152
	v_fmac_f32_e32 v7, v184, v156
	v_fmac_f32_e32 v8, v184, v160
	v_fmac_f32_e32 v9, v184, v164
	v_fmac_f32_e32 v10, v184, v168
	v_fmac_f32_e32 v11, v184, v172
	v_fmac_f32_e32 v4, v184, v176
	v_fmac_f32_e32 v5, v184, v180
	v_mul_f32_e32 v184, v69, v149
	v_fmac_f32_e32 v6, v184, v153
	v_fmac_f32_e32 v7, v184, v157
	v_fmac_f32_e32 v8, v184, v161
	v_fmac_f32_e32 v9, v184, v165
	v_fmac_f32_e32 v10, v184, v169
	v_fmac_f32_e32 v11, v184, v173
	v_fmac_f32_e32 v4, v184, v177
	v_fmac_f32_e32 v5, v184, v181
	v_mul_f32_e32 v184, v70, v150
	v_fmac_f32_e32 v6, v184, v154
	v_fmac_f32_e32 v7, v184, v158
	v_fmac_f32_e32 v8, v184, v162
	v_fmac_f32_e32 v9, v184, v166
	v_fmac_f32_e32 v10, v184, v170
	v_fmac_f32_e32 v11, v184, v174
	v_fmac_f32_e32 v4, v184, v178
	v_fmac_f32_e32 v5, v184, v182
	v_mul_f32_e32 v184, v71, v151
	v_fmac_f32_e32 v6, v184, v155
	v_fmac_f32_e32 v7, v184, v159
	v_fmac_f32_e32 v8, v184, v163
	v_fmac_f32_e32 v9, v184, v167
	v_fmac_f32_e32 v10, v184, v171
	v_fmac_f32_e32 v11, v184, v175
	v_fmac_f32_e32 v4, v184, v179
	v_fmac_f32_e32 v5, v184, v183
	global_load_dword v56, v[2:3], off
	v_lshl_add_u64 v[2:3], v[2:3], 0, s[14:15]
	global_load_dword v57, v[2:3], off
	v_lshl_add_u64 v[2:3], v[2:3], 0, s[14:15]
	global_load_dword v58, v[2:3], off
	v_lshl_add_u64 v[2:3], v[2:3], 0, s[14:15]
	global_load_dword v59, v[2:3], off
	v_lshl_add_u64 v[2:3], v[2:3], 0, s[14:15]
	global_load_dword v60, v[2:3], off
	v_lshl_add_u64 v[2:3], v[2:3], 0, s[14:15]
	global_load_dword v61, v[2:3], off
	v_lshl_add_u64 v[2:3], v[2:3], 0, s[14:15]
	global_load_dword v62, v[2:3], off
	v_lshl_add_u64 v[2:3], v[2:3], 0, s[14:15]
	global_load_dword v63, v[2:3], off
	v_lshl_add_u64 v[2:3], v[2:3], 0, s[14:15]
	global_load_dword v64, v[2:3], off
	v_lshl_add_u64 v[2:3], v[2:3], 0, s[14:15]
	global_load_dword v65, v[2:3], off
	v_lshl_add_u64 v[2:3], v[2:3], 0, s[14:15]
	global_load_dword v66, v[2:3], off
	v_lshl_add_u64 v[2:3], v[2:3], 0, s[14:15]
	global_load_dword v67, v[2:3], off
	v_lshl_add_u64 v[2:3], v[2:3], 0, s[14:15]
	global_load_dword v68, v[2:3], off
	v_lshl_add_u64 v[2:3], v[2:3], 0, s[14:15]
	global_load_dword v69, v[2:3], off
	v_lshl_add_u64 v[2:3], v[2:3], 0, s[14:15]
	global_load_dword v70, v[2:3], off
	v_lshl_add_u64 v[2:3], v[2:3], 0, s[14:15]
	global_load_dword v71, v[2:3], off
	v_lshl_add_u64 v[2:3], v[2:3], 0, s[14:15]
	s_waitcnt vmcnt(32)
	ds_read_b128 v[148:151], v185 offset:4176
	ds_read_b128 v[152:155], v185 offset:80
	ds_read_b128 v[156:159], v185 offset:592
	ds_read_b128 v[160:163], v185 offset:1104
	ds_read_b128 v[164:167], v185 offset:1616
	ds_read_b128 v[168:171], v185 offset:2128
	ds_read_b128 v[172:175], v185 offset:2640
	ds_read_b128 v[176:179], v185 offset:3152
	ds_read_b128 v[180:183], v185 offset:3664
	s_waitcnt lgkmcnt(9)
	v_mul_f32_e32 v184, v72, v112
	v_fmac_f32_e32 v6, v184, v116
	v_fmac_f32_e32 v7, v184, v120
	v_fmac_f32_e32 v8, v184, v124
	v_fmac_f32_e32 v9, v184, v128
	v_fmac_f32_e32 v10, v184, v132
	v_fmac_f32_e32 v11, v184, v136
	v_fmac_f32_e32 v4, v184, v140
	v_fmac_f32_e32 v5, v184, v144
	v_mul_f32_e32 v184, v73, v113
	v_fmac_f32_e32 v6, v184, v117
	v_fmac_f32_e32 v7, v184, v121
	v_fmac_f32_e32 v8, v184, v125
	v_fmac_f32_e32 v9, v184, v129
	v_fmac_f32_e32 v10, v184, v133
	v_fmac_f32_e32 v11, v184, v137
	v_fmac_f32_e32 v4, v184, v141
	v_fmac_f32_e32 v5, v184, v145
	v_mul_f32_e32 v184, v74, v114
	v_fmac_f32_e32 v6, v184, v118
	v_fmac_f32_e32 v7, v184, v122
	v_fmac_f32_e32 v8, v184, v126
	v_fmac_f32_e32 v9, v184, v130
	v_fmac_f32_e32 v10, v184, v134
	v_fmac_f32_e32 v11, v184, v138
	v_fmac_f32_e32 v4, v184, v142
	v_fmac_f32_e32 v5, v184, v146
	v_mul_f32_e32 v184, v75, v115
	v_fmac_f32_e32 v6, v184, v119
	v_fmac_f32_e32 v7, v184, v123
	v_fmac_f32_e32 v8, v184, v127
	v_fmac_f32_e32 v9, v184, v131
	v_fmac_f32_e32 v10, v184, v135
	v_fmac_f32_e32 v11, v184, v139
	v_fmac_f32_e32 v4, v184, v143
	v_fmac_f32_e32 v5, v184, v147
	ds_read_b128 v[112:115], v185 offset:4192
	ds_read_b128 v[116:119], v185 offset:96
	ds_read_b128 v[120:123], v185 offset:608
	ds_read_b128 v[124:127], v185 offset:1120
	ds_read_b128 v[128:131], v185 offset:1632
	ds_read_b128 v[132:135], v185 offset:2144
	ds_read_b128 v[136:139], v185 offset:2656
	ds_read_b128 v[140:143], v185 offset:3168
	ds_read_b128 v[144:147], v185 offset:3680
	s_waitcnt lgkmcnt(9)
	v_mul_f32_e32 v184, v76, v148
	v_fmac_f32_e32 v6, v184, v152
	v_fmac_f32_e32 v7, v184, v156
	v_fmac_f32_e32 v8, v184, v160
	v_fmac_f32_e32 v9, v184, v164
	v_fmac_f32_e32 v10, v184, v168
	v_fmac_f32_e32 v11, v184, v172
	v_fmac_f32_e32 v4, v184, v176
	v_fmac_f32_e32 v5, v184, v180
	v_mul_f32_e32 v184, v77, v149
	v_fmac_f32_e32 v6, v184, v153
	v_fmac_f32_e32 v7, v184, v157
	v_fmac_f32_e32 v8, v184, v161
	v_fmac_f32_e32 v9, v184, v165
	v_fmac_f32_e32 v10, v184, v169
	v_fmac_f32_e32 v11, v184, v173
	v_fmac_f32_e32 v4, v184, v177
	v_fmac_f32_e32 v5, v184, v181
	v_mul_f32_e32 v184, v78, v150
	v_fmac_f32_e32 v6, v184, v154
	v_fmac_f32_e32 v7, v184, v158
	v_fmac_f32_e32 v8, v184, v162
	v_fmac_f32_e32 v9, v184, v166
	v_fmac_f32_e32 v10, v184, v170
	v_fmac_f32_e32 v11, v184, v174
	v_fmac_f32_e32 v4, v184, v178
	v_fmac_f32_e32 v5, v184, v182
	v_mul_f32_e32 v184, v79, v151
	v_fmac_f32_e32 v6, v184, v155
	v_fmac_f32_e32 v7, v184, v159
	v_fmac_f32_e32 v8, v184, v163
	v_fmac_f32_e32 v9, v184, v167
	v_fmac_f32_e32 v10, v184, v171
	v_fmac_f32_e32 v11, v184, v175
	v_fmac_f32_e32 v4, v184, v179
	v_fmac_f32_e32 v5, v184, v183
	ds_read_b128 v[148:151], v185 offset:4208
	ds_read_b128 v[152:155], v185 offset:112
	ds_read_b128 v[156:159], v185 offset:624
	ds_read_b128 v[160:163], v185 offset:1136
	ds_read_b128 v[164:167], v185 offset:1648
	ds_read_b128 v[168:171], v185 offset:2160
	ds_read_b128 v[172:175], v185 offset:2672
	ds_read_b128 v[176:179], v185 offset:3184
	ds_read_b128 v[180:183], v185 offset:3696
	s_waitcnt lgkmcnt(9)
; __device__ __forceinline__ void prep_hybrid(const float* w_in, const float* w_out, const float* pool_w, const float* pool_scale, bf16_t* WIN, bf16_t* WOUT, int gw, int NGW, LAS float* scr, int lane) {
;     ...
;         for (int d = 0; d < 128; ++d) {
;             const float wv = w_out[(size_t)(512 + g * 128 + d) * D + n] * pool_scale[g * 128 + d];
; #pragma unroll
;             for (int i = 0; i < 8; ++i) a[i] += pw[i * 128 + d] * wv;
;         }
	v_mul_f32_e32 v184, v80, v112
	v_fmac_f32_e32 v6, v184, v116
	v_fmac_f32_e32 v7, v184, v120
	v_fmac_f32_e32 v8, v184, v124
	v_fmac_f32_e32 v9, v184, v128
	v_fmac_f32_e32 v10, v184, v132
	v_fmac_f32_e32 v11, v184, v136
	v_fmac_f32_e32 v4, v184, v140
	v_fmac_f32_e32 v5, v184, v144
	v_mul_f32_e32 v184, v81, v113
	v_fmac_f32_e32 v6, v184, v117
	v_fmac_f32_e32 v7, v184, v121
	v_fmac_f32_e32 v8, v184, v125
	v_fmac_f32_e32 v9, v184, v129
	v_fmac_f32_e32 v10, v184, v133
	v_fmac_f32_e32 v11, v184, v137
	v_fmac_f32_e32 v4, v184, v141
	v_fmac_f32_e32 v5, v184, v145
	v_mul_f32_e32 v184, v82, v114
	v_fmac_f32_e32 v6, v184, v118
	v_fmac_f32_e32 v7, v184, v122
	v_fmac_f32_e32 v8, v184, v126
	v_fmac_f32_e32 v9, v184, v130
	v_fmac_f32_e32 v10, v184, v134
	v_fmac_f32_e32 v11, v184, v138
	v_fmac_f32_e32 v4, v184, v142
	v_fmac_f32_e32 v5, v184, v146
	v_mul_f32_e32 v184, v83, v115
	v_fmac_f32_e32 v6, v184, v119
	v_fmac_f32_e32 v7, v184, v123
	v_fmac_f32_e32 v8, v184, v127
	v_fmac_f32_e32 v9, v184, v131
	v_fmac_f32_e32 v10, v184, v135
	v_fmac_f32_e32 v11, v184, v139
	v_fmac_f32_e32 v4, v184, v143
	v_fmac_f32_e32 v5, v184, v147
	ds_read_b128 v[112:115], v185 offset:4224
	ds_read_b128 v[116:119], v185 offset:128
	ds_read_b128 v[120:123], v185 offset:640
	ds_read_b128 v[124:127], v185 offset:1152
	ds_read_b128 v[128:131], v185 offset:1664
	ds_read_b128 v[132:135], v185 offset:2176
	ds_read_b128 v[136:139], v185 offset:2688
	ds_read_b128 v[140:143], v185 offset:3200
	ds_read_b128 v[144:147], v185 offset:3712
	s_waitcnt lgkmcnt(9)
	v_mul_f32_e32 v184, v84, v148
	v_fmac_f32_e32 v6, v184, v152
	v_fmac_f32_e32 v7, v184, v156
	v_fmac_f32_e32 v8, v184, v160
	v_fmac_f32_e32 v9, v184, v164
	v_fmac_f32_e32 v10, v184, v168
	v_fmac_f32_e32 v11, v184, v172
	v_fmac_f32_e32 v4, v184, v176
	v_fmac_f32_e32 v5, v184, v180
	v_mul_f32_e32 v184, v85, v149
	v_fmac_f32_e32 v6, v184, v153
	v_fmac_f32_e32 v7, v184, v157
	v_fmac_f32_e32 v8, v184, v161
	v_fmac_f32_e32 v9, v184, v165
	v_fmac_f32_e32 v10, v184, v169
	v_fmac_f32_e32 v11, v184, v173
	v_fmac_f32_e32 v4, v184, v177
	v_fmac_f32_e32 v5, v184, v181
	v_mul_f32_e32 v184, v86, v150
	v_fmac_f32_e32 v6, v184, v154
	v_fmac_f32_e32 v7, v184, v158
	v_fmac_f32_e32 v8, v184, v162
	v_fmac_f32_e32 v9, v184, v166
	v_fmac_f32_e32 v10, v184, v170
	v_fmac_f32_e32 v11, v184, v174
	v_fmac_f32_e32 v4, v184, v178
	v_fmac_f32_e32 v5, v184, v182
	v_mul_f32_e32 v184, v87, v151
	v_fmac_f32_e32 v6, v184, v155
	v_fmac_f32_e32 v7, v184, v159
	v_fmac_f32_e32 v8, v184, v163
	v_fmac_f32_e32 v9, v184, v167
	v_fmac_f32_e32 v10, v184, v171
	v_fmac_f32_e32 v11, v184, v175
	v_fmac_f32_e32 v4, v184, v179
	v_fmac_f32_e32 v5, v184, v183
	global_load_dword v72, v[2:3], off
	v_lshl_add_u64 v[2:3], v[2:3], 0, s[14:15]
	global_load_dword v73, v[2:3], off
	v_lshl_add_u64 v[2:3], v[2:3], 0, s[14:15]
	global_load_dword v74, v[2:3], off
	v_lshl_add_u64 v[2:3], v[2:3], 0, s[14:15]
	global_load_dword v75, v[2:3], off
	v_lshl_add_u64 v[2:3], v[2:3], 0, s[14:15]
	global_load_dword v76, v[2:3], off
	v_lshl_add_u64 v[2:3], v[2:3], 0, s[14:15]
	global_load_dword v77, v[2:3], off
	v_lshl_add_u64 v[2:3], v[2:3], 0, s[14:15]
	global_load_dword v78, v[2:3], off
	v_lshl_add_u64 v[2:3], v[2:3], 0, s[14:15]
	global_load_dword v79, v[2:3], off
	v_lshl_add_u64 v[2:3], v[2:3], 0, s[14:15]
	global_load_dword v80, v[2:3], off
	v_lshl_add_u64 v[2:3], v[2:3], 0, s[14:15]
	global_load_dword v81, v[2:3], off
	v_lshl_add_u64 v[2:3], v[2:3], 0, s[14:15]
	global_load_dword v82, v[2:3], off
	v_lshl_add_u64 v[2:3], v[2:3], 0, s[14:15]
	global_load_dword v83, v[2:3], off
	v_lshl_add_u64 v[2:3], v[2:3], 0, s[14:15]
	global_load_dword v84, v[2:3], off
	v_lshl_add_u64 v[2:3], v[2:3], 0, s[14:15]
	global_load_dword v85, v[2:3], off
	v_lshl_add_u64 v[2:3], v[2:3], 0, s[14:15]
	global_load_dword v86, v[2:3], off
	v_lshl_add_u64 v[2:3], v[2:3], 0, s[14:15]
	global_load_dword v87, v[2:3], off
	v_lshl_add_u64 v[2:3], v[2:3], 0, s[14:15]
	s_waitcnt vmcnt(32)
	ds_read_b128 v[148:151], v185 offset:4240
	ds_read_b128 v[152:155], v185 offset:144
	ds_read_b128 v[156:159], v185 offset:656
	ds_read_b128 v[160:163], v185 offset:1168
	ds_read_b128 v[164:167], v185 offset:1680
	ds_read_b128 v[168:171], v185 offset:2192
	ds_read_b128 v[172:175], v185 offset:2704
	ds_read_b128 v[176:179], v185 offset:3216
	ds_read_b128 v[180:183], v185 offset:3728
	s_waitcnt lgkmcnt(9)
	v_mul_f32_e32 v184, v88, v112
	v_fmac_f32_e32 v6, v184, v116
	v_fmac_f32_e32 v7, v184, v120
	v_fmac_f32_e32 v8, v184, v124
	v_fmac_f32_e32 v9, v184, v128
	v_fmac_f32_e32 v10, v184, v132
	v_fmac_f32_e32 v11, v184, v136
	v_fmac_f32_e32 v4, v184, v140
	v_fmac_f32_e32 v5, v184, v144
	v_mul_f32_e32 v184, v89, v113
	v_fmac_f32_e32 v6, v184, v117
	v_fmac_f32_e32 v7, v184, v121
	v_fmac_f32_e32 v8, v184, v125
	v_fmac_f32_e32 v9, v184, v129
	v_fmac_f32_e32 v10, v184, v133
	v_fmac_f32_e32 v11, v184, v137
	v_fmac_f32_e32 v4, v184, v141
	v_fmac_f32_e32 v5, v184, v145
	v_mul_f32_e32 v184, v90, v114
	v_fmac_f32_e32 v6, v184, v118
	v_fmac_f32_e32 v7, v184, v122
	v_fmac_f32_e32 v8, v184, v126
	v_fmac_f32_e32 v9, v184, v130
	v_fmac_f32_e32 v10, v184, v134
	v_fmac_f32_e32 v11, v184, v138
	v_fmac_f32_e32 v4, v184, v142
	v_fmac_f32_e32 v5, v184, v146
	v_mul_f32_e32 v184, v91, v115
	v_fmac_f32_e32 v6, v184, v119
	v_fmac_f32_e32 v7, v184, v123
	v_fmac_f32_e32 v8, v184, v127
	v_fmac_f32_e32 v9, v184, v131
	v_fmac_f32_e32 v10, v184, v135
	v_fmac_f32_e32 v11, v184, v139
	v_fmac_f32_e32 v4, v184, v143
	v_fmac_f32_e32 v5, v184, v147
	ds_read_b128 v[112:115], v185 offset:4256
	ds_read_b128 v[116:119], v185 offset:160
	ds_read_b128 v[120:123], v185 offset:672
	ds_read_b128 v[124:127], v185 offset:1184
	ds_read_b128 v[128:131], v185 offset:1696
	ds_read_b128 v[132:135], v185 offset:2208
	ds_read_b128 v[136:139], v185 offset:2720
	ds_read_b128 v[140:143], v185 offset:3232
	ds_read_b128 v[144:147], v185 offset:3744
	s_waitcnt lgkmcnt(9)
; __device__ __forceinline__ void prep_hybrid(const float* w_in, const float* w_out, const float* pool_w, const float* pool_scale, bf16_t* WIN, bf16_t* WOUT, int gw, int NGW, LAS float* scr, int lane) {
;     ...
;         for (int d = 0; d < 128; ++d) {
;             const float wv = w_out[(size_t)(512 + g * 128 + d) * D + n] * pool_scale[g * 128 + d];
; #pragma unroll
;             for (int i = 0; i < 8; ++i) a[i] += pw[i * 128 + d] * wv;
;         }
	v_mul_f32_e32 v184, v100, v148
	v_fmac_f32_e32 v6, v184, v152
	v_fmac_f32_e32 v7, v184, v156
	v_fmac_f32_e32 v8, v184, v160
	v_fmac_f32_e32 v9, v184, v164
	v_fmac_f32_e32 v10, v184, v168
	v_fmac_f32_e32 v11, v184, v172
	v_fmac_f32_e32 v4, v184, v176
	v_fmac_f32_e32 v5, v184, v180
	v_mul_f32_e32 v184, v101, v149
	v_fmac_f32_e32 v6, v184, v153
	v_fmac_f32_e32 v7, v184, v157
	v_fmac_f32_e32 v8, v184, v161
	v_fmac_f32_e32 v9, v184, v165
	v_fmac_f32_e32 v10, v184, v169
	v_fmac_f32_e32 v11, v184, v173
	v_fmac_f32_e32 v4, v184, v177
	v_fmac_f32_e32 v5, v184, v181
	v_mul_f32_e32 v184, v102, v150
	v_fmac_f32_e32 v6, v184, v154
	v_fmac_f32_e32 v7, v184, v158
	v_fmac_f32_e32 v8, v184, v162
	v_fmac_f32_e32 v9, v184, v166
	v_fmac_f32_e32 v10, v184, v170
	v_fmac_f32_e32 v11, v184, v174
	v_fmac_f32_e32 v4, v184, v178
	v_fmac_f32_e32 v5, v184, v182
	v_mul_f32_e32 v184, v103, v151
	v_fmac_f32_e32 v6, v184, v155
	v_fmac_f32_e32 v7, v184, v159
	v_fmac_f32_e32 v8, v184, v163
	v_fmac_f32_e32 v9, v184, v167
	v_fmac_f32_e32 v10, v184, v171
	v_fmac_f32_e32 v11, v184, v175
	v_fmac_f32_e32 v4, v184, v179
	v_fmac_f32_e32 v5, v184, v183
	ds_read_b128 v[148:151], v185 offset:4272
	ds_read_b128 v[152:155], v185 offset:176
	ds_read_b128 v[156:159], v185 offset:688
	ds_read_b128 v[160:163], v185 offset:1200
	ds_read_b128 v[164:167], v185 offset:1712
	ds_read_b128 v[168:171], v185 offset:2224
	ds_read_b128 v[172:175], v185 offset:2736
	ds_read_b128 v[176:179], v185 offset:3248
	ds_read_b128 v[180:183], v185 offset:3760
	s_waitcnt lgkmcnt(9)
	v_mul_f32_e32 v184, v104, v112
	v_fmac_f32_e32 v6, v184, v116
	v_fmac_f32_e32 v7, v184, v120
	v_fmac_f32_e32 v8, v184, v124
	v_fmac_f32_e32 v9, v184, v128
	v_fmac_f32_e32 v10, v184, v132
	v_fmac_f32_e32 v11, v184, v136
	v_fmac_f32_e32 v4, v184, v140
	v_fmac_f32_e32 v5, v184, v144
	v_mul_f32_e32 v184, v105, v113
	v_fmac_f32_e32 v6, v184, v117
	v_fmac_f32_e32 v7, v184, v121
	v_fmac_f32_e32 v8, v184, v125
	v_fmac_f32_e32 v9, v184, v129
	v_fmac_f32_e32 v10, v184, v133
	v_fmac_f32_e32 v11, v184, v137
	v_fmac_f32_e32 v4, v184, v141
	v_fmac_f32_e32 v5, v184, v145
	v_mul_f32_e32 v184, v106, v114
	v_fmac_f32_e32 v6, v184, v118
	v_fmac_f32_e32 v7, v184, v122
	v_fmac_f32_e32 v8, v184, v126
	v_fmac_f32_e32 v9, v184, v130
	v_fmac_f32_e32 v10, v184, v134
	v_fmac_f32_e32 v11, v184, v138
	v_fmac_f32_e32 v4, v184, v142
	v_fmac_f32_e32 v5, v184, v146
	v_mul_f32_e32 v184, v107, v115
	v_fmac_f32_e32 v6, v184, v119
	v_fmac_f32_e32 v7, v184, v123
	v_fmac_f32_e32 v8, v184, v127
	v_fmac_f32_e32 v9, v184, v131
	v_fmac_f32_e32 v10, v184, v135
	v_fmac_f32_e32 v11, v184, v139
	v_fmac_f32_e32 v4, v184, v143
	v_fmac_f32_e32 v5, v184, v147
	ds_read_b128 v[112:115], v185 offset:4288
	ds_read_b128 v[116:119], v185 offset:192
	ds_read_b128 v[120:123], v185 offset:704
	ds_read_b128 v[124:127], v185 offset:1216
	ds_read_b128 v[128:131], v185 offset:1728
	ds_read_b128 v[132:135], v185 offset:2240
	ds_read_b128 v[136:139], v185 offset:2752
	ds_read_b128 v[140:143], v185 offset:3264
	ds_read_b128 v[144:147], v185 offset:3776
	s_waitcnt lgkmcnt(9)
	v_mul_f32_e32 v184, v108, v148
	v_fmac_f32_e32 v6, v184, v152
	v_fmac_f32_e32 v7, v184, v156
	v_fmac_f32_e32 v8, v184, v160
	v_fmac_f32_e32 v9, v184, v164
	v_fmac_f32_e32 v10, v184, v168
	v_fmac_f32_e32 v11, v184, v172
	v_fmac_f32_e32 v4, v184, v176
	v_fmac_f32_e32 v5, v184, v180
	v_mul_f32_e32 v184, v109, v149
	v_fmac_f32_e32 v6, v184, v153
	v_fmac_f32_e32 v7, v184, v157
	v_fmac_f32_e32 v8, v184, v161
	v_fmac_f32_e32 v9, v184, v165
	v_fmac_f32_e32 v10, v184, v169
	v_fmac_f32_e32 v11, v184, v173
	v_fmac_f32_e32 v4, v184, v177
	v_fmac_f32_e32 v5, v184, v181
	v_mul_f32_e32 v184, v110, v150
	v_fmac_f32_e32 v6, v184, v154
	v_fmac_f32_e32 v7, v184, v158
	v_fmac_f32_e32 v8, v184, v162
	v_fmac_f32_e32 v9, v184, v166
	v_fmac_f32_e32 v10, v184, v170
	v_fmac_f32_e32 v11, v184, v174
	v_fmac_f32_e32 v4, v184, v178
	v_fmac_f32_e32 v5, v184, v182
	v_mul_f32_e32 v184, v111, v151
	v_fmac_f32_e32 v6, v184, v155
	v_fmac_f32_e32 v7, v184, v159
	v_fmac_f32_e32 v8, v184, v163
	v_fmac_f32_e32 v9, v184, v167
	v_fmac_f32_e32 v10, v184, v171
	v_fmac_f32_e32 v11, v184, v175
	v_fmac_f32_e32 v4, v184, v179
	v_fmac_f32_e32 v5, v184, v183
	global_load_dword v88, v[2:3], off
	v_lshl_add_u64 v[2:3], v[2:3], 0, s[14:15]
	global_load_dword v89, v[2:3], off
	v_lshl_add_u64 v[2:3], v[2:3], 0, s[14:15]
	global_load_dword v90, v[2:3], off
	v_lshl_add_u64 v[2:3], v[2:3], 0, s[14:15]
	global_load_dword v91, v[2:3], off
	v_lshl_add_u64 v[2:3], v[2:3], 0, s[14:15]
	global_load_dword v100, v[2:3], off
	v_lshl_add_u64 v[2:3], v[2:3], 0, s[14:15]
	global_load_dword v101, v[2:3], off
	v_lshl_add_u64 v[2:3], v[2:3], 0, s[14:15]
	global_load_dword v102, v[2:3], off
	v_lshl_add_u64 v[2:3], v[2:3], 0, s[14:15]
	global_load_dword v103, v[2:3], off
	v_lshl_add_u64 v[2:3], v[2:3], 0, s[14:15]
	global_load_dword v104, v[2:3], off
	v_lshl_add_u64 v[2:3], v[2:3], 0, s[14:15]
	global_load_dword v105, v[2:3], off
	v_lshl_add_u64 v[2:3], v[2:3], 0, s[14:15]
	global_load_dword v106, v[2:3], off
	v_lshl_add_u64 v[2:3], v[2:3], 0, s[14:15]
	global_load_dword v107, v[2:3], off
	v_lshl_add_u64 v[2:3], v[2:3], 0, s[14:15]
	global_load_dword v108, v[2:3], off
	v_lshl_add_u64 v[2:3], v[2:3], 0, s[14:15]
	global_load_dword v109, v[2:3], off
	v_lshl_add_u64 v[2:3], v[2:3], 0, s[14:15]
	global_load_dword v110, v[2:3], off
	v_lshl_add_u64 v[2:3], v[2:3], 0, s[14:15]
	global_load_dword v111, v[2:3], off
	v_lshl_add_u64 v[2:3], v[2:3], 0, s[14:15]
	s_waitcnt vmcnt(32)
; __device__ __forceinline__ void prep_hybrid(const float* w_in, const float* w_out, const float* pool_w, const float* pool_scale, bf16_t* WIN, bf16_t* WOUT, int gw, int NGW, LAS float* scr, int lane) {
;     ...
;         for (int d = 0; d < 128; ++d) {
;             const float wv = w_out[(size_t)(512 + g * 128 + d) * D + n] * pool_scale[g * 128 + d];
; #pragma unroll
;             for (int i = 0; i < 8; ++i) a[i] += pw[i * 128 + d] * wv;
;         }
	ds_read_b128 v[148:151], v185 offset:4304
	ds_read_b128 v[152:155], v185 offset:208
	ds_read_b128 v[156:159], v185 offset:720
	ds_read_b128 v[160:163], v185 offset:1232
	ds_read_b128 v[164:167], v185 offset:1744
	ds_read_b128 v[168:171], v185 offset:2256
	ds_read_b128 v[172:175], v185 offset:2768
	ds_read_b128 v[176:179], v185 offset:3280
	ds_read_b128 v[180:183], v185 offset:3792
	s_waitcnt lgkmcnt(9)
	v_mul_f32_e32 v184, v56, v112
	v_fmac_f32_e32 v6, v184, v116
	v_fmac_f32_e32 v7, v184, v120
	v_fmac_f32_e32 v8, v184, v124
	v_fmac_f32_e32 v9, v184, v128
	v_fmac_f32_e32 v10, v184, v132
	v_fmac_f32_e32 v11, v184, v136
	v_fmac_f32_e32 v4, v184, v140
	v_fmac_f32_e32 v5, v184, v144
	v_mul_f32_e32 v184, v57, v113
	v_fmac_f32_e32 v6, v184, v117
	v_fmac_f32_e32 v7, v184, v121
	v_fmac_f32_e32 v8, v184, v125
	v_fmac_f32_e32 v9, v184, v129
	v_fmac_f32_e32 v10, v184, v133
	v_fmac_f32_e32 v11, v184, v137
	v_fmac_f32_e32 v4, v184, v141
	v_fmac_f32_e32 v5, v184, v145
	v_mul_f32_e32 v184, v58, v114
	v_fmac_f32_e32 v6, v184, v118
	v_fmac_f32_e32 v7, v184, v122
	v_fmac_f32_e32 v8, v184, v126
	v_fmac_f32_e32 v9, v184, v130
	v_fmac_f32_e32 v10, v184, v134
	v_fmac_f32_e32 v11, v184, v138
	v_fmac_f32_e32 v4, v184, v142
	v_fmac_f32_e32 v5, v184, v146
	v_mul_f32_e32 v184, v59, v115
	v_fmac_f32_e32 v6, v184, v119
	v_fmac_f32_e32 v7, v184, v123
	v_fmac_f32_e32 v8, v184, v127
	v_fmac_f32_e32 v9, v184, v131
	v_fmac_f32_e32 v10, v184, v135
	v_fmac_f32_e32 v11, v184, v139
	v_fmac_f32_e32 v4, v184, v143
	v_fmac_f32_e32 v5, v184, v147
	ds_read_b128 v[112:115], v185 offset:4320
	ds_read_b128 v[116:119], v185 offset:224
	ds_read_b128 v[120:123], v185 offset:736
	ds_read_b128 v[124:127], v185 offset:1248
	ds_read_b128 v[128:131], v185 offset:1760
	ds_read_b128 v[132:135], v185 offset:2272
	ds_read_b128 v[136:139], v185 offset:2784
	ds_read_b128 v[140:143], v185 offset:3296
	ds_read_b128 v[144:147], v185 offset:3808
	s_waitcnt lgkmcnt(9)
	v_mul_f32_e32 v184, v60, v148
	v_fmac_f32_e32 v6, v184, v152
	v_fmac_f32_e32 v7, v184, v156
	v_fmac_f32_e32 v8, v184, v160
	v_fmac_f32_e32 v9, v184, v164
	v_fmac_f32_e32 v10, v184, v168
	v_fmac_f32_e32 v11, v184, v172
	v_fmac_f32_e32 v4, v184, v176
	v_fmac_f32_e32 v5, v184, v180
	v_mul_f32_e32 v184, v61, v149
	v_fmac_f32_e32 v6, v184, v153
	v_fmac_f32_e32 v7, v184, v157
	v_fmac_f32_e32 v8, v184, v161
	v_fmac_f32_e32 v9, v184, v165
	v_fmac_f32_e32 v10, v184, v169
	v_fmac_f32_e32 v11, v184, v173
	v_fmac_f32_e32 v4, v184, v177
	v_fmac_f32_e32 v5, v184, v181
	v_mul_f32_e32 v184, v62, v150
	v_fmac_f32_e32 v6, v184, v154
	v_fmac_f32_e32 v7, v184, v158
	v_fmac_f32_e32 v8, v184, v162
	v_fmac_f32_e32 v9, v184, v166
	v_fmac_f32_e32 v10, v184, v170
	v_fmac_f32_e32 v11, v184, v174
	v_fmac_f32_e32 v4, v184, v178
	v_fmac_f32_e32 v5, v184, v182
	v_mul_f32_e32 v184, v63, v151
	v_fmac_f32_e32 v6, v184, v155
	v_fmac_f32_e32 v7, v184, v159
	v_fmac_f32_e32 v8, v184, v163
	v_fmac_f32_e32 v9, v184, v167
	v_fmac_f32_e32 v10, v184, v171
	v_fmac_f32_e32 v11, v184, v175
	v_fmac_f32_e32 v4, v184, v179
	v_fmac_f32_e32 v5, v184, v183
	ds_read_b128 v[148:151], v185 offset:4336
	ds_read_b128 v[152:155], v185 offset:240
	ds_read_b128 v[156:159], v185 offset:752
	ds_read_b128 v[160:163], v185 offset:1264
	ds_read_b128 v[164:167], v185 offset:1776
	ds_read_b128 v[168:171], v185 offset:2288
	ds_read_b128 v[172:175], v185 offset:2800
	ds_read_b128 v[176:179], v185 offset:3312
	ds_read_b128 v[180:183], v185 offset:3824
	s_waitcnt lgkmcnt(9)
	v_mul_f32_e32 v184, v64, v112
	v_fmac_f32_e32 v6, v184, v116
	v_fmac_f32_e32 v7, v184, v120
	v_fmac_f32_e32 v8, v184, v124
	v_fmac_f32_e32 v9, v184, v128
	v_fmac_f32_e32 v10, v184, v132
	v_fmac_f32_e32 v11, v184, v136
	v_fmac_f32_e32 v4, v184, v140
	v_fmac_f32_e32 v5, v184, v144
	v_mul_f32_e32 v184, v65, v113
	v_fmac_f32_e32 v6, v184, v117
	v_fmac_f32_e32 v7, v184, v121
	v_fmac_f32_e32 v8, v184, v125
	v_fmac_f32_e32 v9, v184, v129
	v_fmac_f32_e32 v10, v184, v133
	v_fmac_f32_e32 v11, v184, v137
	v_fmac_f32_e32 v4, v184, v141
	v_fmac_f32_e32 v5, v184, v145
	v_mul_f32_e32 v184, v66, v114
	v_fmac_f32_e32 v6, v184, v118
	v_fmac_f32_e32 v7, v184, v122
	v_fmac_f32_e32 v8, v184, v126
	v_fmac_f32_e32 v9, v184, v130
	v_fmac_f32_e32 v10, v184, v134
	v_fmac_f32_e32 v11, v184, v138
	v_fmac_f32_e32 v4, v184, v142
	v_fmac_f32_e32 v5, v184, v146
	v_mul_f32_e32 v184, v67, v115
	v_fmac_f32_e32 v6, v184, v119
	v_fmac_f32_e32 v7, v184, v123
	v_fmac_f32_e32 v8, v184, v127
	v_fmac_f32_e32 v9, v184, v131
	v_fmac_f32_e32 v10, v184, v135
	v_fmac_f32_e32 v11, v184, v139
	v_fmac_f32_e32 v4, v184, v143
	v_fmac_f32_e32 v5, v184, v147
	ds_read_b128 v[112:115], v185 offset:4352
	ds_read_b128 v[116:119], v185 offset:256
	ds_read_b128 v[120:123], v185 offset:768
	ds_read_b128 v[124:127], v185 offset:1280
	ds_read_b128 v[128:131], v185 offset:1792
	ds_read_b128 v[132:135], v185 offset:2304
	ds_read_b128 v[136:139], v185 offset:2816
	ds_read_b128 v[140:143], v185 offset:3328
	ds_read_b128 v[144:147], v185 offset:3840
	s_waitcnt lgkmcnt(9)
; __device__ __forceinline__ void prep_hybrid(const float* w_in, const float* w_out, const float* pool_w, const float* pool_scale, bf16_t* WIN, bf16_t* WOUT, int gw, int NGW, LAS float* scr, int lane) {
;     ...
;         for (int d = 0; d < 128; ++d) {
;             const float wv = w_out[(size_t)(512 + g * 128 + d) * D + n] * pool_scale[g * 128 + d];
; #pragma unroll
;             for (int i = 0; i < 8; ++i) a[i] += pw[i * 128 + d] * wv;
;         }
	v_mul_f32_e32 v184, v68, v148
	v_fmac_f32_e32 v6, v184, v152
	v_fmac_f32_e32 v7, v184, v156
	v_fmac_f32_e32 v8, v184, v160
	v_fmac_f32_e32 v9, v184, v164
	v_fmac_f32_e32 v10, v184, v168
	v_fmac_f32_e32 v11, v184, v172
	v_fmac_f32_e32 v4, v184, v176
	v_fmac_f32_e32 v5, v184, v180
	v_mul_f32_e32 v184, v69, v149
	v_fmac_f32_e32 v6, v184, v153
	v_fmac_f32_e32 v7, v184, v157
	v_fmac_f32_e32 v8, v184, v161
	v_fmac_f32_e32 v9, v184, v165
	v_fmac_f32_e32 v10, v184, v169
	v_fmac_f32_e32 v11, v184, v173
	v_fmac_f32_e32 v4, v184, v177
	v_fmac_f32_e32 v5, v184, v181
	v_mul_f32_e32 v184, v70, v150
	v_fmac_f32_e32 v6, v184, v154
	v_fmac_f32_e32 v7, v184, v158
	v_fmac_f32_e32 v8, v184, v162
	v_fmac_f32_e32 v9, v184, v166
	v_fmac_f32_e32 v10, v184, v170
	v_fmac_f32_e32 v11, v184, v174
	v_fmac_f32_e32 v4, v184, v178
	v_fmac_f32_e32 v5, v184, v182
	v_mul_f32_e32 v184, v71, v151
	v_fmac_f32_e32 v6, v184, v155
	v_fmac_f32_e32 v7, v184, v159
	v_fmac_f32_e32 v8, v184, v163
	v_fmac_f32_e32 v9, v184, v167
	v_fmac_f32_e32 v10, v184, v171
	v_fmac_f32_e32 v11, v184, v175
	v_fmac_f32_e32 v4, v184, v179
	v_fmac_f32_e32 v5, v184, v183
	global_load_dword v56, v[2:3], off
	v_lshl_add_u64 v[2:3], v[2:3], 0, s[14:15]
	global_load_dword v57, v[2:3], off
	v_lshl_add_u64 v[2:3], v[2:3], 0, s[14:15]
	global_load_dword v58, v[2:3], off
	v_lshl_add_u64 v[2:3], v[2:3], 0, s[14:15]
	global_load_dword v59, v[2:3], off
	v_lshl_add_u64 v[2:3], v[2:3], 0, s[14:15]
	global_load_dword v60, v[2:3], off
	v_lshl_add_u64 v[2:3], v[2:3], 0, s[14:15]
	global_load_dword v61, v[2:3], off
	v_lshl_add_u64 v[2:3], v[2:3], 0, s[14:15]
	global_load_dword v62, v[2:3], off
	v_lshl_add_u64 v[2:3], v[2:3], 0, s[14:15]
	global_load_dword v63, v[2:3], off
	v_lshl_add_u64 v[2:3], v[2:3], 0, s[14:15]
	global_load_dword v64, v[2:3], off
	v_lshl_add_u64 v[2:3], v[2:3], 0, s[14:15]
	global_load_dword v65, v[2:3], off
	v_lshl_add_u64 v[2:3], v[2:3], 0, s[14:15]
	global_load_dword v66, v[2:3], off
	v_lshl_add_u64 v[2:3], v[2:3], 0, s[14:15]
	global_load_dword v67, v[2:3], off
	v_lshl_add_u64 v[2:3], v[2:3], 0, s[14:15]
	global_load_dword v68, v[2:3], off
	v_lshl_add_u64 v[2:3], v[2:3], 0, s[14:15]
	global_load_dword v69, v[2:3], off
	v_lshl_add_u64 v[2:3], v[2:3], 0, s[14:15]
	global_load_dword v70, v[2:3], off
	v_lshl_add_u64 v[2:3], v[2:3], 0, s[14:15]
	global_load_dword v71, v[2:3], off
	v_lshl_add_u64 v[2:3], v[2:3], 0, s[14:15]
	s_waitcnt vmcnt(32)
	ds_read_b128 v[148:151], v185 offset:4368
	ds_read_b128 v[152:155], v185 offset:272
	ds_read_b128 v[156:159], v185 offset:784
	ds_read_b128 v[160:163], v185 offset:1296
	ds_read_b128 v[164:167], v185 offset:1808
	ds_read_b128 v[168:171], v185 offset:2320
	ds_read_b128 v[172:175], v185 offset:2832
	ds_read_b128 v[176:179], v185 offset:3344
	ds_read_b128 v[180:183], v185 offset:3856
	s_waitcnt lgkmcnt(9)
	v_mul_f32_e32 v184, v72, v112
	v_fmac_f32_e32 v6, v184, v116
	v_fmac_f32_e32 v7, v184, v120
	v_fmac_f32_e32 v8, v184, v124
	v_fmac_f32_e32 v9, v184, v128
	v_fmac_f32_e32 v10, v184, v132
	v_fmac_f32_e32 v11, v184, v136
	v_fmac_f32_e32 v4, v184, v140
	v_fmac_f32_e32 v5, v184, v144
	v_mul_f32_e32 v184, v73, v113
	v_fmac_f32_e32 v6, v184, v117
	v_fmac_f32_e32 v7, v184, v121
	v_fmac_f32_e32 v8, v184, v125
	v_fmac_f32_e32 v9, v184, v129
	v_fmac_f32_e32 v10, v184, v133
	v_fmac_f32_e32 v11, v184, v137
	v_fmac_f32_e32 v4, v184, v141
	v_fmac_f32_e32 v5, v184, v145
	v_mul_f32_e32 v184, v74, v114
	v_fmac_f32_e32 v6, v184, v118
	v_fmac_f32_e32 v7, v184, v122
	v_fmac_f32_e32 v8, v184, v126
	v_fmac_f32_e32 v9, v184, v130
	v_fmac_f32_e32 v10, v184, v134
	v_fmac_f32_e32 v11, v184, v138
	v_fmac_f32_e32 v4, v184, v142
	v_fmac_f32_e32 v5, v184, v146
	v_mul_f32_e32 v184, v75, v115
	v_fmac_f32_e32 v6, v184, v119
	v_fmac_f32_e32 v7, v184, v123
	v_fmac_f32_e32 v8, v184, v127
	v_fmac_f32_e32 v9, v184, v131
	v_fmac_f32_e32 v10, v184, v135
	v_fmac_f32_e32 v11, v184, v139
	v_fmac_f32_e32 v4, v184, v143
	v_fmac_f32_e32 v5, v184, v147
	ds_read_b128 v[112:115], v185 offset:4384
	ds_read_b128 v[116:119], v185 offset:288
	ds_read_b128 v[120:123], v185 offset:800
	ds_read_b128 v[124:127], v185 offset:1312
	ds_read_b128 v[128:131], v185 offset:1824
	ds_read_b128 v[132:135], v185 offset:2336
	ds_read_b128 v[136:139], v185 offset:2848
	ds_read_b128 v[140:143], v185 offset:3360
	ds_read_b128 v[144:147], v185 offset:3872
	s_waitcnt lgkmcnt(9)
	v_mul_f32_e32 v184, v76, v148
	v_fmac_f32_e32 v6, v184, v152
	v_fmac_f32_e32 v7, v184, v156
	v_fmac_f32_e32 v8, v184, v160
	v_fmac_f32_e32 v9, v184, v164
	v_fmac_f32_e32 v10, v184, v168
	v_fmac_f32_e32 v11, v184, v172
	v_fmac_f32_e32 v4, v184, v176
	v_fmac_f32_e32 v5, v184, v180
	v_mul_f32_e32 v184, v77, v149
	v_fmac_f32_e32 v6, v184, v153
	v_fmac_f32_e32 v7, v184, v157
	v_fmac_f32_e32 v8, v184, v161
	v_fmac_f32_e32 v9, v184, v165
	v_fmac_f32_e32 v10, v184, v169
	v_fmac_f32_e32 v11, v184, v173
	v_fmac_f32_e32 v4, v184, v177
	v_fmac_f32_e32 v5, v184, v181
	v_mul_f32_e32 v184, v78, v150
	v_fmac_f32_e32 v6, v184, v154
	v_fmac_f32_e32 v7, v184, v158
	v_fmac_f32_e32 v8, v184, v162
	v_fmac_f32_e32 v9, v184, v166
	v_fmac_f32_e32 v10, v184, v170
	v_fmac_f32_e32 v11, v184, v174
	v_fmac_f32_e32 v4, v184, v178
	v_fmac_f32_e32 v5, v184, v182
	v_mul_f32_e32 v184, v79, v151
	v_fmac_f32_e32 v6, v184, v155
	v_fmac_f32_e32 v7, v184, v159
	v_fmac_f32_e32 v8, v184, v163
	v_fmac_f32_e32 v9, v184, v167
	v_fmac_f32_e32 v10, v184, v171
	v_fmac_f32_e32 v11, v184, v175
	v_fmac_f32_e32 v4, v184, v179
	v_fmac_f32_e32 v5, v184, v183
	ds_read_b128 v[148:151], v185 offset:4400
	ds_read_b128 v[152:155], v185 offset:304
	ds_read_b128 v[156:159], v185 offset:816
	ds_read_b128 v[160:163], v185 offset:1328
	ds_read_b128 v[164:167], v185 offset:1840
	ds_read_b128 v[168:171], v185 offset:2352
	ds_read_b128 v[172:175], v185 offset:2864
	ds_read_b128 v[176:179], v185 offset:3376
	ds_read_b128 v[180:183], v185 offset:3888
	s_waitcnt lgkmcnt(9)
; __device__ __forceinline__ void prep_hybrid(const float* w_in, const float* w_out, const float* pool_w, const float* pool_scale, bf16_t* WIN, bf16_t* WOUT, int gw, int NGW, LAS float* scr, int lane) {
;     ...
;         for (int d = 0; d < 128; ++d) {
;             const float wv = w_out[(size_t)(512 + g * 128 + d) * D + n] * pool_scale[g * 128 + d];
; #pragma unroll
;             for (int i = 0; i < 8; ++i) a[i] += pw[i * 128 + d] * wv;
;         }
	v_mul_f32_e32 v184, v80, v112
	v_fmac_f32_e32 v6, v184, v116
	v_fmac_f32_e32 v7, v184, v120
	v_fmac_f32_e32 v8, v184, v124
	v_fmac_f32_e32 v9, v184, v128
	v_fmac_f32_e32 v10, v184, v132
	v_fmac_f32_e32 v11, v184, v136
	v_fmac_f32_e32 v4, v184, v140
	v_fmac_f32_e32 v5, v184, v144
	v_mul_f32_e32 v184, v81, v113
	v_fmac_f32_e32 v6, v184, v117
	v_fmac_f32_e32 v7, v184, v121
	v_fmac_f32_e32 v8, v184, v125
	v_fmac_f32_e32 v9, v184, v129
	v_fmac_f32_e32 v10, v184, v133
	v_fmac_f32_e32 v11, v184, v137
	v_fmac_f32_e32 v4, v184, v141
	v_fmac_f32_e32 v5, v184, v145
	v_mul_f32_e32 v184, v82, v114
	v_fmac_f32_e32 v6, v184, v118
	v_fmac_f32_e32 v7, v184, v122
	v_fmac_f32_e32 v8, v184, v126
	v_fmac_f32_e32 v9, v184, v130
	v_fmac_f32_e32 v10, v184, v134
	v_fmac_f32_e32 v11, v184, v138
	v_fmac_f32_e32 v4, v184, v142
	v_fmac_f32_e32 v5, v184, v146
	v_mul_f32_e32 v184, v83, v115
	v_fmac_f32_e32 v6, v184, v119
	v_fmac_f32_e32 v7, v184, v123
	v_fmac_f32_e32 v8, v184, v127
	v_fmac_f32_e32 v9, v184, v131
	v_fmac_f32_e32 v10, v184, v135
	v_fmac_f32_e32 v11, v184, v139
	v_fmac_f32_e32 v4, v184, v143
	v_fmac_f32_e32 v5, v184, v147
	ds_read_b128 v[112:115], v185 offset:4416
	ds_read_b128 v[116:119], v185 offset:320
	ds_read_b128 v[120:123], v185 offset:832
	ds_read_b128 v[124:127], v185 offset:1344
	ds_read_b128 v[128:131], v185 offset:1856
	ds_read_b128 v[132:135], v185 offset:2368
	ds_read_b128 v[136:139], v185 offset:2880
	ds_read_b128 v[140:143], v185 offset:3392
	ds_read_b128 v[144:147], v185 offset:3904
	s_waitcnt lgkmcnt(9)
	v_mul_f32_e32 v184, v84, v148
	v_fmac_f32_e32 v6, v184, v152
	v_fmac_f32_e32 v7, v184, v156
	v_fmac_f32_e32 v8, v184, v160
	v_fmac_f32_e32 v9, v184, v164
	v_fmac_f32_e32 v10, v184, v168
	v_fmac_f32_e32 v11, v184, v172
	v_fmac_f32_e32 v4, v184, v176
	v_fmac_f32_e32 v5, v184, v180
	v_mul_f32_e32 v184, v85, v149
	v_fmac_f32_e32 v6, v184, v153
	v_fmac_f32_e32 v7, v184, v157
	v_fmac_f32_e32 v8, v184, v161
	v_fmac_f32_e32 v9, v184, v165
	v_fmac_f32_e32 v10, v184, v169
	v_fmac_f32_e32 v11, v184, v173
	v_fmac_f32_e32 v4, v184, v177
	v_fmac_f32_e32 v5, v184, v181
	v_mul_f32_e32 v184, v86, v150
	v_fmac_f32_e32 v6, v184, v154
	v_fmac_f32_e32 v7, v184, v158
	v_fmac_f32_e32 v8, v184, v162
	v_fmac_f32_e32 v9, v184, v166
	v_fmac_f32_e32 v10, v184, v170
	v_fmac_f32_e32 v11, v184, v174
	v_fmac_f32_e32 v4, v184, v178
	v_fmac_f32_e32 v5, v184, v182
	v_mul_f32_e32 v184, v87, v151
	v_fmac_f32_e32 v6, v184, v155
	v_fmac_f32_e32 v7, v184, v159
	v_fmac_f32_e32 v8, v184, v163
	v_fmac_f32_e32 v9, v184, v167
	v_fmac_f32_e32 v10, v184, v171
	v_fmac_f32_e32 v11, v184, v175
	v_fmac_f32_e32 v4, v184, v179
	v_fmac_f32_e32 v5, v184, v183
	global_load_dword v72, v[2:3], off
	v_lshl_add_u64 v[2:3], v[2:3], 0, s[14:15]
	global_load_dword v73, v[2:3], off
	v_lshl_add_u64 v[2:3], v[2:3], 0, s[14:15]
	global_load_dword v74, v[2:3], off
	v_lshl_add_u64 v[2:3], v[2:3], 0, s[14:15]
	global_load_dword v75, v[2:3], off
	v_lshl_add_u64 v[2:3], v[2:3], 0, s[14:15]
	global_load_dword v76, v[2:3], off
	v_lshl_add_u64 v[2:3], v[2:3], 0, s[14:15]
	global_load_dword v77, v[2:3], off
	v_lshl_add_u64 v[2:3], v[2:3], 0, s[14:15]
	global_load_dword v78, v[2:3], off
	v_lshl_add_u64 v[2:3], v[2:3], 0, s[14:15]
	global_load_dword v79, v[2:3], off
	v_lshl_add_u64 v[2:3], v[2:3], 0, s[14:15]
	global_load_dword v80, v[2:3], off
	v_lshl_add_u64 v[2:3], v[2:3], 0, s[14:15]
	global_load_dword v81, v[2:3], off
	v_lshl_add_u64 v[2:3], v[2:3], 0, s[14:15]
	global_load_dword v82, v[2:3], off
	v_lshl_add_u64 v[2:3], v[2:3], 0, s[14:15]
	global_load_dword v83, v[2:3], off
	v_lshl_add_u64 v[2:3], v[2:3], 0, s[14:15]
	global_load_dword v84, v[2:3], off
	v_lshl_add_u64 v[2:3], v[2:3], 0, s[14:15]
	global_load_dword v85, v[2:3], off
	v_lshl_add_u64 v[2:3], v[2:3], 0, s[14:15]
	global_load_dword v86, v[2:3], off
	v_lshl_add_u64 v[2:3], v[2:3], 0, s[14:15]
	global_load_dword v87, v[2:3], off
	v_lshl_add_u64 v[2:3], v[2:3], 0, s[14:15]
	s_waitcnt vmcnt(32)
	ds_read_b128 v[148:151], v185 offset:4432
	ds_read_b128 v[152:155], v185 offset:336
	ds_read_b128 v[156:159], v185 offset:848
	ds_read_b128 v[160:163], v185 offset:1360
	ds_read_b128 v[164:167], v185 offset:1872
	ds_read_b128 v[168:171], v185 offset:2384
	ds_read_b128 v[172:175], v185 offset:2896
	ds_read_b128 v[176:179], v185 offset:3408
	ds_read_b128 v[180:183], v185 offset:3920
	s_waitcnt lgkmcnt(9)
	v_mul_f32_e32 v184, v88, v112
	v_fmac_f32_e32 v6, v184, v116
	v_fmac_f32_e32 v7, v184, v120
	v_fmac_f32_e32 v8, v184, v124
	v_fmac_f32_e32 v9, v184, v128
	v_fmac_f32_e32 v10, v184, v132
	v_fmac_f32_e32 v11, v184, v136
	v_fmac_f32_e32 v4, v184, v140
	v_fmac_f32_e32 v5, v184, v144
	v_mul_f32_e32 v184, v89, v113
	v_fmac_f32_e32 v6, v184, v117
	v_fmac_f32_e32 v7, v184, v121
	v_fmac_f32_e32 v8, v184, v125
	v_fmac_f32_e32 v9, v184, v129
	v_fmac_f32_e32 v10, v184, v133
	v_fmac_f32_e32 v11, v184, v137
	v_fmac_f32_e32 v4, v184, v141
	v_fmac_f32_e32 v5, v184, v145
	v_mul_f32_e32 v184, v90, v114
	v_fmac_f32_e32 v6, v184, v118
	v_fmac_f32_e32 v7, v184, v122
	v_fmac_f32_e32 v8, v184, v126
	v_fmac_f32_e32 v9, v184, v130
	v_fmac_f32_e32 v10, v184, v134
	v_fmac_f32_e32 v11, v184, v138
	v_fmac_f32_e32 v4, v184, v142
	v_fmac_f32_e32 v5, v184, v146
	v_mul_f32_e32 v184, v91, v115
	v_fmac_f32_e32 v6, v184, v119
	v_fmac_f32_e32 v7, v184, v123
	v_fmac_f32_e32 v8, v184, v127
	v_fmac_f32_e32 v9, v184, v131
	v_fmac_f32_e32 v10, v184, v135
	v_fmac_f32_e32 v11, v184, v139
	v_fmac_f32_e32 v4, v184, v143
	v_fmac_f32_e32 v5, v184, v147
	ds_read_b128 v[112:115], v185 offset:4448
	ds_read_b128 v[116:119], v185 offset:352
	ds_read_b128 v[120:123], v185 offset:864
	ds_read_b128 v[124:127], v185 offset:1376
	ds_read_b128 v[128:131], v185 offset:1888
	ds_read_b128 v[132:135], v185 offset:2400
	ds_read_b128 v[136:139], v185 offset:2912
	ds_read_b128 v[140:143], v185 offset:3424
	ds_read_b128 v[144:147], v185 offset:3936
	s_waitcnt lgkmcnt(9)
; __device__ __forceinline__ void prep_hybrid(const float* w_in, const float* w_out, const float* pool_w, const float* pool_scale, bf16_t* WIN, bf16_t* WOUT, int gw, int NGW, LAS float* scr, int lane) {
;     ...
;         for (int d = 0; d < 128; ++d) {
;             const float wv = w_out[(size_t)(512 + g * 128 + d) * D + n] * pool_scale[g * 128 + d];
; #pragma unroll
;             for (int i = 0; i < 8; ++i) a[i] += pw[i * 128 + d] * wv;
;         }
	v_mul_f32_e32 v184, v100, v148
	v_fmac_f32_e32 v6, v184, v152
	v_fmac_f32_e32 v7, v184, v156
	v_fmac_f32_e32 v8, v184, v160
	v_fmac_f32_e32 v9, v184, v164
	v_fmac_f32_e32 v10, v184, v168
	v_fmac_f32_e32 v11, v184, v172
	v_fmac_f32_e32 v4, v184, v176
	v_fmac_f32_e32 v5, v184, v180
	v_mul_f32_e32 v184, v101, v149
	v_fmac_f32_e32 v6, v184, v153
	v_fmac_f32_e32 v7, v184, v157
	v_fmac_f32_e32 v8, v184, v161
	v_fmac_f32_e32 v9, v184, v165
	v_fmac_f32_e32 v10, v184, v169
	v_fmac_f32_e32 v11, v184, v173
	v_fmac_f32_e32 v4, v184, v177
	v_fmac_f32_e32 v5, v184, v181
	v_mul_f32_e32 v184, v102, v150
	v_fmac_f32_e32 v6, v184, v154
	v_fmac_f32_e32 v7, v184, v158
	v_fmac_f32_e32 v8, v184, v162
	v_fmac_f32_e32 v9, v184, v166
	v_fmac_f32_e32 v10, v184, v170
	v_fmac_f32_e32 v11, v184, v174
	v_fmac_f32_e32 v4, v184, v178
	v_fmac_f32_e32 v5, v184, v182
	v_mul_f32_e32 v184, v103, v151
	v_fmac_f32_e32 v6, v184, v155
	v_fmac_f32_e32 v7, v184, v159
	v_fmac_f32_e32 v8, v184, v163
	v_fmac_f32_e32 v9, v184, v167
	v_fmac_f32_e32 v10, v184, v171
	v_fmac_f32_e32 v11, v184, v175
	v_fmac_f32_e32 v4, v184, v179
	v_fmac_f32_e32 v5, v184, v183
	ds_read_b128 v[148:151], v185 offset:4464
	ds_read_b128 v[152:155], v185 offset:368
	ds_read_b128 v[156:159], v185 offset:880
	ds_read_b128 v[160:163], v185 offset:1392
	ds_read_b128 v[164:167], v185 offset:1904
	ds_read_b128 v[168:171], v185 offset:2416
	ds_read_b128 v[172:175], v185 offset:2928
	ds_read_b128 v[176:179], v185 offset:3440
	ds_read_b128 v[180:183], v185 offset:3952
	s_waitcnt lgkmcnt(9)
	v_mul_f32_e32 v184, v104, v112
	v_fmac_f32_e32 v6, v184, v116
	v_fmac_f32_e32 v7, v184, v120
	v_fmac_f32_e32 v8, v184, v124
	v_fmac_f32_e32 v9, v184, v128
	v_fmac_f32_e32 v10, v184, v132
	v_fmac_f32_e32 v11, v184, v136
	v_fmac_f32_e32 v4, v184, v140
	v_fmac_f32_e32 v5, v184, v144
	v_mul_f32_e32 v184, v105, v113
	v_fmac_f32_e32 v6, v184, v117
	v_fmac_f32_e32 v7, v184, v121
	v_fmac_f32_e32 v8, v184, v125
	v_fmac_f32_e32 v9, v184, v129
	v_fmac_f32_e32 v10, v184, v133
	v_fmac_f32_e32 v11, v184, v137
	v_fmac_f32_e32 v4, v184, v141
	v_fmac_f32_e32 v5, v184, v145
	v_mul_f32_e32 v184, v106, v114
	v_fmac_f32_e32 v6, v184, v118
	v_fmac_f32_e32 v7, v184, v122
	v_fmac_f32_e32 v8, v184, v126
	v_fmac_f32_e32 v9, v184, v130
	v_fmac_f32_e32 v10, v184, v134
	v_fmac_f32_e32 v11, v184, v138
	v_fmac_f32_e32 v4, v184, v142
	v_fmac_f32_e32 v5, v184, v146
	v_mul_f32_e32 v184, v107, v115
	v_fmac_f32_e32 v6, v184, v119
	v_fmac_f32_e32 v7, v184, v123
	v_fmac_f32_e32 v8, v184, v127
	v_fmac_f32_e32 v9, v184, v131
	v_fmac_f32_e32 v10, v184, v135
	v_fmac_f32_e32 v11, v184, v139
	v_fmac_f32_e32 v4, v184, v143
	v_fmac_f32_e32 v5, v184, v147
	ds_read_b128 v[112:115], v185 offset:4480
	ds_read_b128 v[116:119], v185 offset:384
	ds_read_b128 v[120:123], v185 offset:896
	ds_read_b128 v[124:127], v185 offset:1408
	ds_read_b128 v[128:131], v185 offset:1920
	ds_read_b128 v[132:135], v185 offset:2432
	ds_read_b128 v[136:139], v185 offset:2944
	ds_read_b128 v[140:143], v185 offset:3456
	ds_read_b128 v[144:147], v185 offset:3968
	s_waitcnt lgkmcnt(9)
	v_mul_f32_e32 v184, v108, v148
	v_fmac_f32_e32 v6, v184, v152
	v_fmac_f32_e32 v7, v184, v156
	v_fmac_f32_e32 v8, v184, v160
	v_fmac_f32_e32 v9, v184, v164
	v_fmac_f32_e32 v10, v184, v168
	v_fmac_f32_e32 v11, v184, v172
	v_fmac_f32_e32 v4, v184, v176
	v_fmac_f32_e32 v5, v184, v180
	v_mul_f32_e32 v184, v109, v149
	v_fmac_f32_e32 v6, v184, v153
	v_fmac_f32_e32 v7, v184, v157
	v_fmac_f32_e32 v8, v184, v161
	v_fmac_f32_e32 v9, v184, v165
	v_fmac_f32_e32 v10, v184, v169
	v_fmac_f32_e32 v11, v184, v173
	v_fmac_f32_e32 v4, v184, v177
	v_fmac_f32_e32 v5, v184, v181
	v_mul_f32_e32 v184, v110, v150
	v_fmac_f32_e32 v6, v184, v154
	v_fmac_f32_e32 v7, v184, v158
	v_fmac_f32_e32 v8, v184, v162
	v_fmac_f32_e32 v9, v184, v166
	v_fmac_f32_e32 v10, v184, v170
	v_fmac_f32_e32 v11, v184, v174
	v_fmac_f32_e32 v4, v184, v178
	v_fmac_f32_e32 v5, v184, v182
	v_mul_f32_e32 v184, v111, v151
	v_fmac_f32_e32 v6, v184, v155
	v_fmac_f32_e32 v7, v184, v159
	v_fmac_f32_e32 v8, v184, v163
	v_fmac_f32_e32 v9, v184, v167
	v_fmac_f32_e32 v10, v184, v171
	v_fmac_f32_e32 v11, v184, v175
	v_fmac_f32_e32 v4, v184, v179
	v_fmac_f32_e32 v5, v184, v183
	s_waitcnt vmcnt(16)
	ds_read_b128 v[148:151], v185 offset:4496
	ds_read_b128 v[152:155], v185 offset:400
	ds_read_b128 v[156:159], v185 offset:912
	ds_read_b128 v[160:163], v185 offset:1424
	ds_read_b128 v[164:167], v185 offset:1936
	ds_read_b128 v[168:171], v185 offset:2448
	ds_read_b128 v[172:175], v185 offset:2960
	ds_read_b128 v[176:179], v185 offset:3472
	ds_read_b128 v[180:183], v185 offset:3984
	s_waitcnt lgkmcnt(9)
	v_mul_f32_e32 v184, v56, v112
	v_fmac_f32_e32 v6, v184, v116
	v_fmac_f32_e32 v7, v184, v120
	v_fmac_f32_e32 v8, v184, v124
	v_fmac_f32_e32 v9, v184, v128
	v_fmac_f32_e32 v10, v184, v132
	v_fmac_f32_e32 v11, v184, v136
	v_fmac_f32_e32 v4, v184, v140
	v_fmac_f32_e32 v5, v184, v144
	v_mul_f32_e32 v184, v57, v113
	v_fmac_f32_e32 v6, v184, v117
	v_fmac_f32_e32 v7, v184, v121
	v_fmac_f32_e32 v8, v184, v125
	v_fmac_f32_e32 v9, v184, v129
	v_fmac_f32_e32 v10, v184, v133
	v_fmac_f32_e32 v11, v184, v137
	v_fmac_f32_e32 v4, v184, v141
	v_fmac_f32_e32 v5, v184, v145
	v_mul_f32_e32 v184, v58, v114
	v_fmac_f32_e32 v6, v184, v118
	v_fmac_f32_e32 v7, v184, v122
	v_fmac_f32_e32 v8, v184, v126
	v_fmac_f32_e32 v9, v184, v130
	v_fmac_f32_e32 v10, v184, v134
	v_fmac_f32_e32 v11, v184, v138
	v_fmac_f32_e32 v4, v184, v142
	v_fmac_f32_e32 v5, v184, v146
	v_mul_f32_e32 v184, v59, v115
	v_fmac_f32_e32 v6, v184, v119
	v_fmac_f32_e32 v7, v184, v123
	v_fmac_f32_e32 v8, v184, v127
	v_fmac_f32_e32 v9, v184, v131
	v_fmac_f32_e32 v10, v184, v135
	v_fmac_f32_e32 v11, v184, v139
	v_fmac_f32_e32 v4, v184, v143
	v_fmac_f32_e32 v5, v184, v147
	ds_read_b128 v[112:115], v185 offset:4512
	ds_read_b128 v[116:119], v185 offset:416
	ds_read_b128 v[120:123], v185 offset:928
	ds_read_b128 v[124:127], v185 offset:1440
	ds_read_b128 v[128:131], v185 offset:1952
	ds_read_b128 v[132:135], v185 offset:2464
	ds_read_b128 v[136:139], v185 offset:2976
	ds_read_b128 v[140:143], v185 offset:3488
	ds_read_b128 v[144:147], v185 offset:4000
	s_waitcnt lgkmcnt(9)
; __device__ __forceinline__ void prep_hybrid(const float* w_in, const float* w_out, const float* pool_w, const float* pool_scale, bf16_t* WIN, bf16_t* WOUT, int gw, int NGW, LAS float* scr, int lane) {
;     ...
;         for (int d = 0; d < 128; ++d) {
;             const float wv = w_out[(size_t)(512 + g * 128 + d) * D + n] * pool_scale[g * 128 + d];
; #pragma unroll
;             for (int i = 0; i < 8; ++i) a[i] += pw[i * 128 + d] * wv;
	v_mul_f32_e32 v184, v60, v148
	v_fmac_f32_e32 v6, v184, v152
	v_fmac_f32_e32 v7, v184, v156
	v_fmac_f32_e32 v8, v184, v160
	v_fmac_f32_e32 v9, v184, v164
	v_fmac_f32_e32 v10, v184, v168
	v_fmac_f32_e32 v11, v184, v172
	v_fmac_f32_e32 v4, v184, v176
	v_fmac_f32_e32 v5, v184, v180
	v_mul_f32_e32 v184, v61, v149
	v_fmac_f32_e32 v6, v184, v153
	v_fmac_f32_e32 v7, v184, v157
	v_fmac_f32_e32 v8, v184, v161
	v_fmac_f32_e32 v9, v184, v165
	v_fmac_f32_e32 v10, v184, v169
	v_fmac_f32_e32 v11, v184, v173
	v_fmac_f32_e32 v4, v184, v177
	v_fmac_f32_e32 v5, v184, v181
	v_mul_f32_e32 v184, v62, v150
	v_fmac_f32_e32 v6, v184, v154
	v_fmac_f32_e32 v7, v184, v158
	v_fmac_f32_e32 v8, v184, v162
	v_fmac_f32_e32 v9, v184, v166
	v_fmac_f32_e32 v10, v184, v170
	v_fmac_f32_e32 v11, v184, v174
	v_fmac_f32_e32 v4, v184, v178
	v_fmac_f32_e32 v5, v184, v182
	v_mul_f32_e32 v184, v63, v151
	v_fmac_f32_e32 v6, v184, v155
	v_fmac_f32_e32 v7, v184, v159
	v_fmac_f32_e32 v8, v184, v163
	v_fmac_f32_e32 v9, v184, v167
	v_fmac_f32_e32 v10, v184, v171
	v_fmac_f32_e32 v11, v184, v175
	v_fmac_f32_e32 v4, v184, v179
	v_fmac_f32_e32 v5, v184, v183
	ds_read_b128 v[148:151], v185 offset:4528
	ds_read_b128 v[152:155], v185 offset:432
	ds_read_b128 v[156:159], v185 offset:944
	ds_read_b128 v[160:163], v185 offset:1456
	ds_read_b128 v[164:167], v185 offset:1968
	ds_read_b128 v[168:171], v185 offset:2480
	ds_read_b128 v[172:175], v185 offset:2992
	ds_read_b128 v[176:179], v185 offset:3504
	ds_read_b128 v[180:183], v185 offset:4016
	s_waitcnt lgkmcnt(9)
	v_mul_f32_e32 v184, v64, v112
	v_fmac_f32_e32 v6, v184, v116
	v_fmac_f32_e32 v7, v184, v120
	v_fmac_f32_e32 v8, v184, v124
	v_fmac_f32_e32 v9, v184, v128
	v_fmac_f32_e32 v10, v184, v132
	v_fmac_f32_e32 v11, v184, v136
	v_fmac_f32_e32 v4, v184, v140
	v_fmac_f32_e32 v5, v184, v144
	v_mul_f32_e32 v184, v65, v113
	v_fmac_f32_e32 v6, v184, v117
	v_fmac_f32_e32 v7, v184, v121
	v_fmac_f32_e32 v8, v184, v125
	v_fmac_f32_e32 v9, v184, v129
	v_fmac_f32_e32 v10, v184, v133
	v_fmac_f32_e32 v11, v184, v137
	v_fmac_f32_e32 v4, v184, v141
	v_fmac_f32_e32 v5, v184, v145
	v_mul_f32_e32 v184, v66, v114
	v_fmac_f32_e32 v6, v184, v118
	v_fmac_f32_e32 v7, v184, v122
	v_fmac_f32_e32 v8, v184, v126
	v_fmac_f32_e32 v9, v184, v130
	v_fmac_f32_e32 v10, v184, v134
	v_fmac_f32_e32 v11, v184, v138
	v_fmac_f32_e32 v4, v184, v142
	v_fmac_f32_e32 v5, v184, v146
	v_mul_f32_e32 v184, v67, v115
	v_fmac_f32_e32 v6, v184, v119
	v_fmac_f32_e32 v7, v184, v123
	v_fmac_f32_e32 v8, v184, v127
	v_fmac_f32_e32 v9, v184, v131
	v_fmac_f32_e32 v10, v184, v135
	v_fmac_f32_e32 v11, v184, v139
	v_fmac_f32_e32 v4, v184, v143
	v_fmac_f32_e32 v5, v184, v147
	ds_read_b128 v[112:115], v185 offset:4544
	ds_read_b128 v[116:119], v185 offset:448
	ds_read_b128 v[120:123], v185 offset:960
	ds_read_b128 v[124:127], v185 offset:1472
	ds_read_b128 v[128:131], v185 offset:1984
	ds_read_b128 v[132:135], v185 offset:2496
	ds_read_b128 v[136:139], v185 offset:3008
	ds_read_b128 v[140:143], v185 offset:3520
	ds_read_b128 v[144:147], v185 offset:4032
	s_waitcnt lgkmcnt(9)
	v_mul_f32_e32 v184, v68, v148
	v_fmac_f32_e32 v6, v184, v152
	v_fmac_f32_e32 v7, v184, v156
	v_fmac_f32_e32 v8, v184, v160
	v_fmac_f32_e32 v9, v184, v164
	v_fmac_f32_e32 v10, v184, v168
	v_fmac_f32_e32 v11, v184, v172
	v_fmac_f32_e32 v4, v184, v176
	v_fmac_f32_e32 v5, v184, v180
	v_mul_f32_e32 v184, v69, v149
	v_fmac_f32_e32 v6, v184, v153
	v_fmac_f32_e32 v7, v184, v157
	v_fmac_f32_e32 v8, v184, v161
	v_fmac_f32_e32 v9, v184, v165
	v_fmac_f32_e32 v10, v184, v169
	v_fmac_f32_e32 v11, v184, v173
	v_fmac_f32_e32 v4, v184, v177
	v_fmac_f32_e32 v5, v184, v181
	v_mul_f32_e32 v184, v70, v150
	v_fmac_f32_e32 v6, v184, v154
	v_fmac_f32_e32 v7, v184, v158
	v_fmac_f32_e32 v8, v184, v162
	v_fmac_f32_e32 v9, v184, v166
	v_fmac_f32_e32 v10, v184, v170
	v_fmac_f32_e32 v11, v184, v174
	v_fmac_f32_e32 v4, v184, v178
	v_fmac_f32_e32 v5, v184, v182
	v_mul_f32_e32 v184, v71, v151
	v_fmac_f32_e32 v6, v184, v155
	v_fmac_f32_e32 v7, v184, v159
	v_fmac_f32_e32 v8, v184, v163
	v_fmac_f32_e32 v9, v184, v167
	v_fmac_f32_e32 v10, v184, v171
	v_fmac_f32_e32 v11, v184, v175
	v_fmac_f32_e32 v4, v184, v179
	v_fmac_f32_e32 v5, v184, v183
	s_waitcnt vmcnt(0)
	ds_read_b128 v[148:151], v185 offset:4560
	ds_read_b128 v[152:155], v185 offset:464
	ds_read_b128 v[156:159], v185 offset:976
	ds_read_b128 v[160:163], v185 offset:1488
	ds_read_b128 v[164:167], v185 offset:2000
	ds_read_b128 v[168:171], v185 offset:2512
	ds_read_b128 v[172:175], v185 offset:3024
	ds_read_b128 v[176:179], v185 offset:3536
	ds_read_b128 v[180:183], v185 offset:4048
	s_waitcnt lgkmcnt(9)
; #define GAS __attribute__((address_space(1)))
; __device__ __forceinline__ unsigned cvt_pk_bf16(float lo, float hi) { const f32x2 v = {lo, hi}; return __builtin_bit_cast(unsigned, __builtin_convertvector(v, b16x2_t)); }
; __device__ __forceinline__ void prep_hybrid(const float* w_in, const float* w_out, const float* pool_w, const float* pool_scale, bf16_t* WIN, bf16_t* WOUT, int gw, int NGW, LAS float* scr, int lane) {
;     ...
;         for (int d = 0; d < 128; ++d) {
;             const float wv = w_out[(size_t)(512 + g * 128 + d) * D + n] * pool_scale[g * 128 + d];
; #pragma unroll
;             for (int i = 0; i < 8; ++i) a[i] += pw[i * 128 + d] * wv;
;         }
;         u32x4 o; o.x = cvt_pk_bf16(a[0], a[1]); o.y = cvt_pk_bf16(a[2], a[3]); o.z = cvt_pk_bf16(a[4], a[5]); o.w = cvt_pk_bf16(a[6], a[7]);
;         *(GAS u32x4*)(WOUT + (size_t)n * D + 512 + g * 128 + c8 * 8) = o;
	v_mul_f32_e32 v184, v72, v112
	v_fmac_f32_e32 v6, v184, v116
	v_fmac_f32_e32 v7, v184, v120
	v_fmac_f32_e32 v8, v184, v124
	v_fmac_f32_e32 v9, v184, v128
	v_fmac_f32_e32 v10, v184, v132
	v_fmac_f32_e32 v11, v184, v136
	v_fmac_f32_e32 v4, v184, v140
	v_fmac_f32_e32 v5, v184, v144
	v_mul_f32_e32 v184, v73, v113
	v_fmac_f32_e32 v6, v184, v117
	v_fmac_f32_e32 v7, v184, v121
	v_fmac_f32_e32 v8, v184, v125
	v_fmac_f32_e32 v9, v184, v129
	v_fmac_f32_e32 v10, v184, v133
	v_fmac_f32_e32 v11, v184, v137
	v_fmac_f32_e32 v4, v184, v141
	v_fmac_f32_e32 v5, v184, v145
	v_mul_f32_e32 v184, v74, v114
	v_fmac_f32_e32 v6, v184, v118
	v_fmac_f32_e32 v7, v184, v122
	v_fmac_f32_e32 v8, v184, v126
	v_fmac_f32_e32 v9, v184, v130
	v_fmac_f32_e32 v10, v184, v134
	v_fmac_f32_e32 v11, v184, v138
	v_fmac_f32_e32 v4, v184, v142
	v_fmac_f32_e32 v5, v184, v146
	v_mul_f32_e32 v184, v75, v115
	v_fmac_f32_e32 v6, v184, v119
	v_fmac_f32_e32 v7, v184, v123
	v_fmac_f32_e32 v8, v184, v127
	v_fmac_f32_e32 v9, v184, v131
	v_fmac_f32_e32 v10, v184, v135
	v_fmac_f32_e32 v11, v184, v139
	v_fmac_f32_e32 v4, v184, v143
	v_fmac_f32_e32 v5, v184, v147
	ds_read_b128 v[112:115], v185 offset:4576
	ds_read_b128 v[116:119], v185 offset:480
	ds_read_b128 v[120:123], v185 offset:992
	ds_read_b128 v[124:127], v185 offset:1504
	ds_read_b128 v[128:131], v185 offset:2016
	ds_read_b128 v[132:135], v185 offset:2528
	ds_read_b128 v[136:139], v185 offset:3040
	ds_read_b128 v[140:143], v185 offset:3552
	ds_read_b128 v[144:147], v185 offset:4064
	s_waitcnt lgkmcnt(9)
	v_mul_f32_e32 v184, v76, v148
	v_fmac_f32_e32 v6, v184, v152
	v_fmac_f32_e32 v7, v184, v156
	v_fmac_f32_e32 v8, v184, v160
	v_fmac_f32_e32 v9, v184, v164
	v_fmac_f32_e32 v10, v184, v168
	v_fmac_f32_e32 v11, v184, v172
	v_fmac_f32_e32 v4, v184, v176
	v_fmac_f32_e32 v5, v184, v180
	v_mul_f32_e32 v184, v77, v149
	v_fmac_f32_e32 v6, v184, v153
	v_fmac_f32_e32 v7, v184, v157
	v_fmac_f32_e32 v8, v184, v161
	v_fmac_f32_e32 v9, v184, v165
	v_fmac_f32_e32 v10, v184, v169
	v_fmac_f32_e32 v11, v184, v173
	v_fmac_f32_e32 v4, v184, v177
	v_fmac_f32_e32 v5, v184, v181
	v_mul_f32_e32 v184, v78, v150
	v_fmac_f32_e32 v6, v184, v154
	v_fmac_f32_e32 v7, v184, v158
	v_fmac_f32_e32 v8, v184, v162
	v_fmac_f32_e32 v9, v184, v166
	v_fmac_f32_e32 v10, v184, v170
	v_fmac_f32_e32 v11, v184, v174
	v_fmac_f32_e32 v4, v184, v178
	v_fmac_f32_e32 v5, v184, v182
	v_mul_f32_e32 v184, v79, v151
	v_fmac_f32_e32 v6, v184, v155
	v_fmac_f32_e32 v7, v184, v159
	v_fmac_f32_e32 v8, v184, v163
	v_fmac_f32_e32 v9, v184, v167
	v_fmac_f32_e32 v10, v184, v171
	v_fmac_f32_e32 v11, v184, v175
	v_fmac_f32_e32 v4, v184, v179
	v_fmac_f32_e32 v5, v184, v183
	ds_read_b128 v[148:151], v185 offset:4592
	ds_read_b128 v[152:155], v185 offset:496
	ds_read_b128 v[156:159], v185 offset:1008
	ds_read_b128 v[160:163], v185 offset:1520
	ds_read_b128 v[164:167], v185 offset:2032
	ds_read_b128 v[168:171], v185 offset:2544
	ds_read_b128 v[172:175], v185 offset:3056
	ds_read_b128 v[176:179], v185 offset:3568
	ds_read_b128 v[180:183], v185 offset:4080
	s_waitcnt lgkmcnt(9)
	v_mul_f32_e32 v184, v80, v112
	v_fmac_f32_e32 v6, v184, v116
	v_fmac_f32_e32 v7, v184, v120
	v_fmac_f32_e32 v8, v184, v124
	v_fmac_f32_e32 v9, v184, v128
	v_fmac_f32_e32 v10, v184, v132
	v_fmac_f32_e32 v11, v184, v136
	v_fmac_f32_e32 v4, v184, v140
	v_fmac_f32_e32 v5, v184, v144
	v_mul_f32_e32 v184, v81, v113
	v_fmac_f32_e32 v6, v184, v117
	v_fmac_f32_e32 v7, v184, v121
	v_fmac_f32_e32 v8, v184, v125
	v_fmac_f32_e32 v9, v184, v129
	v_fmac_f32_e32 v10, v184, v133
	v_fmac_f32_e32 v11, v184, v137
	v_fmac_f32_e32 v4, v184, v141
	v_fmac_f32_e32 v5, v184, v145
	v_mul_f32_e32 v184, v82, v114
	v_fmac_f32_e32 v6, v184, v118
	v_fmac_f32_e32 v7, v184, v122
	v_fmac_f32_e32 v8, v184, v126
	v_fmac_f32_e32 v9, v184, v130
	v_fmac_f32_e32 v10, v184, v134
	v_fmac_f32_e32 v11, v184, v138
	v_fmac_f32_e32 v4, v184, v142
	v_fmac_f32_e32 v5, v184, v146
	v_mul_f32_e32 v184, v83, v115
	v_fmac_f32_e32 v6, v184, v119
	v_fmac_f32_e32 v7, v184, v123
	v_fmac_f32_e32 v8, v184, v127
	v_fmac_f32_e32 v9, v184, v131
	v_fmac_f32_e32 v10, v184, v135
	v_fmac_f32_e32 v11, v184, v139
	v_fmac_f32_e32 v4, v184, v143
	v_fmac_f32_e32 v5, v184, v147
	s_waitcnt lgkmcnt(0)
	v_mul_f32_e32 v184, v84, v148
	v_fmac_f32_e32 v6, v184, v152
	v_fmac_f32_e32 v7, v184, v156
	v_fmac_f32_e32 v8, v184, v160
	v_fmac_f32_e32 v9, v184, v164
	v_fmac_f32_e32 v10, v184, v168
	v_fmac_f32_e32 v11, v184, v172
	v_fmac_f32_e32 v4, v184, v176
	v_fmac_f32_e32 v5, v184, v180
	v_mul_f32_e32 v184, v85, v149
	v_fmac_f32_e32 v6, v184, v153
	v_fmac_f32_e32 v7, v184, v157
	v_fmac_f32_e32 v8, v184, v161
	v_fmac_f32_e32 v9, v184, v165
	v_fmac_f32_e32 v10, v184, v169
	v_fmac_f32_e32 v11, v184, v173
	v_fmac_f32_e32 v4, v184, v177
	v_fmac_f32_e32 v5, v184, v181
	v_mul_f32_e32 v184, v86, v150
	v_fmac_f32_e32 v6, v184, v154
	v_fmac_f32_e32 v7, v184, v158
	v_fmac_f32_e32 v8, v184, v162
	v_fmac_f32_e32 v9, v184, v166
	v_fmac_f32_e32 v10, v184, v170
	v_fmac_f32_e32 v11, v184, v174
	v_fmac_f32_e32 v4, v184, v178
	v_fmac_f32_e32 v5, v184, v182
	v_mul_f32_e32 v184, v87, v151
	v_fmac_f32_e32 v6, v184, v155
	v_fmac_f32_e32 v7, v184, v159
	v_fmac_f32_e32 v8, v184, v163
	v_fmac_f32_e32 v9, v184, v167
	v_fmac_f32_e32 v10, v184, v171
	v_fmac_f32_e32 v11, v184, v175
	v_fmac_f32_e32 v4, v184, v179
	v_fmac_f32_e32 v5, v184, v183
	s_lshl_b32 s0, s24, 6
	s_and_b32 s0, s0, 0x3c0
	v_add_u32_e32 v2, s0, v16
	v_ashrrev_i32_e32 v3, 31, v2
	v_lshlrev_b64 v[2:3], 11, v[2:3]
	v_lshl_add_u64 v[2:3], s[4:5], 0, v[2:3]
	v_lshl_add_u64 v[2:3], s[12:13], 1, v[2:3]
	s_and_b32 s6, s24, 0xf0
	s_add_i32 s24, s24, s16
	s_add_i32 s25, s25, s26
	v_cvt_pk_bf16_f32 v6, v6, v7
	v_cvt_pk_bf16_f32 v7, v8, v9
	v_cvt_pk_bf16_f32 v8, v10, v11
	v_cvt_pk_bf16_f32 v9, v4, v5
	v_lshl_add_u64 v[2:3], v[2:3], 0, s[6:7]
	s_cmpk_gt_i32 s24, 0x3ff
	global_store_dwordx4 v[2:3], v[6:9], off offset:1024
	s_cbranch_scc0 .LBB0_1676
